# v112 + B-fragment reads one phase earlier in the GEMM loops
# baseline (speedup 1.0000x reference)
.LBB0_315:
	s_ashr_i32 s65, s64, 31
	s_lshl_b64 s[0:1], s[64:65], 20
	s_add_u32 s70, s20, s0
	s_addc_u32 s71, s21, s1
	s_and_b64 s[0:1], s[8:9], exec
	s_cselect_b32 s0, s71, s75
	s_cselect_b32 s1, s70, s74
	s_add_u32 s8, s76, 0x80080
	s_addc_u32 s9, s77, 0
	s_add_u32 s12, s74, 0x100
	v_mov_b32_e32 v0, 0
	s_addc_u32 s24, s75, 0
	s_mov_b32 s25, -2
	v_mov_b32_e32 v1, v0
	v_mov_b32_e32 v2, v0
	v_mov_b32_e32 v3, v0
	v_mov_b32_e32 v4, v0
	v_mov_b32_e32 v5, v0
	v_mov_b32_e32 v6, v0
	v_mov_b32_e32 v7, v0
	v_mov_b32_e32 v8, v0
	v_mov_b32_e32 v9, v0
	v_mov_b32_e32 v10, v0
	v_mov_b32_e32 v11, v0
	v_mov_b32_e32 v12, v0
	v_mov_b32_e32 v13, v0
	v_mov_b32_e32 v14, v0
	v_mov_b32_e32 v15, v0
	v_mov_b32_e32 v20, v0
	v_mov_b32_e32 v21, v0
	v_mov_b32_e32 v22, v0
	v_mov_b32_e32 v23, v0
	v_mov_b32_e32 v28, v0
	v_mov_b32_e32 v29, v0
	v_mov_b32_e32 v30, v0
	v_mov_b32_e32 v31, v0
	v_mov_b32_e32 v36, v0
	v_mov_b32_e32 v37, v0
	v_mov_b32_e32 v38, v0
	v_mov_b32_e32 v39, v0
	v_mov_b32_e32 v44, v0
	v_mov_b32_e32 v45, v0
	v_mov_b32_e32 v46, v0
	v_mov_b32_e32 v47, v0
	v_mov_b32_e32 v16, v0
	v_mov_b32_e32 v17, v0
	v_mov_b32_e32 v18, v0
	v_mov_b32_e32 v19, v0
	v_mov_b32_e32 v24, v0
	v_mov_b32_e32 v25, v0
	v_mov_b32_e32 v26, v0
	v_mov_b32_e32 v27, v0
	v_mov_b32_e32 v32, v0
	v_mov_b32_e32 v33, v0
	v_mov_b32_e32 v34, v0
	v_mov_b32_e32 v35, v0
	v_mov_b32_e32 v40, v0
	v_mov_b32_e32 v41, v0
	v_mov_b32_e32 v42, v0
	v_mov_b32_e32 v43, v0
	v_mov_b32_e32 v48, v0
	v_mov_b32_e32 v49, v0
	v_mov_b32_e32 v50, v0
	v_mov_b32_e32 v51, v0
	v_mov_b32_e32 v52, v0
	v_mov_b32_e32 v53, v0
	v_mov_b32_e32 v54, v0
	v_mov_b32_e32 v55, v0
	v_mov_b32_e32 v56, v0
	v_mov_b32_e32 v57, v0
	v_mov_b32_e32 v58, v0
	v_mov_b32_e32 v59, v0
	v_mov_b32_e32 v60, v0
	v_mov_b32_e32 v61, v0
	v_mov_b32_e32 v62, v0
	v_mov_b32_e32 v63, v0
	v_mov_b32_e32 v64, v0
	v_mov_b32_e32 v65, v0
	v_mov_b32_e32 v66, v0
	v_mov_b32_e32 v67, v0
	v_mov_b32_e32 v68, v0
	v_mov_b32_e32 v69, v0
	v_mov_b32_e32 v70, v0
	v_mov_b32_e32 v71, v0
	v_mov_b32_e32 v72, v0
	v_mov_b32_e32 v73, v0
	v_mov_b32_e32 v74, v0
	v_mov_b32_e32 v75, v0
	v_mov_b32_e32 v76, v0
	v_mov_b32_e32 v77, v0
	v_mov_b32_e32 v78, v0
	v_mov_b32_e32 v79, v0
	v_mov_b32_e32 v88, v0
	v_mov_b32_e32 v89, v0
	v_mov_b32_e32 v90, v0
	v_mov_b32_e32 v91, v0
	v_mov_b32_e32 v92, v0
	v_mov_b32_e32 v93, v0
	v_mov_b32_e32 v94, v0
	v_mov_b32_e32 v95, v0
	v_mov_b32_e32 v104, v0
	v_mov_b32_e32 v105, v0
	v_mov_b32_e32 v106, v0
	v_mov_b32_e32 v107, v0
	v_mov_b32_e32 v108, v0
	v_mov_b32_e32 v109, v0
	v_mov_b32_e32 v110, v0
	v_mov_b32_e32 v111, v0
	v_mov_b32_e32 v80, v0
	v_mov_b32_e32 v81, v0
	v_mov_b32_e32 v82, v0
	v_mov_b32_e32 v83, v0
	v_mov_b32_e32 v84, v0
	v_mov_b32_e32 v85, v0
	v_mov_b32_e32 v86, v0
	v_mov_b32_e32 v87, v0
	v_mov_b32_e32 v96, v0
	v_mov_b32_e32 v97, v0
	v_mov_b32_e32 v98, v0
	v_mov_b32_e32 v99, v0
	v_mov_b32_e32 v100, v0
	v_mov_b32_e32 v101, v0
	v_mov_b32_e32 v102, v0
	v_mov_b32_e32 v103, v0
	v_mov_b32_e32 v112, v0
	v_mov_b32_e32 v113, v0
	v_mov_b32_e32 v114, v0
	v_mov_b32_e32 v115, v0
	v_mov_b32_e32 v116, v0
	v_mov_b32_e32 v117, v0
	v_mov_b32_e32 v118, v0
	v_mov_b32_e32 v119, v0
	v_mov_b32_e32 v120, v0
	v_mov_b32_e32 v121, v0
	v_mov_b32_e32 v122, v0
	v_mov_b32_e32 v123, v0
	v_mov_b32_e32 v124, v0
	v_mov_b32_e32 v125, v0
	v_mov_b32_e32 v126, v0
	v_mov_b32_e32 v127, v0
	ds_read_b128 v[150:153], v167
	ds_read_b128 v[154:157], v167 offset:1024
	ds_read_b128 v[158:161], v167 offset:2048
	ds_read_b128 v[172:175], v167 offset:3072
	.p2alignl 6, 3212836864
.LBB0_316:
	s_add_u32 s4, s8, 0xfff80080
	s_addc_u32 s5, s9, -1
	s_cmp_eq_u32 s25, 28
	s_cselect_b32 s5, s69, s5
	s_cselect_b32 s4, s68, s4
	s_cselect_b32 s75, s0, s24
	s_cselect_b32 s74, s1, s12
	s_add_i32 m0, s11, 0xc000
	ds_read_b128 v[176:179], v168
	ds_read_b128 v[180:183], v168 offset:1024
	ds_read_b128 v[184:187], v168 offset:2048
	ds_read_b128 v[188:191], v168 offset:3072
	ds_read_b128 v[192:195], v168 offset:4096
	ds_read_b128 v[196:199], v168 offset:5120
	ds_read_b128 v[200:203], v168 offset:6144
	ds_read_b128 v[204:207], v168 offset:7168
	global_load_lds_dwordx4 v142, s[8:9]
	s_add_i32 m0, s11, 0xe000
	s_nop 0
	global_load_lds_dwordx4 v144, s[8:9]
	s_waitcnt lgkmcnt(8)
	s_barrier
	s_waitcnt lgkmcnt(0)
	s_waitcnt lgkmcnt(0)
	v_mfma_f32_16x16x32_bf16 v[124:127], v[150:153], v[176:179], v[124:127]
	v_mfma_f32_16x16x32_bf16 v[120:123], v[158:161], v[176:179], v[120:123]
	v_mfma_f32_16x16x32_bf16 v[116:119], v[150:153], v[184:187], v[116:119]
	v_mfma_f32_16x16x32_bf16 v[112:115], v[158:161], v[184:187], v[112:115]
	v_mfma_f32_16x16x32_bf16 v[100:103], v[150:153], v[192:195], v[100:103]
	v_mfma_f32_16x16x32_bf16 v[96:99], v[158:161], v[192:195], v[96:99]
	v_mfma_f32_16x16x32_bf16 v[84:87], v[150:153], v[200:203], v[84:87]
	v_mfma_f32_16x16x32_bf16 v[80:83], v[158:161], v[200:203], v[80:83]
	v_mfma_f32_16x16x32_bf16 v[124:127], v[154:157], v[180:183], v[124:127]
	v_mfma_f32_16x16x32_bf16 v[120:123], v[172:175], v[180:183], v[120:123]
	v_mfma_f32_16x16x32_bf16 v[116:119], v[154:157], v[188:191], v[116:119]
	v_mfma_f32_16x16x32_bf16 v[112:115], v[172:175], v[188:191], v[112:115]
	v_mfma_f32_16x16x32_bf16 v[100:103], v[154:157], v[196:199], v[100:103]
	v_mfma_f32_16x16x32_bf16 v[96:99], v[172:175], v[196:199], v[96:99]
	v_mfma_f32_16x16x32_bf16 v[84:87], v[154:157], v[204:207], v[84:87]
	v_mfma_f32_16x16x32_bf16 v[80:83], v[172:175], v[204:207], v[80:83]
	s_barrier
	s_add_i32 s33, s80, s28
	s_add_u32 s98, s74, s14
	s_addc_u32 s99, s75, s15
	s_mov_b32 m0, s33
	ds_read_b128 v[208:211], v169
	ds_read_b128 v[212:215], v169 offset:1024
	ds_read_b128 v[218:221], v169 offset:2048
	ds_read_b128 v[222:225], v169 offset:3072
	global_load_lds_dwordx4 v132, s[74:75]
	s_add_i32 m0, s33, 0x2000
	s_nop 0
	global_load_lds_dwordx4 v136, s[74:75]
	s_barrier
	s_waitcnt lgkmcnt(0)
	s_waitcnt lgkmcnt(0)
	v_mfma_f32_16x16x32_bf16 v[108:111], v[208:211], v[176:179], v[108:111]
	v_mfma_f32_16x16x32_bf16 v[104:107], v[218:221], v[176:179], v[104:107]
	v_mfma_f32_16x16x32_bf16 v[92:95], v[208:211], v[184:187], v[92:95]
	v_mfma_f32_16x16x32_bf16 v[88:91], v[218:221], v[184:187], v[88:91]
	v_mfma_f32_16x16x32_bf16 v[76:79], v[208:211], v[192:195], v[76:79]
	v_mfma_f32_16x16x32_bf16 v[72:75], v[218:221], v[192:195], v[72:75]
	v_mfma_f32_16x16x32_bf16 v[68:71], v[208:211], v[200:203], v[68:71]
	v_mfma_f32_16x16x32_bf16 v[64:67], v[218:221], v[200:203], v[64:67]
	v_mfma_f32_16x16x32_bf16 v[108:111], v[212:215], v[180:183], v[108:111]
	v_mfma_f32_16x16x32_bf16 v[104:107], v[222:225], v[180:183], v[104:107]
	v_mfma_f32_16x16x32_bf16 v[92:95], v[212:215], v[188:191], v[92:95]
	v_mfma_f32_16x16x32_bf16 v[88:91], v[222:225], v[188:191], v[88:91]
	v_mfma_f32_16x16x32_bf16 v[76:79], v[212:215], v[196:199], v[76:79]
	v_mfma_f32_16x16x32_bf16 v[72:75], v[222:225], v[196:199], v[72:75]
	v_mfma_f32_16x16x32_bf16 v[68:71], v[212:215], v[204:207], v[68:71]
	v_mfma_f32_16x16x32_bf16 v[64:67], v[222:225], v[204:207], v[64:67]
	s_mov_b32 m0, s11
	s_add_u32 s100, s4, s14
	s_addc_u32 s101, s5, s15
	s_barrier
	s_waitcnt vmcnt(8)
	ds_read_b128 v[176:179], v168 offset:16384
	ds_read_b128 v[180:183], v168 offset:17408
	ds_read_b128 v[184:187], v168 offset:18432
	ds_read_b128 v[188:191], v168 offset:19456
	ds_read_b128 v[192:195], v168 offset:20480
	ds_read_b128 v[196:199], v168 offset:21504
	ds_read_b128 v[200:203], v168 offset:22528
	ds_read_b128 v[204:207], v168 offset:23552
	global_load_lds_dwordx4 v130, s[4:5]
	s_mov_b32 m0, s29
	s_nop 0
	global_load_lds_dwordx4 v134, s[4:5]
	s_barrier
	s_waitcnt lgkmcnt(0)
	s_waitcnt lgkmcnt(0)
	v_mfma_f32_16x16x32_bf16 v[60:63], v[150:153], v[176:179], v[60:63]
	v_mfma_f32_16x16x32_bf16 v[56:59], v[158:161], v[176:179], v[56:59]
	v_mfma_f32_16x16x32_bf16 v[52:55], v[150:153], v[184:187], v[52:55]
	v_mfma_f32_16x16x32_bf16 v[48:51], v[158:161], v[184:187], v[48:51]
	v_mfma_f32_16x16x32_bf16 v[40:43], v[150:153], v[192:195], v[40:43]
	v_mfma_f32_16x16x32_bf16 v[32:35], v[158:161], v[192:195], v[32:35]
	v_mfma_f32_16x16x32_bf16 v[24:27], v[150:153], v[200:203], v[24:27]
	v_mfma_f32_16x16x32_bf16 v[16:19], v[158:161], v[200:203], v[16:19]
	v_mfma_f32_16x16x32_bf16 v[60:63], v[154:157], v[180:183], v[60:63]
	v_mfma_f32_16x16x32_bf16 v[56:59], v[172:175], v[180:183], v[56:59]
	v_mfma_f32_16x16x32_bf16 v[52:55], v[154:157], v[188:191], v[52:55]
	v_mfma_f32_16x16x32_bf16 v[48:51], v[172:175], v[188:191], v[48:51]
	v_mfma_f32_16x16x32_bf16 v[40:43], v[154:157], v[196:199], v[40:43]
	v_mfma_f32_16x16x32_bf16 v[32:35], v[172:175], v[196:199], v[32:35]
	v_mfma_f32_16x16x32_bf16 v[24:27], v[154:157], v[204:207], v[24:27]
	v_mfma_f32_16x16x32_bf16 v[16:19], v[172:175], v[204:207], v[16:19]
	s_barrier
	s_add_u32 s76, s74, 0x80000
	s_addc_u32 s77, s75, 0
	s_add_i32 s33, s81, s28
	s_mov_b32 m0, s33
	s_nop 0
	global_load_lds_dwordx4 v132, s[76:77]
	s_add_i32 m0, s33, 0x2000
	s_nop 0
	global_load_lds_dwordx4 v136, s[76:77]
	v_add_u32_e32 v138, 0x18000, v164
	ds_read_b128 v[150:153], v138
	ds_read_b128 v[154:157], v138 offset:1024
	ds_read_b128 v[158:161], v138 offset:2048
	ds_read_b128 v[172:175], v138 offset:3072
	s_waitcnt vmcnt(6)
	s_barrier
	v_mfma_f32_16x16x32_bf16 v[44:47], v[208:211], v[176:179], v[44:47]
	v_mfma_f32_16x16x32_bf16 v[36:39], v[218:221], v[176:179], v[36:39]
	v_mfma_f32_16x16x32_bf16 v[28:31], v[208:211], v[184:187], v[28:31]
	v_mfma_f32_16x16x32_bf16 v[20:23], v[218:221], v[184:187], v[20:23]
	v_mfma_f32_16x16x32_bf16 v[12:15], v[208:211], v[192:195], v[12:15]
	v_mfma_f32_16x16x32_bf16 v[8:11], v[218:221], v[192:195], v[8:11]
	v_mfma_f32_16x16x32_bf16 v[4:7], v[208:211], v[200:203], v[4:7]
	v_mfma_f32_16x16x32_bf16 v[0:3], v[218:221], v[200:203], v[0:3]
	v_mfma_f32_16x16x32_bf16 v[44:47], v[212:215], v[180:183], v[44:47]
	v_mfma_f32_16x16x32_bf16 v[36:39], v[222:225], v[180:183], v[36:39]
	v_mfma_f32_16x16x32_bf16 v[28:31], v[212:215], v[188:191], v[28:31]
	v_mfma_f32_16x16x32_bf16 v[20:23], v[222:225], v[188:191], v[20:23]
	v_mfma_f32_16x16x32_bf16 v[12:15], v[212:215], v[196:199], v[12:15]
	v_mfma_f32_16x16x32_bf16 v[8:11], v[222:225], v[196:199], v[8:11]
	v_mfma_f32_16x16x32_bf16 v[4:7], v[212:215], v[204:207], v[4:7]
	v_mfma_f32_16x16x32_bf16 v[0:3], v[222:225], v[204:207], v[0:3]
	s_add_i32 s33, 0, 0x18000
	s_barrier
	s_add_u32 s4, s4, 0x80000
	s_addc_u32 s5, s5, 0
	s_mov_b32 m0, s36
	ds_read_b128 v[176:179], v168 offset:32768
	ds_read_b128 v[180:183], v168 offset:33792
	ds_read_b128 v[184:187], v168 offset:34816
	ds_read_b128 v[188:191], v168 offset:35840
	ds_read_b128 v[192:195], v168 offset:36864
	ds_read_b128 v[196:199], v168 offset:37888
	ds_read_b128 v[200:203], v168 offset:38912
	ds_read_b128 v[204:207], v168 offset:39936
	global_load_lds_dwordx4 v130, s[4:5]
	s_mov_b32 m0, s37
	s_nop 0
	global_load_lds_dwordx4 v134, s[4:5]
	s_waitcnt lgkmcnt(8)
	s_barrier
	s_waitcnt lgkmcnt(0)
	s_waitcnt lgkmcnt(0)
	v_mfma_f32_16x16x32_bf16 v[124:127], v[150:153], v[176:179], v[124:127]
	v_mfma_f32_16x16x32_bf16 v[120:123], v[158:161], v[176:179], v[120:123]
	v_mfma_f32_16x16x32_bf16 v[116:119], v[150:153], v[184:187], v[116:119]
	v_mfma_f32_16x16x32_bf16 v[112:115], v[158:161], v[184:187], v[112:115]
	v_mfma_f32_16x16x32_bf16 v[100:103], v[150:153], v[192:195], v[100:103]
	v_mfma_f32_16x16x32_bf16 v[96:99], v[158:161], v[192:195], v[96:99]
	v_mfma_f32_16x16x32_bf16 v[84:87], v[150:153], v[200:203], v[84:87]
	v_mfma_f32_16x16x32_bf16 v[80:83], v[158:161], v[200:203], v[80:83]
	v_mfma_f32_16x16x32_bf16 v[124:127], v[154:157], v[180:183], v[124:127]
	v_mfma_f32_16x16x32_bf16 v[120:123], v[172:175], v[180:183], v[120:123]
	v_mfma_f32_16x16x32_bf16 v[116:119], v[154:157], v[188:191], v[116:119]
	v_mfma_f32_16x16x32_bf16 v[112:115], v[172:175], v[188:191], v[112:115]
	v_mfma_f32_16x16x32_bf16 v[100:103], v[154:157], v[196:199], v[100:103]
	v_mfma_f32_16x16x32_bf16 v[96:99], v[172:175], v[196:199], v[96:99]
	v_mfma_f32_16x16x32_bf16 v[84:87], v[154:157], v[204:207], v[84:87]
	v_mfma_f32_16x16x32_bf16 v[80:83], v[172:175], v[204:207], v[80:83]
	s_barrier
	s_add_i32 s65, 0, 0x1c000
	s_add_i32 s4, s33, s28
	v_add_u32_e32 v138, s65, v164
	s_mov_b32 m0, s4
	ds_read_b128 v[208:211], v138
	ds_read_b128 v[212:215], v138 offset:1024
	ds_read_b128 v[218:221], v138 offset:2048
	ds_read_b128 v[222:225], v138 offset:3072
	global_load_lds_dwordx4 v132, s[98:99]
	s_add_i32 m0, s4, 0x2000
	s_nop 0
	global_load_lds_dwordx4 v136, s[98:99]
	s_barrier
	s_waitcnt lgkmcnt(0)
	s_waitcnt lgkmcnt(0)
	v_mfma_f32_16x16x32_bf16 v[108:111], v[208:211], v[176:179], v[108:111]
	v_mfma_f32_16x16x32_bf16 v[104:107], v[218:221], v[176:179], v[104:107]
	v_mfma_f32_16x16x32_bf16 v[92:95], v[208:211], v[184:187], v[92:95]
	v_mfma_f32_16x16x32_bf16 v[88:91], v[218:221], v[184:187], v[88:91]
	v_mfma_f32_16x16x32_bf16 v[76:79], v[208:211], v[192:195], v[76:79]
	v_mfma_f32_16x16x32_bf16 v[72:75], v[218:221], v[192:195], v[72:75]
	v_mfma_f32_16x16x32_bf16 v[68:71], v[208:211], v[200:203], v[68:71]
	v_mfma_f32_16x16x32_bf16 v[64:67], v[218:221], v[200:203], v[64:67]
	v_mfma_f32_16x16x32_bf16 v[108:111], v[212:215], v[180:183], v[108:111]
	v_mfma_f32_16x16x32_bf16 v[104:107], v[222:225], v[180:183], v[104:107]
	v_mfma_f32_16x16x32_bf16 v[92:95], v[212:215], v[188:191], v[92:95]
	v_mfma_f32_16x16x32_bf16 v[88:91], v[222:225], v[188:191], v[88:91]
	v_mfma_f32_16x16x32_bf16 v[76:79], v[212:215], v[196:199], v[76:79]
	v_mfma_f32_16x16x32_bf16 v[72:75], v[222:225], v[196:199], v[72:75]
	v_mfma_f32_16x16x32_bf16 v[68:71], v[212:215], v[204:207], v[68:71]
	v_mfma_f32_16x16x32_bf16 v[64:67], v[222:225], v[204:207], v[64:67]
	s_mov_b32 m0, s73
	s_barrier
	s_waitcnt vmcnt(8)
	ds_read_b128 v[176:179], v168 offset:49152
	ds_read_b128 v[180:183], v168 offset:50176
	ds_read_b128 v[184:187], v168 offset:51200
	ds_read_b128 v[188:191], v168 offset:52224
	ds_read_b128 v[192:195], v168 offset:53248
	ds_read_b128 v[196:199], v168 offset:54272
	ds_read_b128 v[200:203], v168 offset:55296
	ds_read_b128 v[204:207], v168 offset:56320
	global_load_lds_dwordx4 v130, s[100:101]
	s_mov_b32 m0, s78
	s_nop 0
	global_load_lds_dwordx4 v134, s[100:101]
	s_barrier
	s_waitcnt lgkmcnt(0)
	s_waitcnt lgkmcnt(0)
	v_mfma_f32_16x16x32_bf16 v[60:63], v[150:153], v[176:179], v[60:63]
	v_mfma_f32_16x16x32_bf16 v[56:59], v[158:161], v[176:179], v[56:59]
	v_mfma_f32_16x16x32_bf16 v[52:55], v[150:153], v[184:187], v[52:55]
	v_mfma_f32_16x16x32_bf16 v[48:51], v[158:161], v[184:187], v[48:51]
	v_mfma_f32_16x16x32_bf16 v[40:43], v[150:153], v[192:195], v[40:43]
	v_mfma_f32_16x16x32_bf16 v[32:35], v[158:161], v[192:195], v[32:35]
	v_mfma_f32_16x16x32_bf16 v[24:27], v[150:153], v[200:203], v[24:27]
	v_mfma_f32_16x16x32_bf16 v[16:19], v[158:161], v[200:203], v[16:19]
	v_mfma_f32_16x16x32_bf16 v[60:63], v[154:157], v[180:183], v[60:63]
	v_mfma_f32_16x16x32_bf16 v[56:59], v[172:175], v[180:183], v[56:59]
	v_mfma_f32_16x16x32_bf16 v[52:55], v[154:157], v[188:191], v[52:55]
	v_mfma_f32_16x16x32_bf16 v[48:51], v[172:175], v[188:191], v[48:51]
	v_mfma_f32_16x16x32_bf16 v[40:43], v[154:157], v[196:199], v[40:43]
	v_mfma_f32_16x16x32_bf16 v[32:35], v[172:175], v[196:199], v[32:35]
	v_mfma_f32_16x16x32_bf16 v[24:27], v[154:157], v[204:207], v[24:27]
	v_mfma_f32_16x16x32_bf16 v[16:19], v[172:175], v[204:207], v[16:19]
	s_barrier
	s_add_u32 s4, s74, 0x80080
	s_addc_u32 s5, s75, 0
	s_add_i32 s33, s65, s28
	s_mov_b32 m0, s33
	s_nop 0
	global_load_lds_dwordx4 v132, s[4:5]
	s_add_i32 m0, s33, 0x2000
	s_nop 0
	global_load_lds_dwordx4 v136, s[4:5]
	ds_read_b128 v[150:153], v167
	ds_read_b128 v[154:157], v167 offset:1024
	ds_read_b128 v[158:161], v167 offset:2048
	ds_read_b128 v[172:175], v167 offset:3072
	s_waitcnt vmcnt(6)
	s_barrier
	v_mfma_f32_16x16x32_bf16 v[44:47], v[208:211], v[176:179], v[44:47]
	v_mfma_f32_16x16x32_bf16 v[36:39], v[218:221], v[176:179], v[36:39]
	v_mfma_f32_16x16x32_bf16 v[28:31], v[208:211], v[184:187], v[28:31]
	v_mfma_f32_16x16x32_bf16 v[20:23], v[218:221], v[184:187], v[20:23]
	v_mfma_f32_16x16x32_bf16 v[12:15], v[208:211], v[192:195], v[12:15]
	v_mfma_f32_16x16x32_bf16 v[8:11], v[218:221], v[192:195], v[8:11]
	v_mfma_f32_16x16x32_bf16 v[4:7], v[208:211], v[200:203], v[4:7]
	v_mfma_f32_16x16x32_bf16 v[0:3], v[218:221], v[200:203], v[0:3]
	v_mfma_f32_16x16x32_bf16 v[44:47], v[212:215], v[180:183], v[44:47]
	v_mfma_f32_16x16x32_bf16 v[36:39], v[222:225], v[180:183], v[36:39]
	v_mfma_f32_16x16x32_bf16 v[28:31], v[212:215], v[188:191], v[28:31]
	v_mfma_f32_16x16x32_bf16 v[20:23], v[222:225], v[188:191], v[20:23]
	v_mfma_f32_16x16x32_bf16 v[12:15], v[212:215], v[196:199], v[12:15]
	v_mfma_f32_16x16x32_bf16 v[8:11], v[222:225], v[196:199], v[8:11]
	v_mfma_f32_16x16x32_bf16 v[4:7], v[212:215], v[204:207], v[4:7]
	v_mfma_f32_16x16x32_bf16 v[0:3], v[222:225], v[204:207], v[0:3]
	s_add_i32 s25, s25, 2
	s_add_u32 s8, s8, 0x100
	s_addc_u32 s9, s9, 0
	s_add_u32 s12, s12, 0x100
	s_addc_u32 s24, s24, 0
	s_cmp_gt_u32 s25, 29
	s_barrier
	s_cbranch_scc0 .LBB0_316
	s_and_b32 s0, s10, -8
	v_lshl_add_u32 v150, s72, 8, v129
	s_cmp_lg_u32 s0, 8
	s_mov_b64 s[0:1], -1
	s_cbranch_scc0 .LBB0_435
	s_cmp_gt_i32 s10, 23
	s_cbranch_scc0 .LBB0_432
	s_cmp_lt_i32 s10, 26
	s_cbranch_scc1 .LBB0_323
	s_cmp_eq_u32 s10, 26
	v_mov_b32_e32 v161, v123
	v_mov_b32_e32 v160, v122
	v_mov_b32_e32 v157, v121
	v_mov_b32_e32 v156, v120
	v_mov_b32_e32 v163, v127
	v_mov_b32_e32 v162, v126
	v_mov_b32_e32 v159, v125
	v_mov_b32_e32 v158, v124
	s_cbranch_scc0 .LBB0_322
	v_mul_f32_e32 v138, 0xbfb8aa3b, v124
	v_exp_f32_e32 v138, v138
	v_mul_f32_e32 v151, 0xbfb8aa3b, v120
	v_exp_f32_e32 v151, v151
	v_mul_f32_e32 v152, 0xbfb8aa3b, v121
	v_add_f32_e32 v138, 1.0, v138
	v_rcp_f32_e32 v158, v138
	v_mul_f32_e32 v138, 0xbfb8aa3b, v125
	v_exp_f32_e32 v138, v138
	v_exp_f32_e32 v152, v152
	v_add_f32_e32 v151, 1.0, v151
	v_rcp_f32_e32 v156, v151
	v_add_f32_e32 v138, 1.0, v138
	v_mul_f32_e32 v151, 0xbfb8aa3b, v126
	v_rcp_f32_e32 v159, v138
	v_add_f32_e32 v138, 1.0, v152
	v_exp_f32_e32 v151, v151
	v_mul_f32_e32 v152, 0xbfb8aa3b, v122
	v_exp_f32_e32 v152, v152
	v_rcp_f32_e32 v157, v138
	v_add_f32_e32 v138, 1.0, v151
	v_mul_f32_e32 v151, 0xbfb8aa3b, v127
	v_rcp_f32_e32 v162, v138
	v_add_f32_e32 v138, 1.0, v152
	v_exp_f32_e32 v151, v151
	v_mul_f32_e32 v152, 0xbfb8aa3b, v123
	v_exp_f32_e32 v152, v152
	v_rcp_f32_e32 v160, v138
	v_add_f32_e32 v138, 1.0, v151
	v_rcp_f32_e32 v163, v138
	v_add_f32_e32 v138, 1.0, v152
	v_rcp_f32_e32 v161, v138

.LBB0_849:
	s_ashr_i32 s67, s66, 31
	v_cmp_lt_i64_e32 vcc, s[0:1], v[136:137]
	s_lshl_b64 s[0:1], s[66:67], 20
	s_add_u32 s68, s8, s0
	s_addc_u32 s69, s9, s1
	s_and_b64 s[0:1], vcc, exec
	s_cselect_b32 s0, s69, s75
	s_cselect_b32 s1, s68, s74
	s_ashr_i32 s61, s60, 31
	s_lshl_b64 s[4:5], s[60:61], 20
	s_add_u32 s70, s64, s4
	s_addc_u32 s71, s65, s5
	s_and_b64 s[4:5], vcc, exec
	s_cselect_b32 s46, s71, s51
	s_cselect_b32 s47, s70, s50
	s_add_u32 s61, s50, 0x100
	v_mov_b32_e32 v0, 0
	s_addc_u32 s67, s51, 0
	s_mov_b32 s73, -2
	v_mov_b32_e32 v1, v0
	v_mov_b32_e32 v2, v0
	v_mov_b32_e32 v3, v0
	v_mov_b32_e32 v20, v0
	v_mov_b32_e32 v21, v0
	v_mov_b32_e32 v22, v0
	v_mov_b32_e32 v23, v0
	v_mov_b32_e32 v4, v0
	v_mov_b32_e32 v5, v0
	v_mov_b32_e32 v6, v0
	v_mov_b32_e32 v7, v0
	v_mov_b32_e32 v28, v0
	v_mov_b32_e32 v29, v0
	v_mov_b32_e32 v30, v0
	v_mov_b32_e32 v31, v0
	v_mov_b32_e32 v8, v0
	v_mov_b32_e32 v9, v0
	v_mov_b32_e32 v10, v0
	v_mov_b32_e32 v11, v0
	v_mov_b32_e32 v36, v0
	v_mov_b32_e32 v37, v0
	v_mov_b32_e32 v38, v0
	v_mov_b32_e32 v39, v0
	v_mov_b32_e32 v12, v0
	v_mov_b32_e32 v13, v0
	v_mov_b32_e32 v14, v0
	v_mov_b32_e32 v15, v0
	v_mov_b32_e32 v44, v0
	v_mov_b32_e32 v45, v0
	v_mov_b32_e32 v46, v0
	v_mov_b32_e32 v47, v0
	v_mov_b32_e32 v56, v0
	v_mov_b32_e32 v57, v0
	v_mov_b32_e32 v58, v0
	v_mov_b32_e32 v59, v0
	v_mov_b32_e32 v84, v0
	v_mov_b32_e32 v85, v0
	v_mov_b32_e32 v86, v0
	v_mov_b32_e32 v87, v0
	v_mov_b32_e32 v64, v0
	v_mov_b32_e32 v65, v0
	v_mov_b32_e32 v66, v0
	v_mov_b32_e32 v67, v0
	v_mov_b32_e32 v92, v0
	v_mov_b32_e32 v93, v0
	v_mov_b32_e32 v94, v0
	v_mov_b32_e32 v95, v0
	v_mov_b32_e32 v72, v0
	v_mov_b32_e32 v73, v0
	v_mov_b32_e32 v74, v0
	v_mov_b32_e32 v75, v0
	v_mov_b32_e32 v104, v0
	v_mov_b32_e32 v105, v0
	v_mov_b32_e32 v106, v0
	v_mov_b32_e32 v107, v0
	v_mov_b32_e32 v76, v0
	v_mov_b32_e32 v77, v0
	v_mov_b32_e32 v78, v0
	v_mov_b32_e32 v79, v0
	v_mov_b32_e32 v108, v0
	v_mov_b32_e32 v109, v0
	v_mov_b32_e32 v110, v0
	v_mov_b32_e32 v111, v0
	v_mov_b32_e32 v16, v0
	v_mov_b32_e32 v17, v0
	v_mov_b32_e32 v18, v0
	v_mov_b32_e32 v19, v0
	v_mov_b32_e32 v48, v0
	v_mov_b32_e32 v49, v0
	v_mov_b32_e32 v50, v0
	v_mov_b32_e32 v51, v0
	v_mov_b32_e32 v24, v0
	v_mov_b32_e32 v25, v0
	v_mov_b32_e32 v26, v0
	v_mov_b32_e32 v27, v0
	v_mov_b32_e32 v52, v0
	v_mov_b32_e32 v53, v0
	v_mov_b32_e32 v54, v0
	v_mov_b32_e32 v55, v0
	v_mov_b32_e32 v32, v0
	v_mov_b32_e32 v33, v0
	v_mov_b32_e32 v34, v0
	v_mov_b32_e32 v35, v0
	v_mov_b32_e32 v60, v0
	v_mov_b32_e32 v61, v0
	v_mov_b32_e32 v62, v0
	v_mov_b32_e32 v63, v0
	v_mov_b32_e32 v40, v0
	v_mov_b32_e32 v41, v0
	v_mov_b32_e32 v42, v0
	v_mov_b32_e32 v43, v0
	v_mov_b32_e32 v68, v0
	v_mov_b32_e32 v69, v0
	v_mov_b32_e32 v70, v0
	v_mov_b32_e32 v71, v0
	v_mov_b32_e32 v80, v0
	v_mov_b32_e32 v81, v0
	v_mov_b32_e32 v82, v0
	v_mov_b32_e32 v83, v0
	v_mov_b32_e32 v112, v0
	v_mov_b32_e32 v113, v0
	v_mov_b32_e32 v114, v0
	v_mov_b32_e32 v115, v0
	v_mov_b32_e32 v88, v0
	v_mov_b32_e32 v89, v0
	v_mov_b32_e32 v90, v0
	v_mov_b32_e32 v91, v0
	v_mov_b32_e32 v116, v0
	v_mov_b32_e32 v117, v0
	v_mov_b32_e32 v118, v0
	v_mov_b32_e32 v119, v0
	v_mov_b32_e32 v96, v0
	v_mov_b32_e32 v97, v0
	v_mov_b32_e32 v98, v0
	v_mov_b32_e32 v99, v0
	v_mov_b32_e32 v120, v0
	v_mov_b32_e32 v121, v0
	v_mov_b32_e32 v122, v0
	v_mov_b32_e32 v123, v0
	v_mov_b32_e32 v100, v0
	v_mov_b32_e32 v101, v0
	v_mov_b32_e32 v102, v0
	v_mov_b32_e32 v103, v0
	v_mov_b32_e32 v124, v0
	v_mov_b32_e32 v125, v0
	v_mov_b32_e32 v126, v0
	v_mov_b32_e32 v127, v0
	ds_read_b128 v[140:143], v147
	ds_read_b128 v[150:153], v147 offset:1024
	ds_read_b128 v[154:157], v147 offset:2048
	ds_read_b128 v[158:161], v147 offset:3072
	.p2alignl 6, 3212836864
.LBB0_850:
	s_add_u32 s76, s74, 0x100
	s_addc_u32 s77, s75, 0
	s_cmp_eq_u32 s73, 28
	s_cselect_b32 s5, s0, s77
	s_cselect_b32 s4, s1, s76
	s_cselect_b32 s51, s46, s67
	s_cselect_b32 s50, s47, s61
	s_add_i32 m0, s23, 0xc000
	ds_read_b128 v[162:165], v148
	ds_read_b128 v[166:169], v148 offset:1024
	ds_read_b128 v[170:173], v148 offset:2048
	ds_read_b128 v[174:177], v148 offset:3072
	ds_read_b128 v[178:181], v148 offset:4096
	ds_read_b128 v[182:185], v148 offset:5120
	ds_read_b128 v[186:189], v148 offset:6144
	ds_read_b128 v[190:193], v148 offset:7168
	global_load_lds_dwordx4 v132, s[74:75]
	s_add_i32 m0, s23, 0xe000
	s_nop 0
	global_load_lds_dwordx4 v134, s[74:75]
	s_waitcnt lgkmcnt(8)
	s_barrier
	s_waitcnt lgkmcnt(0)
	s_waitcnt lgkmcnt(0)
	v_mfma_f32_16x16x32_bf16 v[124:127], v[140:143], v[162:165], v[124:127]
	v_mfma_f32_16x16x32_bf16 v[100:103], v[154:157], v[162:165], v[100:103]
	v_mfma_f32_16x16x32_bf16 v[120:123], v[140:143], v[170:173], v[120:123]
	v_mfma_f32_16x16x32_bf16 v[96:99], v[154:157], v[170:173], v[96:99]
	v_mfma_f32_16x16x32_bf16 v[116:119], v[140:143], v[178:181], v[116:119]
	v_mfma_f32_16x16x32_bf16 v[88:91], v[154:157], v[178:181], v[88:91]
	v_mfma_f32_16x16x32_bf16 v[112:115], v[140:143], v[186:189], v[112:115]
	v_mfma_f32_16x16x32_bf16 v[80:83], v[154:157], v[186:189], v[80:83]
	v_mfma_f32_16x16x32_bf16 v[124:127], v[150:153], v[166:169], v[124:127]
	v_mfma_f32_16x16x32_bf16 v[100:103], v[158:161], v[166:169], v[100:103]
	v_mfma_f32_16x16x32_bf16 v[120:123], v[150:153], v[174:177], v[120:123]
	v_mfma_f32_16x16x32_bf16 v[96:99], v[158:161], v[174:177], v[96:99]
	v_mfma_f32_16x16x32_bf16 v[116:119], v[150:153], v[182:185], v[116:119]
	v_mfma_f32_16x16x32_bf16 v[88:91], v[158:161], v[182:185], v[88:91]
	v_mfma_f32_16x16x32_bf16 v[112:115], v[150:153], v[190:193], v[112:115]
	v_mfma_f32_16x16x32_bf16 v[80:83], v[158:161], v[190:193], v[80:83]
	s_barrier
	s_add_i32 s42, s37, s21
	s_add_u32 s98, s50, s16
	s_addc_u32 s99, s51, s17
	s_mov_b32 m0, s42
	ds_read_b128 v[194:197], v149
	ds_read_b128 v[198:201], v149 offset:1024
	ds_read_b128 v[202:205], v149 offset:2048
	ds_read_b128 v[206:209], v149 offset:3072
	global_load_lds_dwordx4 v130, s[50:51]
	s_add_i32 m0, s42, 0x2000
	s_nop 0
	global_load_lds_dwordx4 v128, s[50:51]
	s_barrier
	s_waitcnt lgkmcnt(0)
	s_waitcnt lgkmcnt(0)
	v_mfma_f32_16x16x32_bf16 v[68:71], v[194:197], v[162:165], v[68:71]
	v_mfma_f32_16x16x32_bf16 v[40:43], v[202:205], v[162:165], v[40:43]
	v_mfma_f32_16x16x32_bf16 v[60:63], v[194:197], v[170:173], v[60:63]
	v_mfma_f32_16x16x32_bf16 v[32:35], v[202:205], v[170:173], v[32:35]
	v_mfma_f32_16x16x32_bf16 v[52:55], v[194:197], v[178:181], v[52:55]
	v_mfma_f32_16x16x32_bf16 v[24:27], v[202:205], v[178:181], v[24:27]
	v_mfma_f32_16x16x32_bf16 v[48:51], v[194:197], v[186:189], v[48:51]
	v_mfma_f32_16x16x32_bf16 v[16:19], v[202:205], v[186:189], v[16:19]
	v_mfma_f32_16x16x32_bf16 v[68:71], v[198:201], v[166:169], v[68:71]
	v_mfma_f32_16x16x32_bf16 v[40:43], v[206:209], v[166:169], v[40:43]
	v_mfma_f32_16x16x32_bf16 v[60:63], v[198:201], v[174:177], v[60:63]
	v_mfma_f32_16x16x32_bf16 v[32:35], v[206:209], v[174:177], v[32:35]
	v_mfma_f32_16x16x32_bf16 v[52:55], v[198:201], v[182:185], v[52:55]
	v_mfma_f32_16x16x32_bf16 v[24:27], v[206:209], v[182:185], v[24:27]
	v_mfma_f32_16x16x32_bf16 v[48:51], v[198:201], v[190:193], v[48:51]
	v_mfma_f32_16x16x32_bf16 v[16:19], v[206:209], v[190:193], v[16:19]
	s_mov_b32 m0, s23
	s_add_u32 s100, s4, s16
	s_addc_u32 s101, s5, s17
	s_barrier
	s_waitcnt vmcnt(8)
	ds_read_b128 v[162:165], v148 offset:16384
	ds_read_b128 v[166:169], v148 offset:17408
	ds_read_b128 v[170:173], v148 offset:18432
	ds_read_b128 v[174:177], v148 offset:19456
	ds_read_b128 v[178:181], v148 offset:20480
	ds_read_b128 v[182:185], v148 offset:21504
	ds_read_b128 v[186:189], v148 offset:22528
	ds_read_b128 v[190:193], v148 offset:23552
	global_load_lds_dwordx4 v130, s[4:5]
	s_mov_b32 m0, s24
	s_nop 0
	global_load_lds_dwordx4 v128, s[4:5]
	s_barrier
	s_waitcnt lgkmcnt(0)
	s_waitcnt lgkmcnt(0)
	v_mfma_f32_16x16x32_bf16 v[108:111], v[140:143], v[162:165], v[108:111]
	v_mfma_f32_16x16x32_bf16 v[76:79], v[154:157], v[162:165], v[76:79]
	v_mfma_f32_16x16x32_bf16 v[104:107], v[140:143], v[170:173], v[104:107]
	v_mfma_f32_16x16x32_bf16 v[72:75], v[154:157], v[170:173], v[72:75]
	v_mfma_f32_16x16x32_bf16 v[92:95], v[140:143], v[178:181], v[92:95]
	v_mfma_f32_16x16x32_bf16 v[64:67], v[154:157], v[178:181], v[64:67]
	v_mfma_f32_16x16x32_bf16 v[84:87], v[140:143], v[186:189], v[84:87]
	v_mfma_f32_16x16x32_bf16 v[56:59], v[154:157], v[186:189], v[56:59]
	v_mfma_f32_16x16x32_bf16 v[108:111], v[150:153], v[166:169], v[108:111]
	v_mfma_f32_16x16x32_bf16 v[76:79], v[158:161], v[166:169], v[76:79]
	v_mfma_f32_16x16x32_bf16 v[104:107], v[150:153], v[174:177], v[104:107]
	v_mfma_f32_16x16x32_bf16 v[72:75], v[158:161], v[174:177], v[72:75]
	v_mfma_f32_16x16x32_bf16 v[92:95], v[150:153], v[182:185], v[92:95]
	v_mfma_f32_16x16x32_bf16 v[64:67], v[158:161], v[182:185], v[64:67]
	v_mfma_f32_16x16x32_bf16 v[84:87], v[150:153], v[190:193], v[84:87]
	v_mfma_f32_16x16x32_bf16 v[56:59], v[158:161], v[190:193], v[56:59]
	s_barrier
	s_add_u32 s42, s50, 0x80000
	s_addc_u32 s43, s51, 0
	s_add_i32 s44, s40, s21
	s_mov_b32 m0, s44
	s_nop 0
	global_load_lds_dwordx4 v130, s[42:43]
	s_add_i32 m0, s44, 0x2000
	s_nop 0
	global_load_lds_dwordx4 v128, s[42:43]
	v_add_u32_e32 v158, 0x18000, v145
	ds_read_b128 v[140:143], v158
	ds_read_b128 v[150:153], v158 offset:1024
	ds_read_b128 v[154:157], v158 offset:2048
	ds_read_b128 v[158:161], v158 offset:3072
	s_waitcnt vmcnt(6)
	s_barrier
	v_mfma_f32_16x16x32_bf16 v[44:47], v[194:197], v[162:165], v[44:47]
	v_mfma_f32_16x16x32_bf16 v[12:15], v[202:205], v[162:165], v[12:15]
	v_mfma_f32_16x16x32_bf16 v[36:39], v[194:197], v[170:173], v[36:39]
	v_mfma_f32_16x16x32_bf16 v[8:11], v[202:205], v[170:173], v[8:11]
	v_mfma_f32_16x16x32_bf16 v[28:31], v[194:197], v[178:181], v[28:31]
	v_mfma_f32_16x16x32_bf16 v[4:7], v[202:205], v[178:181], v[4:7]
	v_mfma_f32_16x16x32_bf16 v[20:23], v[194:197], v[186:189], v[20:23]
	v_mfma_f32_16x16x32_bf16 v[0:3], v[202:205], v[186:189], v[0:3]
	v_mfma_f32_16x16x32_bf16 v[44:47], v[198:201], v[166:169], v[44:47]
	v_mfma_f32_16x16x32_bf16 v[12:15], v[206:209], v[166:169], v[12:15]
	v_mfma_f32_16x16x32_bf16 v[36:39], v[198:201], v[174:177], v[36:39]
	v_mfma_f32_16x16x32_bf16 v[8:11], v[206:209], v[174:177], v[8:11]
	v_mfma_f32_16x16x32_bf16 v[28:31], v[198:201], v[182:185], v[28:31]
	v_mfma_f32_16x16x32_bf16 v[4:7], v[206:209], v[182:185], v[4:7]
	v_mfma_f32_16x16x32_bf16 v[20:23], v[198:201], v[190:193], v[20:23]
	v_mfma_f32_16x16x32_bf16 v[0:3], v[206:209], v[190:193], v[0:3]
	s_add_i32 s42, 0, 0x18000
	s_barrier
	s_add_u32 s4, s4, 0x80000
	s_addc_u32 s5, s5, 0
	s_mov_b32 m0, s25
	ds_read_b128 v[162:165], v148 offset:32768
	ds_read_b128 v[166:169], v148 offset:33792
	ds_read_b128 v[170:173], v148 offset:34816
	ds_read_b128 v[174:177], v148 offset:35840
	ds_read_b128 v[178:181], v148 offset:36864
	ds_read_b128 v[182:185], v148 offset:37888
	ds_read_b128 v[186:189], v148 offset:38912
	ds_read_b128 v[190:193], v148 offset:39936
	global_load_lds_dwordx4 v130, s[4:5]
	s_mov_b32 m0, s28
	s_nop 0
	global_load_lds_dwordx4 v128, s[4:5]
	s_waitcnt lgkmcnt(8)
	s_barrier
	s_waitcnt lgkmcnt(0)
	s_waitcnt lgkmcnt(0)
	v_mfma_f32_16x16x32_bf16 v[124:127], v[140:143], v[162:165], v[124:127]
	v_mfma_f32_16x16x32_bf16 v[100:103], v[154:157], v[162:165], v[100:103]
	v_mfma_f32_16x16x32_bf16 v[120:123], v[140:143], v[170:173], v[120:123]
	v_mfma_f32_16x16x32_bf16 v[96:99], v[154:157], v[170:173], v[96:99]
	v_mfma_f32_16x16x32_bf16 v[116:119], v[140:143], v[178:181], v[116:119]
	v_mfma_f32_16x16x32_bf16 v[88:91], v[154:157], v[178:181], v[88:91]
	v_mfma_f32_16x16x32_bf16 v[112:115], v[140:143], v[186:189], v[112:115]
	v_mfma_f32_16x16x32_bf16 v[80:83], v[154:157], v[186:189], v[80:83]
	v_mfma_f32_16x16x32_bf16 v[124:127], v[150:153], v[166:169], v[124:127]
	v_mfma_f32_16x16x32_bf16 v[100:103], v[158:161], v[166:169], v[100:103]
	v_mfma_f32_16x16x32_bf16 v[120:123], v[150:153], v[174:177], v[120:123]
	v_mfma_f32_16x16x32_bf16 v[96:99], v[158:161], v[174:177], v[96:99]
	v_mfma_f32_16x16x32_bf16 v[116:119], v[150:153], v[182:185], v[116:119]
	v_mfma_f32_16x16x32_bf16 v[88:91], v[158:161], v[182:185], v[88:91]
	v_mfma_f32_16x16x32_bf16 v[112:115], v[150:153], v[190:193], v[112:115]
	v_mfma_f32_16x16x32_bf16 v[80:83], v[158:161], v[190:193], v[80:83]
	s_barrier
	s_add_i32 s43, 0, 0x1c000
	s_add_i32 s4, s42, s21
	v_add_u32_e32 v206, s43, v145
	s_mov_b32 m0, s4
	ds_read_b128 v[194:197], v206
	ds_read_b128 v[198:201], v206 offset:1024
	ds_read_b128 v[202:205], v206 offset:2048
	ds_read_b128 v[206:209], v206 offset:3072
	global_load_lds_dwordx4 v130, s[98:99]
	s_add_i32 m0, s4, 0x2000
	s_nop 0
	global_load_lds_dwordx4 v128, s[98:99]
	s_barrier
	s_waitcnt lgkmcnt(0)
	s_waitcnt lgkmcnt(0)
	v_mfma_f32_16x16x32_bf16 v[68:71], v[194:197], v[162:165], v[68:71]
	v_mfma_f32_16x16x32_bf16 v[40:43], v[202:205], v[162:165], v[40:43]
	v_mfma_f32_16x16x32_bf16 v[60:63], v[194:197], v[170:173], v[60:63]
	v_mfma_f32_16x16x32_bf16 v[32:35], v[202:205], v[170:173], v[32:35]
	v_mfma_f32_16x16x32_bf16 v[52:55], v[194:197], v[178:181], v[52:55]
	v_mfma_f32_16x16x32_bf16 v[24:27], v[202:205], v[178:181], v[24:27]
	v_mfma_f32_16x16x32_bf16 v[48:51], v[194:197], v[186:189], v[48:51]
	v_mfma_f32_16x16x32_bf16 v[16:19], v[202:205], v[186:189], v[16:19]
	v_mfma_f32_16x16x32_bf16 v[68:71], v[198:201], v[166:169], v[68:71]
	v_mfma_f32_16x16x32_bf16 v[40:43], v[206:209], v[166:169], v[40:43]
	v_mfma_f32_16x16x32_bf16 v[60:63], v[198:201], v[174:177], v[60:63]
	v_mfma_f32_16x16x32_bf16 v[32:35], v[206:209], v[174:177], v[32:35]
	v_mfma_f32_16x16x32_bf16 v[52:55], v[198:201], v[182:185], v[52:55]
	v_mfma_f32_16x16x32_bf16 v[24:27], v[206:209], v[182:185], v[24:27]
	v_mfma_f32_16x16x32_bf16 v[48:51], v[198:201], v[190:193], v[48:51]
	v_mfma_f32_16x16x32_bf16 v[16:19], v[206:209], v[190:193], v[16:19]
	s_mov_b32 m0, s33
	s_barrier
	s_waitcnt vmcnt(8)
	ds_read_b128 v[162:165], v148 offset:49152
	ds_read_b128 v[166:169], v148 offset:50176
	ds_read_b128 v[170:173], v148 offset:51200
	ds_read_b128 v[174:177], v148 offset:52224
	ds_read_b128 v[178:181], v148 offset:53248
	ds_read_b128 v[182:185], v148 offset:54272
	ds_read_b128 v[186:189], v148 offset:55296
	ds_read_b128 v[190:193], v148 offset:56320
	global_load_lds_dwordx4 v130, s[100:101]
	s_mov_b32 m0, s36
	s_nop 0
	global_load_lds_dwordx4 v128, s[100:101]
	s_barrier
	s_waitcnt lgkmcnt(0)
	s_waitcnt lgkmcnt(0)
	v_mfma_f32_16x16x32_bf16 v[108:111], v[140:143], v[162:165], v[108:111]
	v_mfma_f32_16x16x32_bf16 v[76:79], v[154:157], v[162:165], v[76:79]
	v_mfma_f32_16x16x32_bf16 v[104:107], v[140:143], v[170:173], v[104:107]
	v_mfma_f32_16x16x32_bf16 v[72:75], v[154:157], v[170:173], v[72:75]
	v_mfma_f32_16x16x32_bf16 v[92:95], v[140:143], v[178:181], v[92:95]
	v_mfma_f32_16x16x32_bf16 v[64:67], v[154:157], v[178:181], v[64:67]
	v_mfma_f32_16x16x32_bf16 v[84:87], v[140:143], v[186:189], v[84:87]
	v_mfma_f32_16x16x32_bf16 v[56:59], v[154:157], v[186:189], v[56:59]
	v_mfma_f32_16x16x32_bf16 v[108:111], v[150:153], v[166:169], v[108:111]
	v_mfma_f32_16x16x32_bf16 v[76:79], v[158:161], v[166:169], v[76:79]
	v_mfma_f32_16x16x32_bf16 v[104:107], v[150:153], v[174:177], v[104:107]
	v_mfma_f32_16x16x32_bf16 v[72:75], v[158:161], v[174:177], v[72:75]
	v_mfma_f32_16x16x32_bf16 v[92:95], v[150:153], v[182:185], v[92:95]
	v_mfma_f32_16x16x32_bf16 v[64:67], v[158:161], v[182:185], v[64:67]
	v_mfma_f32_16x16x32_bf16 v[84:87], v[150:153], v[190:193], v[84:87]
	v_mfma_f32_16x16x32_bf16 v[56:59], v[158:161], v[190:193], v[56:59]
	s_barrier
	s_add_u32 s4, s50, 0x80080
	s_addc_u32 s5, s51, 0
	s_add_i32 s42, s43, s21
	s_mov_b32 m0, s42
	s_nop 0
	global_load_lds_dwordx4 v130, s[4:5]
	s_add_i32 m0, s42, 0x2000
	s_nop 0
	global_load_lds_dwordx4 v128, s[4:5]
	ds_read_b128 v[140:143], v147
	ds_read_b128 v[150:153], v147 offset:1024
	ds_read_b128 v[154:157], v147 offset:2048
	ds_read_b128 v[158:161], v147 offset:3072
	s_waitcnt vmcnt(6)
	s_barrier
	v_mfma_f32_16x16x32_bf16 v[44:47], v[194:197], v[162:165], v[44:47]
	v_mfma_f32_16x16x32_bf16 v[12:15], v[202:205], v[162:165], v[12:15]
	v_mfma_f32_16x16x32_bf16 v[36:39], v[194:197], v[170:173], v[36:39]
	v_mfma_f32_16x16x32_bf16 v[8:11], v[202:205], v[170:173], v[8:11]
	v_mfma_f32_16x16x32_bf16 v[28:31], v[194:197], v[178:181], v[28:31]
	v_mfma_f32_16x16x32_bf16 v[4:7], v[202:205], v[178:181], v[4:7]
	v_mfma_f32_16x16x32_bf16 v[20:23], v[194:197], v[186:189], v[20:23]
	v_mfma_f32_16x16x32_bf16 v[0:3], v[202:205], v[186:189], v[0:3]
	v_mfma_f32_16x16x32_bf16 v[44:47], v[198:201], v[166:169], v[44:47]
	v_mfma_f32_16x16x32_bf16 v[12:15], v[206:209], v[166:169], v[12:15]
	v_mfma_f32_16x16x32_bf16 v[36:39], v[198:201], v[174:177], v[36:39]
	v_mfma_f32_16x16x32_bf16 v[8:11], v[206:209], v[174:177], v[8:11]
	v_mfma_f32_16x16x32_bf16 v[28:31], v[198:201], v[182:185], v[28:31]
	v_mfma_f32_16x16x32_bf16 v[4:7], v[206:209], v[182:185], v[4:7]
	v_mfma_f32_16x16x32_bf16 v[20:23], v[198:201], v[190:193], v[20:23]
	v_mfma_f32_16x16x32_bf16 v[0:3], v[206:209], v[190:193], v[0:3]
	s_add_i32 s73, s73, 2
	s_add_u32 s61, s61, 0x100
	s_addc_u32 s67, s67, 0
	s_cmp_gt_u32 s73, 29
	s_mov_b64 s[74:75], s[76:77]
	s_barrier
	s_cbranch_scc0 .LBB0_850
	v_lshl_or_b32 v140, s41, 8, v146
	v_lshl_add_u32 v143, s72, 8, v144
	v_lshlrev_b32_e32 v140, 2, v140
	v_lshl_add_u32 v143, v143, 13, v140
	s_mov_b32 s41, s60
	s_mov_b32 s72, s66
	s_mov_b64 s[50:51], s[70:71]
	s_mov_b64 s[74:75], s[68:69]
	v_mov_b32_e32 v141, v143
	v_mov_b32_e32 v142, v143
	global_load_dwordx4 v[166:169], v140, s[14:15] offset:0
	global_load_dwordx4 v[150:153], v141, s[10:11] offset:0
	v_add_u32_e32 v141, 0x20000, v141
	global_load_dwordx4 v[154:157], v141, s[10:11] offset:0
	v_add_u32_e32 v141, 0x20000, v141
	global_load_dwordx4 v[158:161], v141, s[10:11] offset:0
	v_add_u32_e32 v141, 0x20000, v141
	global_load_dwordx4 v[162:165], v141, s[10:11] offset:0
	v_add_u32_e32 v141, 0xa0000, v141
	s_waitcnt vmcnt(3)
	v_pk_fma_f32 v[150:151], v[124:125], v[166:167], v[150:151]
	v_pk_fma_f32 v[152:153], v[126:127], v[168:169], v[152:153]
	global_store_dwordx4 v142, v[150:153], s[12:13] offset:0
	v_add_u32_e32 v142, 0x20000, v142
	global_load_dwordx4 v[150:153], v141, s[10:11] offset:0
	v_add_u32_e32 v141, 0x20000, v141
	s_waitcnt vmcnt(4)
	v_pk_fma_f32 v[154:155], v[120:121], v[166:167], v[154:155]
	v_pk_fma_f32 v[156:157], v[122:123], v[168:169], v[156:157]
	global_store_dwordx4 v142, v[154:157], s[12:13] offset:0
	v_add_u32_e32 v142, 0x20000, v142
	global_load_dwordx4 v[154:157], v141, s[10:11] offset:0
	v_add_u32_e32 v141, 0x20000, v141
	s_waitcnt vmcnt(5)
	v_pk_fma_f32 v[158:159], v[116:117], v[166:167], v[158:159]
	v_pk_fma_f32 v[160:161], v[118:119], v[168:169], v[160:161]
	global_store_dwordx4 v142, v[158:161], s[12:13] offset:0
	v_add_u32_e32 v142, 0x20000, v142
	global_load_dwordx4 v[158:161], v141, s[10:11] offset:0
	v_add_u32_e32 v141, 0x20000, v141
	s_waitcnt vmcnt(6)
	v_pk_fma_f32 v[162:163], v[112:113], v[166:167], v[162:163]
	v_pk_fma_f32 v[164:165], v[114:115], v[168:169], v[164:165]
	global_store_dwordx4 v142, v[162:165], s[12:13] offset:0
	v_add_u32_e32 v142, 0xa0000, v142
	global_load_dwordx4 v[162:165], v141, s[10:11] offset:0
	v_add_u32_e32 v141, 0x20000, v141
	s_waitcnt vmcnt(6)
	v_pk_fma_f32 v[150:151], v[108:109], v[166:167], v[150:151]
	v_pk_fma_f32 v[152:153], v[110:111], v[168:169], v[152:153]
	global_store_dwordx4 v142, v[150:153], s[12:13] offset:0
	v_add_u32_e32 v142, 0x20000, v142
	s_waitcnt vmcnt(5)
	v_pk_fma_f32 v[154:155], v[104:105], v[166:167], v[154:155]
	v_pk_fma_f32 v[156:157], v[106:107], v[168:169], v[156:157]
	global_store_dwordx4 v142, v[154:157], s[12:13] offset:0
	v_add_u32_e32 v142, 0x20000, v142
	s_waitcnt vmcnt(4)
	v_pk_fma_f32 v[158:159], v[92:93], v[166:167], v[158:159]
	v_pk_fma_f32 v[160:161], v[94:95], v[168:169], v[160:161]
	global_store_dwordx4 v142, v[158:161], s[12:13] offset:0
	v_add_u32_e32 v142, 0x20000, v142
	s_waitcnt vmcnt(3)
	v_pk_fma_f32 v[162:163], v[84:85], v[166:167], v[162:163]
	v_pk_fma_f32 v[164:165], v[86:87], v[168:169], v[164:165]
	global_store_dwordx4 v142, v[162:165], s[12:13] offset:0
	v_add_u32_e32 v142, 0x20000, v142
	v_mov_b32_e32 v141, v143
	v_mov_b32_e32 v142, v143
	global_load_dwordx4 v[166:169], v140, s[14:15] offset:64
	global_load_dwordx4 v[150:153], v141, s[10:11] offset:64
	v_add_u32_e32 v141, 0x20000, v141
	global_load_dwordx4 v[154:157], v141, s[10:11] offset:64
	v_add_u32_e32 v141, 0x20000, v141
	global_load_dwordx4 v[158:161], v141, s[10:11] offset:64
	v_add_u32_e32 v141, 0x20000, v141
	global_load_dwordx4 v[162:165], v141, s[10:11] offset:64
	v_add_u32_e32 v141, 0xa0000, v141
	s_waitcnt vmcnt(3)
	v_pk_fma_f32 v[150:151], v[100:101], v[166:167], v[150:151]
	v_pk_fma_f32 v[152:153], v[102:103], v[168:169], v[152:153]
	global_store_dwordx4 v142, v[150:153], s[12:13] offset:64
	v_add_u32_e32 v142, 0x20000, v142
	global_load_dwordx4 v[150:153], v141, s[10:11] offset:64
	v_add_u32_e32 v141, 0x20000, v141
	s_waitcnt vmcnt(4)
	v_pk_fma_f32 v[154:155], v[96:97], v[166:167], v[154:155]
	v_pk_fma_f32 v[156:157], v[98:99], v[168:169], v[156:157]
	global_store_dwordx4 v142, v[154:157], s[12:13] offset:64
	v_add_u32_e32 v142, 0x20000, v142
	global_load_dwordx4 v[154:157], v141, s[10:11] offset:64
	v_add_u32_e32 v141, 0x20000, v141
	s_waitcnt vmcnt(5)
	v_pk_fma_f32 v[158:159], v[88:89], v[166:167], v[158:159]
	v_pk_fma_f32 v[160:161], v[90:91], v[168:169], v[160:161]
	global_store_dwordx4 v142, v[158:161], s[12:13] offset:64
	v_add_u32_e32 v142, 0x20000, v142
	global_load_dwordx4 v[158:161], v141, s[10:11] offset:64
	v_add_u32_e32 v141, 0x20000, v141
	s_waitcnt vmcnt(6)
	v_pk_fma_f32 v[162:163], v[80:81], v[166:167], v[162:163]
	v_pk_fma_f32 v[164:165], v[82:83], v[168:169], v[164:165]
	global_store_dwordx4 v142, v[162:165], s[12:13] offset:64
	v_add_u32_e32 v142, 0xa0000, v142
	global_load_dwordx4 v[162:165], v141, s[10:11] offset:64
	v_add_u32_e32 v141, 0x20000, v141
	s_waitcnt vmcnt(6)
	v_pk_fma_f32 v[150:151], v[76:77], v[166:167], v[150:151]
	v_pk_fma_f32 v[152:153], v[78:79], v[168:169], v[152:153]
	global_store_dwordx4 v142, v[150:153], s[12:13] offset:64
	v_add_u32_e32 v142, 0x20000, v142
	s_waitcnt vmcnt(5)
	v_pk_fma_f32 v[154:155], v[72:73], v[166:167], v[154:155]
	v_pk_fma_f32 v[156:157], v[74:75], v[168:169], v[156:157]
	global_store_dwordx4 v142, v[154:157], s[12:13] offset:64
	v_add_u32_e32 v142, 0x20000, v142
	s_waitcnt vmcnt(4)
	v_pk_fma_f32 v[158:159], v[64:65], v[166:167], v[158:159]
	v_pk_fma_f32 v[160:161], v[66:67], v[168:169], v[160:161]
	global_store_dwordx4 v142, v[158:161], s[12:13] offset:64
	v_add_u32_e32 v142, 0x20000, v142
	s_waitcnt vmcnt(3)
	v_pk_fma_f32 v[162:163], v[56:57], v[166:167], v[162:163]
	v_pk_fma_f32 v[164:165], v[58:59], v[168:169], v[164:165]
	global_store_dwordx4 v142, v[162:165], s[12:13] offset:64
	v_add_u32_e32 v142, 0x20000, v142
	v_mov_b32_e32 v141, v143
	v_mov_b32_e32 v142, v143
	global_load_dwordx4 v[166:169], v140, s[14:15] offset:512
	global_load_dwordx4 v[150:153], v141, s[10:11] offset:512
	v_add_u32_e32 v141, 0x20000, v141
	global_load_dwordx4 v[154:157], v141, s[10:11] offset:512
	v_add_u32_e32 v141, 0x20000, v141
	global_load_dwordx4 v[158:161], v141, s[10:11] offset:512
	v_add_u32_e32 v141, 0x20000, v141
	global_load_dwordx4 v[162:165], v141, s[10:11] offset:512
	v_add_u32_e32 v141, 0xa0000, v141
	s_waitcnt vmcnt(3)
	v_pk_fma_f32 v[150:151], v[68:69], v[166:167], v[150:151]
	v_pk_fma_f32 v[152:153], v[70:71], v[168:169], v[152:153]
	global_store_dwordx4 v142, v[150:153], s[12:13] offset:512
	v_add_u32_e32 v142, 0x20000, v142
	global_load_dwordx4 v[150:153], v141, s[10:11] offset:512
	v_add_u32_e32 v141, 0x20000, v141
	s_waitcnt vmcnt(4)
	v_pk_fma_f32 v[154:155], v[60:61], v[166:167], v[154:155]
	v_pk_fma_f32 v[156:157], v[62:63], v[168:169], v[156:157]
	global_store_dwordx4 v142, v[154:157], s[12:13] offset:512
	v_add_u32_e32 v142, 0x20000, v142
	global_load_dwordx4 v[154:157], v141, s[10:11] offset:512
	v_add_u32_e32 v141, 0x20000, v141
	s_waitcnt vmcnt(5)
	v_pk_fma_f32 v[158:159], v[52:53], v[166:167], v[158:159]
	v_pk_fma_f32 v[160:161], v[54:55], v[168:169], v[160:161]
	global_store_dwordx4 v142, v[158:161], s[12:13] offset:512
	v_add_u32_e32 v142, 0x20000, v142
	global_load_dwordx4 v[158:161], v141, s[10:11] offset:512
	v_add_u32_e32 v141, 0x20000, v141
	s_waitcnt vmcnt(6)
	v_pk_fma_f32 v[162:163], v[48:49], v[166:167], v[162:163]
	v_pk_fma_f32 v[164:165], v[50:51], v[168:169], v[164:165]
	global_store_dwordx4 v142, v[162:165], s[12:13] offset:512
	v_add_u32_e32 v142, 0xa0000, v142
	global_load_dwordx4 v[162:165], v141, s[10:11] offset:512
	v_add_u32_e32 v141, 0x20000, v141
	s_waitcnt vmcnt(6)
	v_pk_fma_f32 v[150:151], v[44:45], v[166:167], v[150:151]
	v_pk_fma_f32 v[152:153], v[46:47], v[168:169], v[152:153]
	global_store_dwordx4 v142, v[150:153], s[12:13] offset:512
	v_add_u32_e32 v142, 0x20000, v142
	s_waitcnt vmcnt(5)
	v_pk_fma_f32 v[154:155], v[36:37], v[166:167], v[154:155]
	v_pk_fma_f32 v[156:157], v[38:39], v[168:169], v[156:157]
	global_store_dwordx4 v142, v[154:157], s[12:13] offset:512
	v_add_u32_e32 v142, 0x20000, v142
	s_waitcnt vmcnt(4)
	v_pk_fma_f32 v[158:159], v[28:29], v[166:167], v[158:159]
	v_pk_fma_f32 v[160:161], v[30:31], v[168:169], v[160:161]
	global_store_dwordx4 v142, v[158:161], s[12:13] offset:512
	v_add_u32_e32 v142, 0x20000, v142
	s_waitcnt vmcnt(3)
	v_pk_fma_f32 v[162:163], v[20:21], v[166:167], v[162:163]
	v_pk_fma_f32 v[164:165], v[22:23], v[168:169], v[164:165]
	global_store_dwordx4 v142, v[162:165], s[12:13] offset:512
	v_add_u32_e32 v142, 0x20000, v142
	v_mov_b32_e32 v141, v143
	v_mov_b32_e32 v142, v143
	global_load_dwordx4 v[166:169], v140, s[14:15] offset:576
	global_load_dwordx4 v[150:153], v141, s[10:11] offset:576
	v_add_u32_e32 v141, 0x20000, v141
	global_load_dwordx4 v[154:157], v141, s[10:11] offset:576
	v_add_u32_e32 v141, 0x20000, v141
	global_load_dwordx4 v[158:161], v141, s[10:11] offset:576
	v_add_u32_e32 v141, 0x20000, v141
	global_load_dwordx4 v[162:165], v141, s[10:11] offset:576
	v_add_u32_e32 v141, 0xa0000, v141
	s_waitcnt vmcnt(3)
	v_pk_fma_f32 v[150:151], v[40:41], v[166:167], v[150:151]
	v_pk_fma_f32 v[152:153], v[42:43], v[168:169], v[152:153]
	global_store_dwordx4 v142, v[150:153], s[12:13] offset:576
	v_add_u32_e32 v142, 0x20000, v142
	global_load_dwordx4 v[150:153], v141, s[10:11] offset:576
	v_add_u32_e32 v141, 0x20000, v141
	s_waitcnt vmcnt(4)
	v_pk_fma_f32 v[154:155], v[32:33], v[166:167], v[154:155]
	v_pk_fma_f32 v[156:157], v[34:35], v[168:169], v[156:157]
	global_store_dwordx4 v142, v[154:157], s[12:13] offset:576
	v_add_u32_e32 v142, 0x20000, v142
	global_load_dwordx4 v[154:157], v141, s[10:11] offset:576
	v_add_u32_e32 v141, 0x20000, v141
	s_waitcnt vmcnt(5)
	v_pk_fma_f32 v[158:159], v[24:25], v[166:167], v[158:159]
	v_pk_fma_f32 v[160:161], v[26:27], v[168:169], v[160:161]
	global_store_dwordx4 v142, v[158:161], s[12:13] offset:576
	v_add_u32_e32 v142, 0x20000, v142
	global_load_dwordx4 v[158:161], v141, s[10:11] offset:576
	v_add_u32_e32 v141, 0x20000, v141
	s_waitcnt vmcnt(6)
	v_pk_fma_f32 v[162:163], v[16:17], v[166:167], v[162:163]
	v_pk_fma_f32 v[164:165], v[18:19], v[168:169], v[164:165]
	global_store_dwordx4 v142, v[162:165], s[12:13] offset:576
	v_add_u32_e32 v142, 0xa0000, v142
	global_load_dwordx4 v[162:165], v141, s[10:11] offset:576
	v_add_u32_e32 v141, 0x20000, v141
	s_waitcnt vmcnt(6)
	v_pk_fma_f32 v[150:151], v[12:13], v[166:167], v[150:151]
	v_pk_fma_f32 v[152:153], v[14:15], v[168:169], v[152:153]
	global_store_dwordx4 v142, v[150:153], s[12:13] offset:576
	v_add_u32_e32 v142, 0x20000, v142
	s_waitcnt vmcnt(5)
	v_pk_fma_f32 v[154:155], v[8:9], v[166:167], v[154:155]
	v_pk_fma_f32 v[156:157], v[10:11], v[168:169], v[156:157]
	global_store_dwordx4 v142, v[154:157], s[12:13] offset:576
	v_add_u32_e32 v142, 0x20000, v142
	s_waitcnt vmcnt(4)
	v_pk_fma_f32 v[158:159], v[4:5], v[166:167], v[158:159]
	v_pk_fma_f32 v[160:161], v[6:7], v[168:169], v[160:161]
	global_store_dwordx4 v142, v[158:161], s[12:13] offset:576
	v_add_u32_e32 v142, 0x20000, v142
	s_waitcnt vmcnt(3)
	v_pk_fma_f32 v[162:163], v[0:1], v[166:167], v[162:163]
	v_pk_fma_f32 v[164:165], v[2:3], v[168:169], v[164:165]
	global_store_dwordx4 v142, v[162:165], s[12:13] offset:576
	v_add_u32_e32 v142, 0x20000, v142
	s_and_b64 vcc, exec, s[6:7]
	s_cbranch_vccz .LBB0_843
	s_waitcnt vmcnt(0)
	s_cmpk_gt_u32 s20, 0xff
	s_cbranch_scc1 .LBB0_854
	s_barrier

.LBB0_985:
	s_ashr_i32 s13, s12, 31
	v_cmp_lt_i64_e32 vcc, s[0:1], v[142:143]
	s_lshl_b64 s[0:1], s[12:13], 20
	s_add_u32 s14, s38, s0
	s_addc_u32 s15, s39, s1
	s_and_b64 s[0:1], vcc, exec
	s_cselect_b32 s0, s15, s37
	s_cselect_b32 s1, s14, s36
	s_ashr_i32 s11, s10, 31
	s_lshl_b64 s[4:5], s[10:11], 20
	s_add_u32 s16, s62, s4
	s_addc_u32 s17, s63, s5
	s_and_b64 s[4:5], vcc, exec
	s_cselect_b32 s11, s17, s51
	s_cselect_b32 s13, s16, s50
	s_add_u32 s60, s36, 0x80080
	s_addc_u32 s61, s37, 0
	s_add_u32 s36, s50, 0x100
	v_mov_b32_e32 v0, 0
	s_addc_u32 s37, s51, 0
	s_mov_b32 s64, -2
	v_mov_b32_e32 v1, v0
	v_mov_b32_e32 v2, v0
	v_mov_b32_e32 v3, v0
	v_mov_b32_e32 v4, v0
	v_mov_b32_e32 v5, v0
	v_mov_b32_e32 v6, v0
	v_mov_b32_e32 v7, v0
	v_mov_b32_e32 v16, v0
	v_mov_b32_e32 v17, v0
	v_mov_b32_e32 v18, v0
	v_mov_b32_e32 v19, v0
	v_mov_b32_e32 v20, v0
	v_mov_b32_e32 v21, v0
	v_mov_b32_e32 v22, v0
	v_mov_b32_e32 v23, v0
	v_mov_b32_e32 v32, v0
	v_mov_b32_e32 v33, v0
	v_mov_b32_e32 v34, v0
	v_mov_b32_e32 v35, v0
	v_mov_b32_e32 v36, v0
	v_mov_b32_e32 v37, v0
	v_mov_b32_e32 v38, v0
	v_mov_b32_e32 v39, v0
	v_mov_b32_e32 v48, v0
	v_mov_b32_e32 v49, v0
	v_mov_b32_e32 v50, v0
	v_mov_b32_e32 v51, v0
	v_mov_b32_e32 v52, v0
	v_mov_b32_e32 v53, v0
	v_mov_b32_e32 v54, v0
	v_mov_b32_e32 v55, v0
	v_mov_b32_e32 v8, v0
	v_mov_b32_e32 v9, v0
	v_mov_b32_e32 v10, v0
	v_mov_b32_e32 v11, v0
	v_mov_b32_e32 v12, v0
	v_mov_b32_e32 v13, v0
	v_mov_b32_e32 v14, v0
	v_mov_b32_e32 v15, v0
	v_mov_b32_e32 v24, v0
	v_mov_b32_e32 v25, v0
	v_mov_b32_e32 v26, v0
	v_mov_b32_e32 v27, v0
	v_mov_b32_e32 v28, v0
	v_mov_b32_e32 v29, v0
	v_mov_b32_e32 v30, v0
	v_mov_b32_e32 v31, v0
	v_mov_b32_e32 v40, v0
	v_mov_b32_e32 v41, v0
	v_mov_b32_e32 v42, v0
	v_mov_b32_e32 v43, v0
	v_mov_b32_e32 v44, v0
	v_mov_b32_e32 v45, v0
	v_mov_b32_e32 v46, v0
	v_mov_b32_e32 v47, v0
	v_mov_b32_e32 v56, v0
	v_mov_b32_e32 v57, v0
	v_mov_b32_e32 v58, v0
	v_mov_b32_e32 v59, v0
	v_mov_b32_e32 v60, v0
	v_mov_b32_e32 v61, v0
	v_mov_b32_e32 v62, v0
	v_mov_b32_e32 v63, v0
	v_mov_b32_e32 v64, v0
	v_mov_b32_e32 v65, v0
	v_mov_b32_e32 v66, v0
	v_mov_b32_e32 v67, v0
	v_mov_b32_e32 v68, v0
	v_mov_b32_e32 v69, v0
	v_mov_b32_e32 v70, v0
	v_mov_b32_e32 v71, v0
	v_mov_b32_e32 v80, v0
	v_mov_b32_e32 v81, v0
	v_mov_b32_e32 v82, v0
	v_mov_b32_e32 v83, v0
	v_mov_b32_e32 v84, v0
	v_mov_b32_e32 v85, v0
	v_mov_b32_e32 v86, v0
	v_mov_b32_e32 v87, v0
	v_mov_b32_e32 v96, v0
	v_mov_b32_e32 v97, v0
	v_mov_b32_e32 v98, v0
	v_mov_b32_e32 v99, v0
	v_mov_b32_e32 v100, v0
	v_mov_b32_e32 v101, v0
	v_mov_b32_e32 v102, v0
	v_mov_b32_e32 v103, v0
	v_mov_b32_e32 v112, v0
	v_mov_b32_e32 v113, v0
	v_mov_b32_e32 v114, v0
	v_mov_b32_e32 v115, v0
	v_mov_b32_e32 v116, v0
	v_mov_b32_e32 v117, v0
	v_mov_b32_e32 v118, v0
	v_mov_b32_e32 v119, v0
	v_mov_b32_e32 v72, v0
	v_mov_b32_e32 v73, v0
	v_mov_b32_e32 v74, v0
	v_mov_b32_e32 v75, v0
	v_mov_b32_e32 v76, v0
	v_mov_b32_e32 v77, v0
	v_mov_b32_e32 v78, v0
	v_mov_b32_e32 v79, v0
	v_mov_b32_e32 v88, v0
	v_mov_b32_e32 v89, v0
	v_mov_b32_e32 v90, v0
	v_mov_b32_e32 v91, v0
	v_mov_b32_e32 v92, v0
	v_mov_b32_e32 v93, v0
	v_mov_b32_e32 v94, v0
	v_mov_b32_e32 v95, v0
	v_mov_b32_e32 v104, v0
	v_mov_b32_e32 v105, v0
	v_mov_b32_e32 v106, v0
	v_mov_b32_e32 v107, v0
	v_mov_b32_e32 v108, v0
	v_mov_b32_e32 v109, v0
	v_mov_b32_e32 v110, v0
	v_mov_b32_e32 v111, v0
	v_mov_b32_e32 v120, v0
	v_mov_b32_e32 v121, v0
	v_mov_b32_e32 v122, v0
	v_mov_b32_e32 v123, v0
	v_mov_b32_e32 v124, v0
	v_mov_b32_e32 v125, v0
	v_mov_b32_e32 v126, v0
	v_mov_b32_e32 v127, v0
	ds_read_b128 v[152:155], v148
	ds_read_b128 v[156:159], v148 offset:1024
	ds_read_b128 v[160:163], v148 offset:2048
	ds_read_b128 v[164:167], v148 offset:3072
	.p2alignl 6, 3212836864
.LBB0_986:
	s_add_u32 s4, s60, 0xfff80080
	s_addc_u32 s5, s61, -1
	s_cmp_eq_u32 s64, 28
	s_cselect_b32 s5, s0, s5
	s_cselect_b32 s4, s1, s4
	s_cselect_b32 s51, s11, s37
	s_cselect_b32 s50, s13, s36
	s_add_i32 m0, s19, 0xc000
	ds_read_b128 v[168:171], v149
	ds_read_b128 v[172:175], v149 offset:1024
	ds_read_b128 v[176:179], v149 offset:2048
	ds_read_b128 v[180:183], v149 offset:3072
	ds_read_b128 v[184:187], v149 offset:4096
	ds_read_b128 v[188:191], v149 offset:5120
	ds_read_b128 v[192:195], v149 offset:6144
	ds_read_b128 v[196:199], v149 offset:7168
	global_load_lds_dwordx4 v138, s[60:61]
	s_add_i32 m0, s19, 0xe000
	s_nop 0
	global_load_lds_dwordx4 v140, s[60:61]
	s_waitcnt lgkmcnt(8)
	s_barrier
	s_waitcnt lgkmcnt(0)
	s_waitcnt lgkmcnt(0)
	v_mfma_f32_16x16x32_bf16 v[124:127], v[152:155], v[168:171], v[124:127]
	v_mfma_f32_16x16x32_bf16 v[120:123], v[160:163], v[168:171], v[120:123]
	v_mfma_f32_16x16x32_bf16 v[108:111], v[152:155], v[176:179], v[108:111]
	v_mfma_f32_16x16x32_bf16 v[104:107], v[160:163], v[176:179], v[104:107]
	v_mfma_f32_16x16x32_bf16 v[92:95], v[152:155], v[184:187], v[92:95]
	v_mfma_f32_16x16x32_bf16 v[88:91], v[160:163], v[184:187], v[88:91]
	v_mfma_f32_16x16x32_bf16 v[76:79], v[152:155], v[192:195], v[76:79]
	v_mfma_f32_16x16x32_bf16 v[72:75], v[160:163], v[192:195], v[72:75]
	v_mfma_f32_16x16x32_bf16 v[124:127], v[156:159], v[172:175], v[124:127]
	v_mfma_f32_16x16x32_bf16 v[120:123], v[164:167], v[172:175], v[120:123]
	v_mfma_f32_16x16x32_bf16 v[108:111], v[156:159], v[180:183], v[108:111]
	v_mfma_f32_16x16x32_bf16 v[104:107], v[164:167], v[180:183], v[104:107]
	v_mfma_f32_16x16x32_bf16 v[92:95], v[156:159], v[188:191], v[92:95]
	v_mfma_f32_16x16x32_bf16 v[88:91], v[164:167], v[188:191], v[88:91]
	v_mfma_f32_16x16x32_bf16 v[76:79], v[156:159], v[196:199], v[76:79]
	v_mfma_f32_16x16x32_bf16 v[72:75], v[164:167], v[196:199], v[72:75]
	s_barrier
	s_add_i32 s42, s41, s21
	s_add_u32 s98, s50, s8
	s_addc_u32 s99, s51, s9
	s_mov_b32 m0, s42
	ds_read_b128 v[200:203], v150
	ds_read_b128 v[204:207], v150 offset:1024
	ds_read_b128 v[208:211], v150 offset:2048
	ds_read_b128 v[212:215], v150 offset:3072
	global_load_lds_dwordx4 v134, s[50:51]
	s_add_i32 m0, s42, 0x2000
	s_nop 0
	global_load_lds_dwordx4 v130, s[50:51]
	s_barrier
	s_waitcnt lgkmcnt(0)
	s_waitcnt lgkmcnt(0)
	v_mfma_f32_16x16x32_bf16 v[116:119], v[200:203], v[168:171], v[116:119]
	v_mfma_f32_16x16x32_bf16 v[112:115], v[208:211], v[168:171], v[112:115]
	v_mfma_f32_16x16x32_bf16 v[100:103], v[200:203], v[176:179], v[100:103]
	v_mfma_f32_16x16x32_bf16 v[96:99], v[208:211], v[176:179], v[96:99]
	v_mfma_f32_16x16x32_bf16 v[84:87], v[200:203], v[184:187], v[84:87]
	v_mfma_f32_16x16x32_bf16 v[80:83], v[208:211], v[184:187], v[80:83]
	v_mfma_f32_16x16x32_bf16 v[68:71], v[200:203], v[192:195], v[68:71]
	v_mfma_f32_16x16x32_bf16 v[64:67], v[208:211], v[192:195], v[64:67]
	v_mfma_f32_16x16x32_bf16 v[116:119], v[204:207], v[172:175], v[116:119]
	v_mfma_f32_16x16x32_bf16 v[112:115], v[212:215], v[172:175], v[112:115]
	v_mfma_f32_16x16x32_bf16 v[100:103], v[204:207], v[180:183], v[100:103]
	v_mfma_f32_16x16x32_bf16 v[96:99], v[212:215], v[180:183], v[96:99]
	v_mfma_f32_16x16x32_bf16 v[84:87], v[204:207], v[188:191], v[84:87]
	v_mfma_f32_16x16x32_bf16 v[80:83], v[212:215], v[188:191], v[80:83]
	v_mfma_f32_16x16x32_bf16 v[68:71], v[204:207], v[196:199], v[68:71]
	v_mfma_f32_16x16x32_bf16 v[64:67], v[212:215], v[196:199], v[64:67]
	s_mov_b32 m0, s19
	s_add_u32 s100, s4, s8
	s_addc_u32 s101, s5, s9
	s_barrier
	s_waitcnt vmcnt(8)
	ds_read_b128 v[168:171], v149 offset:16384
	ds_read_b128 v[172:175], v149 offset:17408
	ds_read_b128 v[176:179], v149 offset:18432
	ds_read_b128 v[180:183], v149 offset:19456
	ds_read_b128 v[184:187], v149 offset:20480
	ds_read_b128 v[188:191], v149 offset:21504
	ds_read_b128 v[192:195], v149 offset:22528
	ds_read_b128 v[196:199], v149 offset:23552
	global_load_lds_dwordx4 v136, s[4:5]
	s_mov_b32 m0, s24
	s_nop 0
	global_load_lds_dwordx4 v132, s[4:5]
	s_barrier
	s_waitcnt lgkmcnt(0)
	s_waitcnt lgkmcnt(0)
	v_mfma_f32_16x16x32_bf16 v[60:63], v[152:155], v[168:171], v[60:63]
	v_mfma_f32_16x16x32_bf16 v[56:59], v[160:163], v[168:171], v[56:59]
	v_mfma_f32_16x16x32_bf16 v[44:47], v[152:155], v[176:179], v[44:47]
	v_mfma_f32_16x16x32_bf16 v[40:43], v[160:163], v[176:179], v[40:43]
	v_mfma_f32_16x16x32_bf16 v[28:31], v[152:155], v[184:187], v[28:31]
	v_mfma_f32_16x16x32_bf16 v[24:27], v[160:163], v[184:187], v[24:27]
	v_mfma_f32_16x16x32_bf16 v[12:15], v[152:155], v[192:195], v[12:15]
	v_mfma_f32_16x16x32_bf16 v[8:11], v[160:163], v[192:195], v[8:11]
	v_mfma_f32_16x16x32_bf16 v[60:63], v[156:159], v[172:175], v[60:63]
	v_mfma_f32_16x16x32_bf16 v[56:59], v[164:167], v[172:175], v[56:59]
	v_mfma_f32_16x16x32_bf16 v[44:47], v[156:159], v[180:183], v[44:47]
	v_mfma_f32_16x16x32_bf16 v[40:43], v[164:167], v[180:183], v[40:43]
	v_mfma_f32_16x16x32_bf16 v[28:31], v[156:159], v[188:191], v[28:31]
	v_mfma_f32_16x16x32_bf16 v[24:27], v[164:167], v[188:191], v[24:27]
	v_mfma_f32_16x16x32_bf16 v[12:15], v[156:159], v[196:199], v[12:15]
	v_mfma_f32_16x16x32_bf16 v[8:11], v[164:167], v[196:199], v[8:11]
	s_barrier
	s_add_u32 s42, s50, 0x80000
	s_addc_u32 s43, s51, 0
	s_add_i32 s44, s46, s21
	s_mov_b32 m0, s44
	s_nop 0
	global_load_lds_dwordx4 v134, s[42:43]
	s_add_i32 m0, s44, 0x2000
	s_nop 0
	global_load_lds_dwordx4 v130, s[42:43]
	v_add_u32_e32 v151, 0x18000, v146
	ds_read_b128 v[152:155], v151
	ds_read_b128 v[156:159], v151 offset:1024
	ds_read_b128 v[160:163], v151 offset:2048
	ds_read_b128 v[164:167], v151 offset:3072
	s_waitcnt vmcnt(6)
	s_barrier
	v_mfma_f32_16x16x32_bf16 v[52:55], v[200:203], v[168:171], v[52:55]
	v_mfma_f32_16x16x32_bf16 v[48:51], v[208:211], v[168:171], v[48:51]
	v_mfma_f32_16x16x32_bf16 v[36:39], v[200:203], v[176:179], v[36:39]
	v_mfma_f32_16x16x32_bf16 v[32:35], v[208:211], v[176:179], v[32:35]
	v_mfma_f32_16x16x32_bf16 v[20:23], v[200:203], v[184:187], v[20:23]
	v_mfma_f32_16x16x32_bf16 v[16:19], v[208:211], v[184:187], v[16:19]
	v_mfma_f32_16x16x32_bf16 v[4:7], v[200:203], v[192:195], v[4:7]
	v_mfma_f32_16x16x32_bf16 v[0:3], v[208:211], v[192:195], v[0:3]
	v_mfma_f32_16x16x32_bf16 v[52:55], v[204:207], v[172:175], v[52:55]
	v_mfma_f32_16x16x32_bf16 v[48:51], v[212:215], v[172:175], v[48:51]
	v_mfma_f32_16x16x32_bf16 v[36:39], v[204:207], v[180:183], v[36:39]
	v_mfma_f32_16x16x32_bf16 v[32:35], v[212:215], v[180:183], v[32:35]
	v_mfma_f32_16x16x32_bf16 v[20:23], v[204:207], v[188:191], v[20:23]
	v_mfma_f32_16x16x32_bf16 v[16:19], v[212:215], v[188:191], v[16:19]
	v_mfma_f32_16x16x32_bf16 v[4:7], v[204:207], v[196:199], v[4:7]
	v_mfma_f32_16x16x32_bf16 v[0:3], v[212:215], v[196:199], v[0:3]
	s_add_i32 s42, 0, 0x18000
	s_barrier
	s_add_u32 s4, s4, 0x80000
	s_addc_u32 s5, s5, 0
	s_mov_b32 m0, s25
	ds_read_b128 v[168:171], v149 offset:32768
	ds_read_b128 v[172:175], v149 offset:33792
	ds_read_b128 v[176:179], v149 offset:34816
	ds_read_b128 v[180:183], v149 offset:35840
	ds_read_b128 v[184:187], v149 offset:36864
	ds_read_b128 v[188:191], v149 offset:37888
	ds_read_b128 v[192:195], v149 offset:38912
	ds_read_b128 v[196:199], v149 offset:39936
	global_load_lds_dwordx4 v136, s[4:5]
	s_mov_b32 m0, s28
	s_nop 0
	global_load_lds_dwordx4 v132, s[4:5]
	s_waitcnt lgkmcnt(8)
	s_barrier
	s_waitcnt lgkmcnt(0)
	s_waitcnt lgkmcnt(0)
	v_mfma_f32_16x16x32_bf16 v[124:127], v[152:155], v[168:171], v[124:127]
	v_mfma_f32_16x16x32_bf16 v[120:123], v[160:163], v[168:171], v[120:123]
	v_mfma_f32_16x16x32_bf16 v[108:111], v[152:155], v[176:179], v[108:111]
	v_mfma_f32_16x16x32_bf16 v[104:107], v[160:163], v[176:179], v[104:107]
	v_mfma_f32_16x16x32_bf16 v[92:95], v[152:155], v[184:187], v[92:95]
	v_mfma_f32_16x16x32_bf16 v[88:91], v[160:163], v[184:187], v[88:91]
	v_mfma_f32_16x16x32_bf16 v[76:79], v[152:155], v[192:195], v[76:79]
	v_mfma_f32_16x16x32_bf16 v[72:75], v[160:163], v[192:195], v[72:75]
	v_mfma_f32_16x16x32_bf16 v[124:127], v[156:159], v[172:175], v[124:127]
	v_mfma_f32_16x16x32_bf16 v[120:123], v[164:167], v[172:175], v[120:123]
	v_mfma_f32_16x16x32_bf16 v[108:111], v[156:159], v[180:183], v[108:111]
	v_mfma_f32_16x16x32_bf16 v[104:107], v[164:167], v[180:183], v[104:107]
	v_mfma_f32_16x16x32_bf16 v[92:95], v[156:159], v[188:191], v[92:95]
	v_mfma_f32_16x16x32_bf16 v[88:91], v[164:167], v[188:191], v[88:91]
	v_mfma_f32_16x16x32_bf16 v[76:79], v[156:159], v[196:199], v[76:79]
	v_mfma_f32_16x16x32_bf16 v[72:75], v[164:167], v[196:199], v[72:75]
	s_barrier
	s_add_i32 s43, 0, 0x1c000
	s_add_i32 s4, s42, s21
	v_add_u32_e32 v151, s43, v146
	s_mov_b32 m0, s4
	ds_read_b128 v[200:203], v151
	ds_read_b128 v[204:207], v151 offset:1024
	ds_read_b128 v[208:211], v151 offset:2048
	ds_read_b128 v[212:215], v151 offset:3072
	global_load_lds_dwordx4 v134, s[98:99]
	s_add_i32 m0, s4, 0x2000
	s_nop 0
	global_load_lds_dwordx4 v130, s[98:99]
	s_barrier
	s_waitcnt lgkmcnt(0)
	s_waitcnt lgkmcnt(0)
	v_mfma_f32_16x16x32_bf16 v[116:119], v[200:203], v[168:171], v[116:119]
	v_mfma_f32_16x16x32_bf16 v[112:115], v[208:211], v[168:171], v[112:115]
	v_mfma_f32_16x16x32_bf16 v[100:103], v[200:203], v[176:179], v[100:103]
	v_mfma_f32_16x16x32_bf16 v[96:99], v[208:211], v[176:179], v[96:99]
	v_mfma_f32_16x16x32_bf16 v[84:87], v[200:203], v[184:187], v[84:87]
	v_mfma_f32_16x16x32_bf16 v[80:83], v[208:211], v[184:187], v[80:83]
	v_mfma_f32_16x16x32_bf16 v[68:71], v[200:203], v[192:195], v[68:71]
	v_mfma_f32_16x16x32_bf16 v[64:67], v[208:211], v[192:195], v[64:67]
	v_mfma_f32_16x16x32_bf16 v[116:119], v[204:207], v[172:175], v[116:119]
	v_mfma_f32_16x16x32_bf16 v[112:115], v[212:215], v[172:175], v[112:115]
	v_mfma_f32_16x16x32_bf16 v[100:103], v[204:207], v[180:183], v[100:103]
	v_mfma_f32_16x16x32_bf16 v[96:99], v[212:215], v[180:183], v[96:99]
	v_mfma_f32_16x16x32_bf16 v[84:87], v[204:207], v[188:191], v[84:87]
	v_mfma_f32_16x16x32_bf16 v[80:83], v[212:215], v[188:191], v[80:83]
	v_mfma_f32_16x16x32_bf16 v[68:71], v[204:207], v[196:199], v[68:71]
	v_mfma_f32_16x16x32_bf16 v[64:67], v[212:215], v[196:199], v[64:67]
	s_mov_b32 m0, s33
	s_barrier
	s_waitcnt vmcnt(8)
	ds_read_b128 v[168:171], v149 offset:49152
	ds_read_b128 v[172:175], v149 offset:50176
	ds_read_b128 v[176:179], v149 offset:51200
	ds_read_b128 v[180:183], v149 offset:52224
	ds_read_b128 v[184:187], v149 offset:53248
	ds_read_b128 v[188:191], v149 offset:54272
	ds_read_b128 v[192:195], v149 offset:55296
	ds_read_b128 v[196:199], v149 offset:56320
	global_load_lds_dwordx4 v136, s[100:101]
	s_mov_b32 m0, s40
	s_nop 0
	global_load_lds_dwordx4 v132, s[100:101]
	s_barrier
	s_waitcnt lgkmcnt(0)
	s_waitcnt lgkmcnt(0)
	v_mfma_f32_16x16x32_bf16 v[60:63], v[152:155], v[168:171], v[60:63]
	v_mfma_f32_16x16x32_bf16 v[56:59], v[160:163], v[168:171], v[56:59]
	v_mfma_f32_16x16x32_bf16 v[44:47], v[152:155], v[176:179], v[44:47]
	v_mfma_f32_16x16x32_bf16 v[40:43], v[160:163], v[176:179], v[40:43]
	v_mfma_f32_16x16x32_bf16 v[28:31], v[152:155], v[184:187], v[28:31]
	v_mfma_f32_16x16x32_bf16 v[24:27], v[160:163], v[184:187], v[24:27]
	v_mfma_f32_16x16x32_bf16 v[12:15], v[152:155], v[192:195], v[12:15]
	v_mfma_f32_16x16x32_bf16 v[8:11], v[160:163], v[192:195], v[8:11]
	v_mfma_f32_16x16x32_bf16 v[60:63], v[156:159], v[172:175], v[60:63]
	v_mfma_f32_16x16x32_bf16 v[56:59], v[164:167], v[172:175], v[56:59]
	v_mfma_f32_16x16x32_bf16 v[44:47], v[156:159], v[180:183], v[44:47]
	v_mfma_f32_16x16x32_bf16 v[40:43], v[164:167], v[180:183], v[40:43]
	v_mfma_f32_16x16x32_bf16 v[28:31], v[156:159], v[188:191], v[28:31]
	v_mfma_f32_16x16x32_bf16 v[24:27], v[164:167], v[188:191], v[24:27]
	v_mfma_f32_16x16x32_bf16 v[12:15], v[156:159], v[196:199], v[12:15]
	v_mfma_f32_16x16x32_bf16 v[8:11], v[164:167], v[196:199], v[8:11]
	s_barrier
	s_add_u32 s4, s50, 0x80080
	s_addc_u32 s5, s51, 0
	s_add_i32 s42, s43, s21
	s_mov_b32 m0, s42
	s_nop 0
	global_load_lds_dwordx4 v134, s[4:5]
	s_add_i32 m0, s42, 0x2000
	s_nop 0
	global_load_lds_dwordx4 v130, s[4:5]
	ds_read_b128 v[152:155], v148
	ds_read_b128 v[156:159], v148 offset:1024
	ds_read_b128 v[160:163], v148 offset:2048
	ds_read_b128 v[164:167], v148 offset:3072
	s_waitcnt vmcnt(6)
	s_barrier
	v_mfma_f32_16x16x32_bf16 v[52:55], v[200:203], v[168:171], v[52:55]
	v_mfma_f32_16x16x32_bf16 v[48:51], v[208:211], v[168:171], v[48:51]
	v_mfma_f32_16x16x32_bf16 v[36:39], v[200:203], v[176:179], v[36:39]
	v_mfma_f32_16x16x32_bf16 v[32:35], v[208:211], v[176:179], v[32:35]
	v_mfma_f32_16x16x32_bf16 v[20:23], v[200:203], v[184:187], v[20:23]
	v_mfma_f32_16x16x32_bf16 v[16:19], v[208:211], v[184:187], v[16:19]
	v_mfma_f32_16x16x32_bf16 v[4:7], v[200:203], v[192:195], v[4:7]
	v_mfma_f32_16x16x32_bf16 v[0:3], v[208:211], v[192:195], v[0:3]
	v_mfma_f32_16x16x32_bf16 v[52:55], v[204:207], v[172:175], v[52:55]
	v_mfma_f32_16x16x32_bf16 v[48:51], v[212:215], v[172:175], v[48:51]
	v_mfma_f32_16x16x32_bf16 v[36:39], v[204:207], v[180:183], v[36:39]
	v_mfma_f32_16x16x32_bf16 v[32:35], v[212:215], v[180:183], v[32:35]
	v_mfma_f32_16x16x32_bf16 v[20:23], v[204:207], v[188:191], v[20:23]
	v_mfma_f32_16x16x32_bf16 v[16:19], v[212:215], v[188:191], v[16:19]
	v_mfma_f32_16x16x32_bf16 v[4:7], v[204:207], v[196:199], v[4:7]
	v_mfma_f32_16x16x32_bf16 v[0:3], v[212:215], v[196:199], v[0:3]
	s_add_i32 s64, s64, 2
	s_add_u32 s60, s60, 0x100
	s_addc_u32 s61, s61, 0
	s_add_u32 s36, s36, 0x100
	s_addc_u32 s37, s37, 0
	s_cmp_gt_u32 s64, 29
	s_barrier
	s_cbranch_scc0 .LBB0_986
	v_mul_f32_e32 v152, 0xbfb8aa3b, v124
	v_exp_f32_e32 v153, v152
	v_mul_f32_e32 v152, 0xbfb8aa3b, v120
	v_exp_f32_e32 v154, v152
	v_lshl_or_b32 v152, s53, 7, v147
	v_add_f32_e32 v153, 1.0, v153
	v_rcp_f32_e32 v155, v153
	v_add_f32_e32 v153, 1.0, v154
	v_rcp_f32_e32 v154, v153
	v_lshl_add_u32 v151, s18, 8, v129
	v_mul_f32_e32 v124, v124, v155
	v_mul_f32_e32 v116, v124, v116
	v_mul_f32_e32 v124, 0xbfb8aa3b, v125
	v_mul_f32_e32 v120, v120, v154
	v_exp_f32_e32 v124, v124
	v_mul_f32_e32 v154, 0xbfb8aa3b, v121
	v_exp_f32_e32 v154, v154
	v_mul_f32_e32 v112, v120, v112
	v_add_f32_e32 v120, 1.0, v124
	v_rcp_f32_e32 v120, v120
	v_add_f32_e32 v124, 1.0, v154
	v_mul_f32_e32 v154, 0xbfb8aa3b, v126
	v_rcp_f32_e32 v124, v124
	v_exp_f32_e32 v154, v154
	v_mul_f32_e32 v120, v125, v120
	v_mul_f32_e32 v117, v120, v117
	v_mul_f32_e32 v120, v121, v124
	v_add_f32_e32 v121, 1.0, v154
	v_rcp_f32_e32 v121, v121
	v_mul_f32_e32 v124, 0xbfb8aa3b, v122
	v_exp_f32_e32 v124, v124
	v_mul_f32_e32 v113, v120, v113
	v_mul_f32_e32 v120, v126, v121
	v_mul_f32_e32 v121, 0xbfb8aa3b, v127
	v_mul_f32_e32 v118, v120, v118
	v_add_f32_e32 v120, 1.0, v124
	v_exp_f32_e32 v121, v121
	v_mul_f32_e32 v124, 0xbfb8aa3b, v123
	v_rcp_f32_e32 v120, v120
	v_exp_f32_e32 v124, v124
	v_add_f32_e32 v121, 1.0, v121
	v_rcp_f32_e32 v121, v121
	v_mul_f32_e32 v120, v122, v120
	v_add_f32_e32 v122, 1.0, v124
	v_rcp_f32_e32 v122, v122
	v_mul_f32_e32 v114, v120, v114
	v_mul_f32_e32 v120, v127, v121
	v_mul_f32_e32 v119, v120, v119
	v_mul_f32_e32 v120, v123, v122
	v_mul_f32_e32 v122, 0xbfb8aa3b, v108
	v_exp_f32_e32 v122, v122
	v_mul_f32_e32 v123, 0xbfb8aa3b, v104
	v_exp_f32_e32 v123, v123
	v_ashrrev_i32_e32 v153, 31, v152
	v_add_f32_e32 v122, 1.0, v122
	v_rcp_f32_e32 v122, v122
	v_mul_f32_e32 v115, v120, v115
	s_nop 1
	v_cvt_pk_bf16_f32 v116, v116, v117
	s_nop 1
	v_cvt_pk_bf16_f32 v117, v118, v119
	s_nop 1
	v_cvt_pk_bf16_f32 v118, v112, v113
	v_mov_b64_e32 v[112:113], s[48:49]
	s_nop 1
	v_cvt_pk_bf16_f32 v119, v114, v115
	v_mad_i64_i32 v[120:121], s[0:1], v151, s47, v[112:113]
	v_lshlrev_b64 v[114:115], 1, v[152:153]
	v_add_f32_e32 v123, 1.0, v123
	v_mul_f32_e32 v108, v108, v122
	v_lshl_add_u64 v[120:121], v[120:121], 0, v[114:115]
	v_rcp_f32_e32 v123, v123
	v_mul_f32_e32 v100, v108, v100
	v_mul_f32_e32 v108, 0xbfb8aa3b, v109
	global_store_dwordx4 v[120:121], v[116:119], off
	v_exp_f32_e32 v108, v108
	v_mul_f32_e32 v104, v104, v123
	v_mul_f32_e32 v116, 0xbfb8aa3b, v105
	v_exp_f32_e32 v116, v116
	v_mul_f32_e32 v104, v104, v96
	v_add_f32_e32 v96, 1.0, v108
	v_rcp_f32_e32 v96, v96
	v_add_f32_e32 v108, 1.0, v116
	v_mul_f32_e32 v116, 0xbfb8aa3b, v110
	v_rcp_f32_e32 v108, v108
	v_exp_f32_e32 v116, v116
	v_mul_f32_e32 v96, v109, v96
	v_mul_f32_e32 v96, v96, v101
	v_mul_f32_e32 v101, v105, v108
	v_add_f32_e32 v105, 1.0, v116
	v_rcp_f32_e32 v105, v105
	v_mul_f32_e32 v108, 0xbfb8aa3b, v106
	v_exp_f32_e32 v108, v108
	v_mul_f32_e32 v101, v101, v97
	v_mul_f32_e32 v97, v110, v105
	v_mul_f32_e32 v105, 0xbfb8aa3b, v111
	v_mul_f32_e32 v97, v97, v102
	v_add_f32_e32 v102, 1.0, v108
	v_exp_f32_e32 v105, v105
	v_mul_f32_e32 v108, 0xbfb8aa3b, v107
	v_rcp_f32_e32 v102, v102
	v_exp_f32_e32 v108, v108
	v_add_f32_e32 v105, 1.0, v105
	v_rcp_f32_e32 v105, v105
	v_mul_f32_e32 v102, v106, v102
	v_add_f32_e32 v106, 1.0, v108
	v_rcp_f32_e32 v106, v106
	v_mul_f32_e32 v102, v102, v98
	v_mul_f32_e32 v98, v111, v105
	v_mul_f32_e32 v98, v98, v103
	v_mul_f32_e32 v103, v107, v106
	v_mul_f32_e32 v99, v103, v99
	s_nop 1
	v_cvt_pk_bf16_f32 v96, v100, v96
	s_nop 1
	v_cvt_pk_bf16_f32 v97, v97, v98
	s_nop 1
	v_cvt_pk_bf16_f32 v98, v104, v101
	s_nop 1
	v_cvt_pk_bf16_f32 v99, v102, v99
	v_mul_f32_e32 v102, 0xbfb8aa3b, v92
	v_exp_f32_e32 v102, v102
	v_mul_f32_e32 v103, 0xbfb8aa3b, v88
	v_exp_f32_e32 v103, v103
	v_or_b32_e32 v100, 16, v151
	v_add_f32_e32 v102, 1.0, v102
	v_rcp_f32_e32 v102, v102
	v_mad_i64_i32 v[100:101], s[0:1], v100, s47, v[112:113]
	v_add_f32_e32 v103, 1.0, v103
	v_mul_f32_e32 v92, v92, v102
	v_lshl_add_u64 v[100:101], v[100:101], 0, v[114:115]
	v_rcp_f32_e32 v103, v103
	v_mul_f32_e32 v84, v92, v84
	v_mul_f32_e32 v92, 0xbfb8aa3b, v93
	global_store_dwordx4 v[100:101], v[96:99], off
	v_exp_f32_e32 v92, v92
	v_mul_f32_e32 v88, v88, v103
	v_mul_f32_e32 v96, 0xbfb8aa3b, v89
	v_exp_f32_e32 v96, v96
	v_mul_f32_e32 v88, v88, v80
	v_add_f32_e32 v80, 1.0, v92
	v_rcp_f32_e32 v80, v80
	v_add_f32_e32 v92, 1.0, v96
	v_mul_f32_e32 v96, 0xbfb8aa3b, v94
	v_rcp_f32_e32 v92, v92
	v_exp_f32_e32 v96, v96
	v_mul_f32_e32 v80, v93, v80
	v_mul_f32_e32 v80, v80, v85
	v_mul_f32_e32 v85, v89, v92
	v_add_f32_e32 v89, 1.0, v96
	v_rcp_f32_e32 v89, v89
	v_mul_f32_e32 v92, 0xbfb8aa3b, v90
	v_exp_f32_e32 v92, v92
	v_mul_f32_e32 v85, v85, v81
	v_mul_f32_e32 v81, v94, v89
	v_mul_f32_e32 v89, 0xbfb8aa3b, v95
	v_mul_f32_e32 v81, v81, v86
	v_add_f32_e32 v86, 1.0, v92
	v_exp_f32_e32 v89, v89
	v_mul_f32_e32 v92, 0xbfb8aa3b, v91
	v_rcp_f32_e32 v86, v86
	v_exp_f32_e32 v92, v92
	v_add_f32_e32 v89, 1.0, v89
	v_rcp_f32_e32 v89, v89
	v_mul_f32_e32 v86, v90, v86
	v_add_f32_e32 v90, 1.0, v92
	v_rcp_f32_e32 v90, v90
	v_mul_f32_e32 v86, v86, v82
	v_mul_f32_e32 v82, v95, v89
	v_mul_f32_e32 v82, v82, v87
	v_mul_f32_e32 v87, v91, v90
	v_mul_f32_e32 v83, v87, v83
	s_nop 1
	v_cvt_pk_bf16_f32 v80, v84, v80
	s_nop 1
	v_cvt_pk_bf16_f32 v81, v81, v82
	s_nop 1
	v_cvt_pk_bf16_f32 v82, v88, v85
	s_nop 1
	v_cvt_pk_bf16_f32 v83, v86, v83
	v_mul_f32_e32 v86, 0xbfb8aa3b, v76
	v_exp_f32_e32 v86, v86
	v_mul_f32_e32 v87, 0xbfb8aa3b, v72
	v_exp_f32_e32 v87, v87
	v_or_b32_e32 v84, 32, v151
	v_add_f32_e32 v86, 1.0, v86
	v_rcp_f32_e32 v86, v86
	v_mad_i64_i32 v[84:85], s[0:1], v84, s47, v[112:113]
	v_add_f32_e32 v87, 1.0, v87
	v_mul_f32_e32 v76, v76, v86
	v_lshl_add_u64 v[84:85], v[84:85], 0, v[114:115]
	v_rcp_f32_e32 v87, v87
	v_mul_f32_e32 v68, v76, v68
	v_mul_f32_e32 v76, 0xbfb8aa3b, v77
	global_store_dwordx4 v[84:85], v[80:83], off
	v_exp_f32_e32 v76, v76
	v_mul_f32_e32 v72, v72, v87
	v_mul_f32_e32 v80, 0xbfb8aa3b, v73
	v_exp_f32_e32 v80, v80
	v_mul_f32_e32 v72, v72, v64
	v_add_f32_e32 v64, 1.0, v76
	v_rcp_f32_e32 v64, v64
	v_add_f32_e32 v76, 1.0, v80
	v_mul_f32_e32 v80, 0xbfb8aa3b, v78
	v_rcp_f32_e32 v76, v76
	v_exp_f32_e32 v80, v80
	v_mul_f32_e32 v64, v77, v64
	v_mul_f32_e32 v64, v64, v69
	v_mul_f32_e32 v69, v73, v76
	v_add_f32_e32 v73, 1.0, v80
	v_rcp_f32_e32 v73, v73
	v_mul_f32_e32 v76, 0xbfb8aa3b, v74
	v_exp_f32_e32 v76, v76
	v_mul_f32_e32 v69, v69, v65
	v_mul_f32_e32 v65, v78, v73
	v_mul_f32_e32 v73, 0xbfb8aa3b, v79
	v_mul_f32_e32 v65, v65, v70
	v_add_f32_e32 v70, 1.0, v76
	v_exp_f32_e32 v73, v73
	v_mul_f32_e32 v76, 0xbfb8aa3b, v75
	v_rcp_f32_e32 v70, v70
	v_exp_f32_e32 v76, v76
	v_add_f32_e32 v73, 1.0, v73
	v_rcp_f32_e32 v73, v73
	v_mul_f32_e32 v70, v74, v70
	v_add_f32_e32 v74, 1.0, v76
	v_rcp_f32_e32 v74, v74
	v_mul_f32_e32 v70, v70, v66
	v_mul_f32_e32 v66, v79, v73
	v_mul_f32_e32 v66, v66, v71
	v_mul_f32_e32 v71, v75, v74
	v_mul_f32_e32 v67, v71, v67
	s_nop 1
	v_cvt_pk_bf16_f32 v64, v68, v64
	s_nop 1
	v_cvt_pk_bf16_f32 v65, v65, v66
	s_nop 1
	v_cvt_pk_bf16_f32 v66, v72, v69
	s_nop 1
	v_cvt_pk_bf16_f32 v67, v70, v67
	v_mul_f32_e32 v70, 0xbfb8aa3b, v60
	v_exp_f32_e32 v70, v70
	v_or_b32_e32 v68, 48, v151
	v_mad_i64_i32 v[68:69], s[0:1], v68, s47, v[112:113]
	v_lshl_add_u64 v[68:69], v[68:69], 0, v[114:115]
	v_mul_f32_e32 v71, 0xbfb8aa3b, v56
	global_store_dwordx4 v[68:69], v[64:67], off
	v_exp_f32_e32 v71, v71
	s_and_b64 vcc, exec, s[6:7]
	v_add_f32_e32 v64, 1.0, v70
	v_rcp_f32_e32 v64, v64
	v_add_f32_e32 v65, 1.0, v71
	v_rcp_f32_e32 v65, v65
	v_add_u32_e32 v66, 0x80, v151
	v_mul_f32_e32 v60, v60, v64
	v_mul_f32_e32 v52, v60, v52
	v_mul_f32_e32 v60, 0xbfb8aa3b, v61
	v_exp_f32_e32 v60, v60
	v_mul_f32_e32 v64, 0xbfb8aa3b, v57
	v_exp_f32_e32 v64, v64
	v_mul_f32_e32 v56, v56, v65
	v_mul_f32_e32 v56, v56, v48
	v_add_f32_e32 v48, 1.0, v60
	v_rcp_f32_e32 v48, v48
	v_add_f32_e32 v60, 1.0, v64
	v_mul_f32_e32 v64, 0xbfb8aa3b, v62
	v_rcp_f32_e32 v60, v60
	v_exp_f32_e32 v64, v64
	v_mul_f32_e32 v48, v61, v48
	v_mul_f32_e32 v48, v48, v53
	v_mul_f32_e32 v53, v57, v60
	v_add_f32_e32 v57, 1.0, v64
	v_rcp_f32_e32 v57, v57
	v_mul_f32_e32 v60, 0xbfb8aa3b, v58
	v_exp_f32_e32 v60, v60
	v_mul_f32_e32 v53, v53, v49
	v_mul_f32_e32 v49, v62, v57
	v_mul_f32_e32 v57, 0xbfb8aa3b, v63
	v_mul_f32_e32 v49, v49, v54
	v_add_f32_e32 v54, 1.0, v60
	v_exp_f32_e32 v57, v57
	v_mul_f32_e32 v60, 0xbfb8aa3b, v59
	v_rcp_f32_e32 v54, v54
	v_exp_f32_e32 v60, v60
	v_add_f32_e32 v57, 1.0, v57
	v_rcp_f32_e32 v57, v57
	v_mul_f32_e32 v54, v58, v54
	v_add_f32_e32 v58, 1.0, v60
	v_rcp_f32_e32 v58, v58
	v_mul_f32_e32 v54, v54, v50
	v_mul_f32_e32 v50, v63, v57
	v_mul_f32_e32 v50, v50, v55
	v_mul_f32_e32 v55, v59, v58
	v_mul_f32_e32 v51, v55, v51
	s_nop 1
	v_cvt_pk_bf16_f32 v48, v52, v48
	s_nop 1
	v_cvt_pk_bf16_f32 v49, v49, v50
	s_nop 1
	v_cvt_pk_bf16_f32 v50, v56, v53
	s_nop 1
	v_cvt_pk_bf16_f32 v51, v54, v51
	v_mul_f32_e32 v54, 0xbfb8aa3b, v44
	v_exp_f32_e32 v54, v54
	v_mul_f32_e32 v55, 0xbfb8aa3b, v40
	v_exp_f32_e32 v55, v55
	v_mad_i64_i32 v[52:53], s[0:1], v66, s47, v[112:113]
	v_add_f32_e32 v54, 1.0, v54
	v_rcp_f32_e32 v54, v54
	v_add_f32_e32 v55, 1.0, v55
	v_lshl_add_u64 v[52:53], v[52:53], 0, v[114:115]
	v_rcp_f32_e32 v55, v55
	v_mul_f32_e32 v44, v44, v54
	v_mul_f32_e32 v36, v44, v36
	v_mul_f32_e32 v44, 0xbfb8aa3b, v45
	global_store_dwordx4 v[52:53], v[48:51], off
	v_exp_f32_e32 v44, v44
	v_mul_f32_e32 v40, v40, v55
	v_mul_f32_e32 v48, 0xbfb8aa3b, v41
	v_exp_f32_e32 v48, v48
	v_mul_f32_e32 v40, v40, v32
	v_add_f32_e32 v32, 1.0, v44
	v_rcp_f32_e32 v32, v32
	v_add_f32_e32 v44, 1.0, v48
	v_mul_f32_e32 v48, 0xbfb8aa3b, v46
	v_rcp_f32_e32 v44, v44
	v_exp_f32_e32 v48, v48
	v_mul_f32_e32 v32, v45, v32
	v_mul_f32_e32 v32, v32, v37
	v_mul_f32_e32 v37, v41, v44
	v_add_f32_e32 v41, 1.0, v48
	v_rcp_f32_e32 v41, v41
	v_mul_f32_e32 v44, 0xbfb8aa3b, v42
	v_exp_f32_e32 v44, v44
	v_mul_f32_e32 v37, v37, v33
	v_mul_f32_e32 v33, v46, v41
	v_mul_f32_e32 v41, 0xbfb8aa3b, v47
	v_mul_f32_e32 v33, v33, v38
	v_add_f32_e32 v38, 1.0, v44
	v_exp_f32_e32 v41, v41
	v_mul_f32_e32 v44, 0xbfb8aa3b, v43
	v_rcp_f32_e32 v38, v38
	v_exp_f32_e32 v44, v44
	v_add_f32_e32 v41, 1.0, v41
	v_rcp_f32_e32 v41, v41
	v_mul_f32_e32 v38, v42, v38
	v_add_f32_e32 v42, 1.0, v44
	v_rcp_f32_e32 v42, v42
	v_mul_f32_e32 v38, v38, v34
	v_mul_f32_e32 v34, v47, v41
	v_mul_f32_e32 v34, v34, v39
	v_mul_f32_e32 v39, v43, v42
	v_mul_f32_e32 v35, v39, v35
	s_nop 1
	v_cvt_pk_bf16_f32 v32, v36, v32
	s_nop 1
	v_cvt_pk_bf16_f32 v33, v33, v34
	s_nop 1
	v_cvt_pk_bf16_f32 v34, v40, v37
	s_nop 1
	v_cvt_pk_bf16_f32 v35, v38, v35
	v_mul_f32_e32 v38, 0xbfb8aa3b, v28
	v_exp_f32_e32 v38, v38
	v_mul_f32_e32 v39, 0xbfb8aa3b, v24
	v_exp_f32_e32 v39, v39
	v_add_u32_e32 v36, 0x90, v151
	v_add_f32_e32 v38, 1.0, v38
	v_rcp_f32_e32 v38, v38
	v_mad_i64_i32 v[36:37], s[0:1], v36, s47, v[112:113]
	v_add_f32_e32 v39, 1.0, v39
	v_mul_f32_e32 v28, v28, v38
	v_lshl_add_u64 v[36:37], v[36:37], 0, v[114:115]
	v_rcp_f32_e32 v39, v39
	v_mul_f32_e32 v20, v28, v20
	v_mul_f32_e32 v28, 0xbfb8aa3b, v29
	global_store_dwordx4 v[36:37], v[32:35], off
	v_exp_f32_e32 v28, v28
	v_mul_f32_e32 v24, v24, v39
	v_mul_f32_e32 v32, 0xbfb8aa3b, v25
	v_exp_f32_e32 v32, v32
	v_mul_f32_e32 v24, v24, v16
	v_add_f32_e32 v16, 1.0, v28
	v_rcp_f32_e32 v16, v16
	v_add_f32_e32 v28, 1.0, v32
	v_mul_f32_e32 v32, 0xbfb8aa3b, v30
	v_rcp_f32_e32 v28, v28
	v_exp_f32_e32 v32, v32
	v_mul_f32_e32 v16, v29, v16
	v_mul_f32_e32 v16, v16, v21
	v_mul_f32_e32 v21, v25, v28
	v_add_f32_e32 v25, 1.0, v32
	v_rcp_f32_e32 v25, v25
	v_mul_f32_e32 v28, 0xbfb8aa3b, v26
	v_exp_f32_e32 v28, v28
	v_mul_f32_e32 v21, v21, v17
	v_mul_f32_e32 v17, v30, v25
	v_mul_f32_e32 v25, 0xbfb8aa3b, v31
	v_mul_f32_e32 v17, v17, v22
	v_add_f32_e32 v22, 1.0, v28
	v_exp_f32_e32 v25, v25
	v_mul_f32_e32 v28, 0xbfb8aa3b, v27
	v_rcp_f32_e32 v22, v22
	v_exp_f32_e32 v28, v28
	v_add_f32_e32 v25, 1.0, v25
	v_rcp_f32_e32 v25, v25
	v_mul_f32_e32 v22, v26, v22
	v_add_f32_e32 v26, 1.0, v28
	v_rcp_f32_e32 v26, v26
	v_mul_f32_e32 v22, v22, v18
	v_mul_f32_e32 v18, v31, v25
	v_mul_f32_e32 v18, v18, v23
	v_mul_f32_e32 v23, v27, v26
	v_mul_f32_e32 v19, v23, v19
	s_nop 1
	v_cvt_pk_bf16_f32 v16, v20, v16
	s_nop 1
	v_cvt_pk_bf16_f32 v17, v17, v18
	s_nop 1
	v_cvt_pk_bf16_f32 v18, v24, v21
	s_nop 1
	v_cvt_pk_bf16_f32 v19, v22, v19
	v_mul_f32_e32 v22, 0xbfb8aa3b, v12
	v_exp_f32_e32 v22, v22
	v_mul_f32_e32 v23, 0xbfb8aa3b, v8
	v_exp_f32_e32 v23, v23
	v_add_u32_e32 v20, 0xa0, v151
	v_add_f32_e32 v22, 1.0, v22
	v_rcp_f32_e32 v22, v22
	v_mad_i64_i32 v[20:21], s[0:1], v20, s47, v[112:113]
	v_add_f32_e32 v23, 1.0, v23
	v_mul_f32_e32 v12, v12, v22
	v_lshl_add_u64 v[20:21], v[20:21], 0, v[114:115]
	v_rcp_f32_e32 v23, v23
	v_mul_f32_e32 v4, v12, v4
	v_mul_f32_e32 v12, 0xbfb8aa3b, v13
	global_store_dwordx4 v[20:21], v[16:19], off
	v_exp_f32_e32 v12, v12
	v_mul_f32_e32 v8, v8, v23
	v_mul_f32_e32 v16, 0xbfb8aa3b, v9
	v_exp_f32_e32 v16, v16
	v_mul_f32_e32 v8, v8, v0
	v_add_f32_e32 v0, 1.0, v12
	v_rcp_f32_e32 v0, v0
	v_add_f32_e32 v12, 1.0, v16
	v_mul_f32_e32 v16, 0xbfb8aa3b, v14
	v_rcp_f32_e32 v12, v12
	v_exp_f32_e32 v16, v16
	v_mul_f32_e32 v0, v13, v0
	v_mul_f32_e32 v0, v0, v5
	v_mul_f32_e32 v5, v9, v12
	v_add_f32_e32 v9, 1.0, v16
	v_rcp_f32_e32 v9, v9
	v_mul_f32_e32 v12, 0xbfb8aa3b, v10
	v_exp_f32_e32 v12, v12
	v_mul_f32_e32 v5, v5, v1
	v_mul_f32_e32 v1, v14, v9
	v_mul_f32_e32 v9, 0xbfb8aa3b, v15
	v_exp_f32_e32 v9, v9
	v_mul_f32_e32 v1, v1, v6
	v_add_f32_e32 v6, 1.0, v12
	v_mul_f32_e32 v12, 0xbfb8aa3b, v11
	v_rcp_f32_e32 v6, v6
	v_exp_f32_e32 v12, v12
	v_add_f32_e32 v9, 1.0, v9
	v_rcp_f32_e32 v9, v9
	v_mul_f32_e32 v6, v10, v6
	v_add_f32_e32 v10, 1.0, v12
	v_rcp_f32_e32 v10, v10
	v_mul_f32_e32 v6, v6, v2
	v_mul_f32_e32 v2, v15, v9
	v_mul_f32_e32 v2, v2, v7
	s_nop 1
	v_cvt_pk_bf16_f32 v0, v4, v0
	v_add_u32_e32 v4, 0xb0, v151
	v_mul_f32_e32 v7, v11, v10
	s_nop 1
	v_cvt_pk_bf16_f32 v1, v1, v2
	s_nop 1
	v_cvt_pk_bf16_f32 v2, v8, v5
	v_mad_i64_i32 v[4:5], s[0:1], v4, s47, v[112:113]
	v_mul_f32_e32 v3, v7, v3
	v_lshl_add_u64 v[4:5], v[4:5], 0, v[114:115]
	s_mov_b32 s53, s10
	s_mov_b32 s18, s12
	s_mov_b64 s[50:51], s[16:17]
	s_mov_b64 s[36:37], s[14:15]
	s_nop 1
	v_cvt_pk_bf16_f32 v3, v6, v3
	global_store_dwordx4 v[4:5], v[0:3], off
	s_cbranch_vccz .LBB0_983
	s_waitcnt vmcnt(0)
	s_cmpk_gt_u32 s20, 0xff
	s_cbranch_scc1 .LBB0_990
	s_barrier

.LBB0_1097:
	s_add_u32 s0, s64, 0x100
	v_mov_b32_e32 v0, 0
	s_addc_u32 s1, s65, 0
	s_mov_b32 s76, -2
	v_mov_b32_e32 v1, v0
	v_mov_b32_e32 v2, v0
	v_mov_b32_e32 v3, v0
	v_mov_b32_e32 v16, v0
	v_mov_b32_e32 v17, v0
	v_mov_b32_e32 v18, v0
	v_mov_b32_e32 v19, v0
	v_mov_b32_e32 v4, v0
	v_mov_b32_e32 v5, v0
	v_mov_b32_e32 v6, v0
	v_mov_b32_e32 v7, v0
	v_mov_b32_e32 v20, v0
	v_mov_b32_e32 v21, v0
	v_mov_b32_e32 v22, v0
	v_mov_b32_e32 v23, v0
	v_mov_b32_e32 v8, v0
	v_mov_b32_e32 v9, v0
	v_mov_b32_e32 v10, v0
	v_mov_b32_e32 v11, v0
	v_mov_b32_e32 v24, v0
	v_mov_b32_e32 v25, v0
	v_mov_b32_e32 v26, v0
	v_mov_b32_e32 v27, v0
	v_mov_b32_e32 v12, v0
	v_mov_b32_e32 v13, v0
	v_mov_b32_e32 v14, v0
	v_mov_b32_e32 v15, v0
	v_mov_b32_e32 v32, v0
	v_mov_b32_e32 v33, v0
	v_mov_b32_e32 v34, v0
	v_mov_b32_e32 v35, v0
	v_mov_b32_e32 v52, v0
	v_mov_b32_e32 v53, v0
	v_mov_b32_e32 v54, v0
	v_mov_b32_e32 v55, v0
	v_mov_b32_e32 v80, v0
	v_mov_b32_e32 v81, v0
	v_mov_b32_e32 v82, v0
	v_mov_b32_e32 v83, v0
	v_mov_b32_e32 v60, v0
	v_mov_b32_e32 v61, v0
	v_mov_b32_e32 v62, v0
	v_mov_b32_e32 v63, v0
	v_mov_b32_e32 v88, v0
	v_mov_b32_e32 v89, v0
	v_mov_b32_e32 v90, v0
	v_mov_b32_e32 v91, v0
	v_mov_b32_e32 v68, v0
	v_mov_b32_e32 v69, v0
	v_mov_b32_e32 v70, v0
	v_mov_b32_e32 v71, v0
	v_mov_b32_e32 v104, v0
	v_mov_b32_e32 v105, v0
	v_mov_b32_e32 v106, v0
	v_mov_b32_e32 v107, v0
	v_mov_b32_e32 v76, v0
	v_mov_b32_e32 v77, v0
	v_mov_b32_e32 v78, v0
	v_mov_b32_e32 v79, v0
	v_mov_b32_e32 v108, v0
	v_mov_b32_e32 v109, v0
	v_mov_b32_e32 v110, v0
	v_mov_b32_e32 v111, v0
	v_mov_b32_e32 v28, v0
	v_mov_b32_e32 v29, v0
	v_mov_b32_e32 v30, v0
	v_mov_b32_e32 v31, v0
	v_mov_b32_e32 v48, v0
	v_mov_b32_e32 v49, v0
	v_mov_b32_e32 v50, v0
	v_mov_b32_e32 v51, v0
	v_mov_b32_e32 v36, v0
	v_mov_b32_e32 v37, v0
	v_mov_b32_e32 v38, v0
	v_mov_b32_e32 v39, v0
	v_mov_b32_e32 v56, v0
	v_mov_b32_e32 v57, v0
	v_mov_b32_e32 v58, v0
	v_mov_b32_e32 v59, v0
	v_mov_b32_e32 v40, v0
	v_mov_b32_e32 v41, v0
	v_mov_b32_e32 v42, v0
	v_mov_b32_e32 v43, v0
	v_mov_b32_e32 v64, v0
	v_mov_b32_e32 v65, v0
	v_mov_b32_e32 v66, v0
	v_mov_b32_e32 v67, v0
	v_mov_b32_e32 v44, v0
	v_mov_b32_e32 v45, v0
	v_mov_b32_e32 v46, v0
	v_mov_b32_e32 v47, v0
	v_mov_b32_e32 v72, v0
	v_mov_b32_e32 v73, v0
	v_mov_b32_e32 v74, v0
	v_mov_b32_e32 v75, v0
	v_mov_b32_e32 v84, v0
	v_mov_b32_e32 v85, v0
	v_mov_b32_e32 v86, v0
	v_mov_b32_e32 v87, v0
	v_mov_b32_e32 v112, v0
	v_mov_b32_e32 v113, v0
	v_mov_b32_e32 v114, v0
	v_mov_b32_e32 v115, v0
	v_mov_b32_e32 v92, v0
	v_mov_b32_e32 v93, v0
	v_mov_b32_e32 v94, v0
	v_mov_b32_e32 v95, v0
	v_mov_b32_e32 v116, v0
	v_mov_b32_e32 v117, v0
	v_mov_b32_e32 v118, v0
	v_mov_b32_e32 v119, v0
	v_mov_b32_e32 v96, v0
	v_mov_b32_e32 v97, v0
	v_mov_b32_e32 v98, v0
	v_mov_b32_e32 v99, v0
	v_mov_b32_e32 v120, v0
	v_mov_b32_e32 v121, v0
	v_mov_b32_e32 v122, v0
	v_mov_b32_e32 v123, v0
	v_mov_b32_e32 v100, v0
	v_mov_b32_e32 v101, v0
	v_mov_b32_e32 v102, v0
	v_mov_b32_e32 v103, v0
	v_mov_b32_e32 v124, v0
	v_mov_b32_e32 v125, v0
	v_mov_b32_e32 v126, v0
	v_mov_b32_e32 v127, v0
	ds_read_b128 v[128:131], v221
	ds_read_b128 v[132:135], v221 offset:1024
	ds_read_b128 v[136:139], v221 offset:2048
	ds_read_b128 v[140:143], v221 offset:3072
	.p2alignl 6, 3212836864
.LBB0_1098:
	s_add_u32 s64, s62, 0x100
	s_addc_u32 s65, s63, 0
	s_cmpk_eq_i32 s76, 0x54
	s_cselect_b32 s5, s9, s65
	s_cselect_b32 s4, s8, s64
	s_cselect_b32 s67, s11, s1
	s_cselect_b32 s66, s10, s0
	s_add_i32 m0, s25, 0xc000
	ds_read_b128 v[144:147], v222
	ds_read_b128 v[148:151], v222 offset:1024
	ds_read_b128 v[152:155], v222 offset:2048
	ds_read_b128 v[156:159], v222 offset:3072
	ds_read_b128 v[160:163], v222 offset:4096
	ds_read_b128 v[176:179], v222 offset:5120
	ds_read_b128 v[180:183], v222 offset:6144
	ds_read_b128 v[184:187], v222 offset:7168
	global_load_lds_dwordx4 v168, s[62:63]
	s_add_i32 m0, s25, 0xe000
	s_nop 0
	global_load_lds_dwordx4 v170, s[62:63]
	s_waitcnt lgkmcnt(8)
	s_barrier
	s_waitcnt lgkmcnt(0)
	s_waitcnt lgkmcnt(0)
	v_mfma_f32_16x16x32_bf16 v[124:127], v[128:131], v[144:147], v[124:127]
	v_mfma_f32_16x16x32_bf16 v[100:103], v[136:139], v[144:147], v[100:103]
	v_mfma_f32_16x16x32_bf16 v[120:123], v[128:131], v[152:155], v[120:123]
	v_mfma_f32_16x16x32_bf16 v[96:99], v[136:139], v[152:155], v[96:99]
	v_mfma_f32_16x16x32_bf16 v[116:119], v[128:131], v[160:163], v[116:119]
	v_mfma_f32_16x16x32_bf16 v[92:95], v[136:139], v[160:163], v[92:95]
	v_mfma_f32_16x16x32_bf16 v[112:115], v[128:131], v[180:183], v[112:115]
	v_mfma_f32_16x16x32_bf16 v[84:87], v[136:139], v[180:183], v[84:87]
	v_mfma_f32_16x16x32_bf16 v[124:127], v[132:135], v[148:151], v[124:127]
	v_mfma_f32_16x16x32_bf16 v[100:103], v[140:143], v[148:151], v[100:103]
	v_mfma_f32_16x16x32_bf16 v[120:123], v[132:135], v[156:159], v[120:123]
	v_mfma_f32_16x16x32_bf16 v[96:99], v[140:143], v[156:159], v[96:99]
	v_mfma_f32_16x16x32_bf16 v[116:119], v[132:135], v[176:179], v[116:119]
	v_mfma_f32_16x16x32_bf16 v[92:95], v[140:143], v[176:179], v[92:95]
	v_mfma_f32_16x16x32_bf16 v[112:115], v[132:135], v[184:187], v[112:115]
	v_mfma_f32_16x16x32_bf16 v[84:87], v[140:143], v[184:187], v[84:87]
	s_barrier
	s_add_i32 s42, s41, s24
	s_add_u32 s98, s66, s18
	s_addc_u32 s99, s67, s19
	s_mov_b32 m0, s42
	ds_read_b128 v[188:191], v223
	ds_read_b128 v[192:195], v223 offset:1024
	ds_read_b128 v[196:199], v223 offset:2048
	ds_read_b128 v[200:203], v223 offset:3072
	global_load_lds_dwordx4 v166, s[66:67]
	s_add_i32 m0, s42, 0x2000
	s_nop 0
	global_load_lds_dwordx4 v164, s[66:67]
	s_barrier
	s_waitcnt lgkmcnt(0)
	s_waitcnt lgkmcnt(0)
	v_mfma_f32_16x16x32_bf16 v[72:75], v[188:191], v[144:147], v[72:75]
	v_mfma_f32_16x16x32_bf16 v[44:47], v[196:199], v[144:147], v[44:47]
	v_mfma_f32_16x16x32_bf16 v[64:67], v[188:191], v[152:155], v[64:67]
	v_mfma_f32_16x16x32_bf16 v[40:43], v[196:199], v[152:155], v[40:43]
	v_mfma_f32_16x16x32_bf16 v[56:59], v[188:191], v[160:163], v[56:59]
	v_mfma_f32_16x16x32_bf16 v[36:39], v[196:199], v[160:163], v[36:39]
	v_mfma_f32_16x16x32_bf16 v[48:51], v[188:191], v[180:183], v[48:51]
	v_mfma_f32_16x16x32_bf16 v[28:31], v[196:199], v[180:183], v[28:31]
	v_mfma_f32_16x16x32_bf16 v[72:75], v[192:195], v[148:151], v[72:75]
	v_mfma_f32_16x16x32_bf16 v[44:47], v[200:203], v[148:151], v[44:47]
	v_mfma_f32_16x16x32_bf16 v[64:67], v[192:195], v[156:159], v[64:67]
	v_mfma_f32_16x16x32_bf16 v[40:43], v[200:203], v[156:159], v[40:43]
	v_mfma_f32_16x16x32_bf16 v[56:59], v[192:195], v[176:179], v[56:59]
	v_mfma_f32_16x16x32_bf16 v[36:39], v[200:203], v[176:179], v[36:39]
	v_mfma_f32_16x16x32_bf16 v[48:51], v[192:195], v[184:187], v[48:51]
	v_mfma_f32_16x16x32_bf16 v[28:31], v[200:203], v[184:187], v[28:31]
	s_mov_b32 m0, s25
	s_add_u32 s100, s4, s18
	s_addc_u32 s101, s5, s19
	s_barrier
	s_waitcnt vmcnt(8)
	ds_read_b128 v[144:147], v222 offset:16384
	ds_read_b128 v[148:151], v222 offset:17408
	ds_read_b128 v[152:155], v222 offset:18432
	ds_read_b128 v[156:159], v222 offset:19456
	ds_read_b128 v[160:163], v222 offset:20480
	ds_read_b128 v[176:179], v222 offset:21504
	ds_read_b128 v[180:183], v222 offset:22528
	ds_read_b128 v[184:187], v222 offset:23552
	global_load_lds_dwordx4 v166, s[4:5]
	s_mov_b32 m0, s28
	s_nop 0
	global_load_lds_dwordx4 v164, s[4:5]
	s_barrier
	s_waitcnt lgkmcnt(0)
	s_waitcnt lgkmcnt(0)
	v_mfma_f32_16x16x32_bf16 v[108:111], v[128:131], v[144:147], v[108:111]
	v_mfma_f32_16x16x32_bf16 v[76:79], v[136:139], v[144:147], v[76:79]
	v_mfma_f32_16x16x32_bf16 v[104:107], v[128:131], v[152:155], v[104:107]
	v_mfma_f32_16x16x32_bf16 v[68:71], v[136:139], v[152:155], v[68:71]
	v_mfma_f32_16x16x32_bf16 v[88:91], v[128:131], v[160:163], v[88:91]
	v_mfma_f32_16x16x32_bf16 v[60:63], v[136:139], v[160:163], v[60:63]
	v_mfma_f32_16x16x32_bf16 v[80:83], v[128:131], v[180:183], v[80:83]
	v_mfma_f32_16x16x32_bf16 v[52:55], v[136:139], v[180:183], v[52:55]
	v_mfma_f32_16x16x32_bf16 v[108:111], v[132:135], v[148:151], v[108:111]
	v_mfma_f32_16x16x32_bf16 v[76:79], v[140:143], v[148:151], v[76:79]
	v_mfma_f32_16x16x32_bf16 v[104:107], v[132:135], v[156:159], v[104:107]
	v_mfma_f32_16x16x32_bf16 v[68:71], v[140:143], v[156:159], v[68:71]
	v_mfma_f32_16x16x32_bf16 v[88:91], v[132:135], v[176:179], v[88:91]
	v_mfma_f32_16x16x32_bf16 v[60:63], v[140:143], v[176:179], v[60:63]
	v_mfma_f32_16x16x32_bf16 v[80:83], v[132:135], v[184:187], v[80:83]
	v_mfma_f32_16x16x32_bf16 v[52:55], v[140:143], v[184:187], v[52:55]
	s_barrier
	s_add_u32 s42, s66, 0x160000
	s_addc_u32 s43, s67, 0
	s_add_i32 s44, s53, s24
	s_mov_b32 m0, s44
	s_nop 0
	global_load_lds_dwordx4 v166, s[42:43]
	s_add_i32 m0, s44, 0x2000
	s_nop 0
	global_load_lds_dwordx4 v164, s[42:43]
	v_add_u32_e32 v140, 0x18000, v219
	ds_read_b128 v[128:131], v140
	ds_read_b128 v[132:135], v140 offset:1024
	ds_read_b128 v[136:139], v140 offset:2048
	ds_read_b128 v[140:143], v140 offset:3072
	s_waitcnt vmcnt(6)
	s_barrier
	v_mfma_f32_16x16x32_bf16 v[32:35], v[188:191], v[144:147], v[32:35]
	v_mfma_f32_16x16x32_bf16 v[12:15], v[196:199], v[144:147], v[12:15]
	v_mfma_f32_16x16x32_bf16 v[24:27], v[188:191], v[152:155], v[24:27]
	v_mfma_f32_16x16x32_bf16 v[8:11], v[196:199], v[152:155], v[8:11]
	v_mfma_f32_16x16x32_bf16 v[20:23], v[188:191], v[160:163], v[20:23]
	v_mfma_f32_16x16x32_bf16 v[4:7], v[196:199], v[160:163], v[4:7]
	v_mfma_f32_16x16x32_bf16 v[16:19], v[188:191], v[180:183], v[16:19]
	v_mfma_f32_16x16x32_bf16 v[0:3], v[196:199], v[180:183], v[0:3]
	v_mfma_f32_16x16x32_bf16 v[32:35], v[192:195], v[148:151], v[32:35]
	v_mfma_f32_16x16x32_bf16 v[12:15], v[200:203], v[148:151], v[12:15]
	v_mfma_f32_16x16x32_bf16 v[24:27], v[192:195], v[156:159], v[24:27]
	v_mfma_f32_16x16x32_bf16 v[8:11], v[200:203], v[156:159], v[8:11]
	v_mfma_f32_16x16x32_bf16 v[20:23], v[192:195], v[176:179], v[20:23]
	v_mfma_f32_16x16x32_bf16 v[4:7], v[200:203], v[176:179], v[4:7]
	v_mfma_f32_16x16x32_bf16 v[16:19], v[192:195], v[184:187], v[16:19]
	v_mfma_f32_16x16x32_bf16 v[0:3], v[200:203], v[184:187], v[0:3]
	s_add_i32 s42, 0, 0x18000
	s_barrier
	s_add_u32 s4, s4, 0x160000
	s_addc_u32 s5, s5, 0
	s_mov_b32 m0, s29
	ds_read_b128 v[144:147], v222 offset:32768
	ds_read_b128 v[148:151], v222 offset:33792
	ds_read_b128 v[152:155], v222 offset:34816
	ds_read_b128 v[156:159], v222 offset:35840
	ds_read_b128 v[160:163], v222 offset:36864
	ds_read_b128 v[176:179], v222 offset:37888
	ds_read_b128 v[180:183], v222 offset:38912
	ds_read_b128 v[184:187], v222 offset:39936
	global_load_lds_dwordx4 v166, s[4:5]
	s_mov_b32 m0, s33
	s_nop 0
	global_load_lds_dwordx4 v164, s[4:5]
	s_waitcnt lgkmcnt(8)
	s_barrier
	s_waitcnt lgkmcnt(0)
	s_waitcnt lgkmcnt(0)
	v_mfma_f32_16x16x32_bf16 v[124:127], v[128:131], v[144:147], v[124:127]
	v_mfma_f32_16x16x32_bf16 v[100:103], v[136:139], v[144:147], v[100:103]
	v_mfma_f32_16x16x32_bf16 v[120:123], v[128:131], v[152:155], v[120:123]
	v_mfma_f32_16x16x32_bf16 v[96:99], v[136:139], v[152:155], v[96:99]
	v_mfma_f32_16x16x32_bf16 v[116:119], v[128:131], v[160:163], v[116:119]
	v_mfma_f32_16x16x32_bf16 v[92:95], v[136:139], v[160:163], v[92:95]
	v_mfma_f32_16x16x32_bf16 v[112:115], v[128:131], v[180:183], v[112:115]
	v_mfma_f32_16x16x32_bf16 v[84:87], v[136:139], v[180:183], v[84:87]
	v_mfma_f32_16x16x32_bf16 v[124:127], v[132:135], v[148:151], v[124:127]
	v_mfma_f32_16x16x32_bf16 v[100:103], v[140:143], v[148:151], v[100:103]
	v_mfma_f32_16x16x32_bf16 v[120:123], v[132:135], v[156:159], v[120:123]
	v_mfma_f32_16x16x32_bf16 v[96:99], v[140:143], v[156:159], v[96:99]
	v_mfma_f32_16x16x32_bf16 v[116:119], v[132:135], v[176:179], v[116:119]
	v_mfma_f32_16x16x32_bf16 v[92:95], v[140:143], v[176:179], v[92:95]
	v_mfma_f32_16x16x32_bf16 v[112:115], v[132:135], v[184:187], v[112:115]
	v_mfma_f32_16x16x32_bf16 v[84:87], v[140:143], v[184:187], v[84:87]
	s_barrier
	s_add_i32 s43, 0, 0x1c000
	s_add_i32 s4, s42, s24
	v_add_u32_e32 v200, s43, v219
	s_mov_b32 m0, s4
	ds_read_b128 v[188:191], v200
	ds_read_b128 v[192:195], v200 offset:1024
	ds_read_b128 v[196:199], v200 offset:2048
	ds_read_b128 v[200:203], v200 offset:3072
	global_load_lds_dwordx4 v166, s[98:99]
	s_add_i32 m0, s4, 0x2000
	s_nop 0
	global_load_lds_dwordx4 v164, s[98:99]
	s_barrier
	s_waitcnt lgkmcnt(0)
	s_waitcnt lgkmcnt(0)
	v_mfma_f32_16x16x32_bf16 v[72:75], v[188:191], v[144:147], v[72:75]
	v_mfma_f32_16x16x32_bf16 v[44:47], v[196:199], v[144:147], v[44:47]
	v_mfma_f32_16x16x32_bf16 v[64:67], v[188:191], v[152:155], v[64:67]
	v_mfma_f32_16x16x32_bf16 v[40:43], v[196:199], v[152:155], v[40:43]
	v_mfma_f32_16x16x32_bf16 v[56:59], v[188:191], v[160:163], v[56:59]
	v_mfma_f32_16x16x32_bf16 v[36:39], v[196:199], v[160:163], v[36:39]
	v_mfma_f32_16x16x32_bf16 v[48:51], v[188:191], v[180:183], v[48:51]
	v_mfma_f32_16x16x32_bf16 v[28:31], v[196:199], v[180:183], v[28:31]
	v_mfma_f32_16x16x32_bf16 v[72:75], v[192:195], v[148:151], v[72:75]
	v_mfma_f32_16x16x32_bf16 v[44:47], v[200:203], v[148:151], v[44:47]
	v_mfma_f32_16x16x32_bf16 v[64:67], v[192:195], v[156:159], v[64:67]
	v_mfma_f32_16x16x32_bf16 v[40:43], v[200:203], v[156:159], v[40:43]
	v_mfma_f32_16x16x32_bf16 v[56:59], v[192:195], v[176:179], v[56:59]
	v_mfma_f32_16x16x32_bf16 v[36:39], v[200:203], v[176:179], v[36:39]
	v_mfma_f32_16x16x32_bf16 v[48:51], v[192:195], v[184:187], v[48:51]
	v_mfma_f32_16x16x32_bf16 v[28:31], v[200:203], v[184:187], v[28:31]
	s_mov_b32 m0, s37
	s_barrier
	s_waitcnt vmcnt(8)
	ds_read_b128 v[144:147], v222 offset:49152
	ds_read_b128 v[148:151], v222 offset:50176
	ds_read_b128 v[152:155], v222 offset:51200
	ds_read_b128 v[156:159], v222 offset:52224
	ds_read_b128 v[160:163], v222 offset:53248
	ds_read_b128 v[176:179], v222 offset:54272
	ds_read_b128 v[180:183], v222 offset:55296
	ds_read_b128 v[184:187], v222 offset:56320
	global_load_lds_dwordx4 v166, s[100:101]
	s_mov_b32 m0, s40
	s_nop 0
	global_load_lds_dwordx4 v164, s[100:101]
	s_barrier
	s_waitcnt lgkmcnt(0)
	s_waitcnt lgkmcnt(0)
	v_mfma_f32_16x16x32_bf16 v[108:111], v[128:131], v[144:147], v[108:111]
	v_mfma_f32_16x16x32_bf16 v[76:79], v[136:139], v[144:147], v[76:79]
	v_mfma_f32_16x16x32_bf16 v[104:107], v[128:131], v[152:155], v[104:107]
	v_mfma_f32_16x16x32_bf16 v[68:71], v[136:139], v[152:155], v[68:71]
	v_mfma_f32_16x16x32_bf16 v[88:91], v[128:131], v[160:163], v[88:91]
	v_mfma_f32_16x16x32_bf16 v[60:63], v[136:139], v[160:163], v[60:63]
	v_mfma_f32_16x16x32_bf16 v[80:83], v[128:131], v[180:183], v[80:83]
	v_mfma_f32_16x16x32_bf16 v[52:55], v[136:139], v[180:183], v[52:55]
	v_mfma_f32_16x16x32_bf16 v[108:111], v[132:135], v[148:151], v[108:111]
	v_mfma_f32_16x16x32_bf16 v[76:79], v[140:143], v[148:151], v[76:79]
	v_mfma_f32_16x16x32_bf16 v[104:107], v[132:135], v[156:159], v[104:107]
	v_mfma_f32_16x16x32_bf16 v[68:71], v[140:143], v[156:159], v[68:71]
	v_mfma_f32_16x16x32_bf16 v[88:91], v[132:135], v[176:179], v[88:91]
	v_mfma_f32_16x16x32_bf16 v[60:63], v[140:143], v[176:179], v[60:63]
	v_mfma_f32_16x16x32_bf16 v[80:83], v[132:135], v[184:187], v[80:83]
	v_mfma_f32_16x16x32_bf16 v[52:55], v[140:143], v[184:187], v[52:55]
	s_barrier
	s_add_u32 s4, s66, 0x160080
	s_addc_u32 s5, s67, 0
	s_add_i32 s42, s43, s24
	s_mov_b32 m0, s42
	s_nop 0
	global_load_lds_dwordx4 v166, s[4:5]
	s_add_i32 m0, s42, 0x2000
	s_nop 0
	global_load_lds_dwordx4 v164, s[4:5]
	ds_read_b128 v[128:131], v221
	ds_read_b128 v[132:135], v221 offset:1024
	ds_read_b128 v[136:139], v221 offset:2048
	ds_read_b128 v[140:143], v221 offset:3072
	s_waitcnt vmcnt(6)
	s_barrier
	v_mfma_f32_16x16x32_bf16 v[32:35], v[188:191], v[144:147], v[32:35]
	v_mfma_f32_16x16x32_bf16 v[12:15], v[196:199], v[144:147], v[12:15]
	v_mfma_f32_16x16x32_bf16 v[24:27], v[188:191], v[152:155], v[24:27]
	v_mfma_f32_16x16x32_bf16 v[8:11], v[196:199], v[152:155], v[8:11]
	v_mfma_f32_16x16x32_bf16 v[20:23], v[188:191], v[160:163], v[20:23]
	v_mfma_f32_16x16x32_bf16 v[4:7], v[196:199], v[160:163], v[4:7]
	v_mfma_f32_16x16x32_bf16 v[16:19], v[188:191], v[180:183], v[16:19]
	v_mfma_f32_16x16x32_bf16 v[0:3], v[196:199], v[180:183], v[0:3]
	v_mfma_f32_16x16x32_bf16 v[32:35], v[192:195], v[148:151], v[32:35]
	v_mfma_f32_16x16x32_bf16 v[12:15], v[200:203], v[148:151], v[12:15]
	v_mfma_f32_16x16x32_bf16 v[24:27], v[192:195], v[156:159], v[24:27]
	v_mfma_f32_16x16x32_bf16 v[8:11], v[200:203], v[156:159], v[8:11]
	v_mfma_f32_16x16x32_bf16 v[20:23], v[192:195], v[176:179], v[20:23]
	v_mfma_f32_16x16x32_bf16 v[4:7], v[200:203], v[176:179], v[4:7]
	v_mfma_f32_16x16x32_bf16 v[16:19], v[192:195], v[184:187], v[16:19]
	v_mfma_f32_16x16x32_bf16 v[0:3], v[200:203], v[184:187], v[0:3]
	s_add_i32 s76, s76, 2
	s_add_u32 s0, s0, 0x100
	s_addc_u32 s1, s1, 0
	s_cmpk_gt_u32 s76, 0x55
	s_mov_b64 s[62:63], s[64:65]
	s_barrier
	s_cbranch_scc0 .LBB0_1098
	v_lshl_add_u32 v144, s74, 8, v218
	v_lshl_or_b32 v184, s75, 8, v220
	v_ashrrev_i32_e32 v145, 31, v144
	v_ashrrev_i32_e32 v185, 31, v184
	v_lshlrev_b64 v[132:133], 13, v[144:145]
	v_lshlrev_b64 v[146:147], 2, v[184:185]
	v_lshl_add_u64 v[132:133], s[12:13], 0, v[132:133]
	v_lshl_add_u64 v[176:177], v[132:133], 0, v[146:147]
	v_or_b32_e32 v136, 16, v144
	v_add_co_u32_e32 v186, vcc, s68, v176
	v_ashrrev_i32_e32 v137, 31, v136
	v_or_b32_e32 v140, 32, v144
	v_or_b32_e32 v144, 48, v144
	v_addc_co_u32_e32 v187, vcc, 0, v177, vcc
	v_lshlrev_b64 v[136:137], 13, v[136:137]
	v_ashrrev_i32_e32 v141, 31, v140
	v_ashrrev_i32_e32 v145, 31, v144
	v_add_co_u32_e32 v190, vcc, s69, v176
	v_lshl_add_u64 v[128:129], s[16:17], 0, v[146:147]
	v_lshl_add_u64 v[136:137], s[12:13], 0, v[136:137]
	v_lshlrev_b64 v[140:141], 13, v[140:141]
	v_lshlrev_b64 v[144:145], 13, v[144:145]
	v_addc_co_u32_e32 v191, vcc, 0, v177, vcc
	global_load_dwordx4 v[128:131], v[128:129], off
	v_lshl_add_u64 v[178:179], v[136:137], 0, v[146:147]
	global_load_dwordx4 v[132:135], v[176:177], off
	global_load_dwordx4 v[136:139], v[178:179], off
	v_lshl_add_u64 v[140:141], s[12:13], 0, v[140:141]
	v_lshl_add_u64 v[144:145], s[12:13], 0, v[144:145]
	v_add_co_u32_e32 v192, vcc, s70, v176
	v_lshl_add_u64 v[180:181], v[140:141], 0, v[146:147]
	v_lshl_add_u64 v[182:183], v[144:145], 0, v[146:147]
	v_addc_co_u32_e32 v193, vcc, 0, v177, vcc
	global_load_dwordx4 v[140:143], v[180:181], off
	global_load_dwordx4 v[144:147], v[182:183], off
	global_load_dwordx4 v[148:151], v[186:187], off
	global_load_dwordx4 v[160:163], v[190:191], off
	global_load_dwordx4 v[156:159], v[192:193], off
	v_add_co_u32_e32 v188, vcc, s71, v176
	v_pk_add_f32 v[212:213], v[126:127], 0 op_sel_hi:[1,0]
	s_nop 0
	v_addc_co_u32_e32 v189, vcc, 0, v177, vcc
	global_load_dwordx4 v[152:155], v[188:189], off
	v_pk_add_f32 v[214:215], v[124:125], 0 op_sel_hi:[1,0]
	v_pk_add_f32 v[126:127], v[122:123], 0 op_sel_hi:[1,0]
	v_pk_add_f32 v[194:195], v[120:121], 0 op_sel_hi:[1,0]
	v_pk_add_f32 v[196:197], v[118:119], 0 op_sel_hi:[1,0]
	v_pk_add_f32 v[198:199], v[116:117], 0 op_sel_hi:[1,0]
	v_pk_add_f32 v[200:201], v[114:115], 0 op_sel_hi:[1,0]
	v_pk_add_f32 v[202:203], v[112:113], 0 op_sel_hi:[1,0]
	v_pk_add_f32 v[204:205], v[110:111], 0 op_sel_hi:[1,0]
	v_pk_add_f32 v[206:207], v[108:109], 0 op_sel_hi:[1,0]
	v_pk_add_f32 v[208:209], v[106:107], 0 op_sel_hi:[1,0]
	v_pk_add_f32 v[210:211], v[104:105], 0 op_sel_hi:[1,0]
	v_lshl_add_u64 v[120:121], v[176:177], 0, s[20:21]
	v_lshl_add_u64 v[122:123], v[176:177], 0, s[46:47]
	global_load_dwordx4 v[104:107], v[176:177], off offset:64
	global_load_dwordx4 v[108:111], v[178:179], off offset:64
	global_load_dwordx4 v[112:115], v[180:181], off offset:64
	global_load_dwordx4 v[116:119], v[182:183], off offset:64
	global_load_dwordx4 v[224:227], v[120:121], off offset:576
	global_load_dwordx4 v[228:231], v[122:123], off offset:576
	v_lshl_add_u64 v[124:125], v[176:177], 0, s[60:61]
	v_pk_add_f32 v[102:103], v[102:103], 0 op_sel_hi:[1,0]
	v_pk_add_f32 v[100:101], v[100:101], 0 op_sel_hi:[1,0]
	v_pk_add_f32 v[98:99], v[98:99], 0 op_sel_hi:[1,0]
	v_pk_add_f32 v[96:97], v[96:97], 0 op_sel_hi:[1,0]
	v_pk_add_f32 v[74:75], v[74:75], 0 op_sel_hi:[1,0]
	v_pk_add_f32 v[72:73], v[72:73], 0 op_sel_hi:[1,0]
	v_pk_add_f32 v[66:67], v[66:67], 0 op_sel_hi:[1,0]
	v_pk_add_f32 v[64:65], v[64:65], 0 op_sel_hi:[1,0]
	v_pk_add_f32 v[58:59], v[58:59], 0 op_sel_hi:[1,0]
	v_pk_add_f32 v[56:57], v[56:57], 0 op_sel_hi:[1,0]
	v_pk_add_f32 v[46:47], v[46:47], 0 op_sel_hi:[1,0]
	v_pk_add_f32 v[44:45], v[44:45], 0 op_sel_hi:[1,0]
	v_pk_add_f32 v[42:43], v[42:43], 0 op_sel_hi:[1,0]
	v_pk_add_f32 v[40:41], v[40:41], 0 op_sel_hi:[1,0]
	v_pk_add_f32 v[38:39], v[38:39], 0 op_sel_hi:[1,0]
	v_pk_add_f32 v[36:37], v[36:37], 0 op_sel_hi:[1,0]
	v_pk_add_f32 v[30:31], v[30:31], 0 op_sel_hi:[1,0]
	v_pk_add_f32 v[28:29], v[28:29], 0 op_sel_hi:[1,0]
	s_and_b64 vcc, exec, s[6:7]
	s_mov_b32 s75, s72
	s_mov_b32 s74, s73
	s_mov_b64 s[64:65], s[10:11]
	s_mov_b64 s[62:63], s[8:9]
	s_waitcnt vmcnt(0)
	v_pk_fma_f32 v[134:135], v[212:213], v[130:131], v[134:135]
	v_pk_fma_f32 v[132:133], v[214:215], v[128:129], v[132:133]
	global_store_dwordx4 v[176:177], v[132:135], off
	s_nop 1
	v_pk_fma_f32 v[134:135], v[126:127], v[130:131], v[138:139]
	v_pk_fma_f32 v[132:133], v[194:195], v[128:129], v[136:137]
	v_pk_add_f32 v[126:127], v[90:91], 0 op_sel_hi:[1,0]
	v_pk_fma_f32 v[138:139], v[196:197], v[130:131], v[142:143]
	v_pk_fma_f32 v[136:137], v[198:199], v[128:129], v[140:141]
	v_pk_fma_f32 v[142:143], v[200:201], v[130:131], v[146:147]
	v_pk_fma_f32 v[140:141], v[202:203], v[128:129], v[144:145]
	v_pk_fma_f32 v[146:147], v[204:205], v[130:131], v[150:151]
	v_pk_fma_f32 v[144:145], v[206:207], v[128:129], v[148:149]
	v_pk_fma_f32 v[150:151], v[208:209], v[130:131], v[162:163]
	v_pk_fma_f32 v[148:149], v[210:211], v[128:129], v[160:161]
	global_store_dwordx4 v[178:179], v[132:135], off
	global_store_dwordx4 v[180:181], v[136:139], off
	global_store_dwordx4 v[182:183], v[140:143], off
	global_store_dwordx4 v[186:187], v[144:147], off
	global_store_dwordx4 v[190:191], v[148:151], off
	v_pk_add_f32 v[132:133], v[88:89], 0 op_sel_hi:[1,0]
	v_pk_fma_f32 v[134:135], v[126:127], v[130:131], v[158:159]
	v_pk_fma_f32 v[132:133], v[132:133], v[128:129], v[156:157]
	v_pk_add_f32 v[126:127], v[82:83], 0 op_sel_hi:[1,0]
	global_store_dwordx4 v[192:193], v[132:135], off
	v_pk_fma_f32 v[130:131], v[126:127], v[130:131], v[154:155]
	v_or_b32_e32 v126, 16, v184
	v_pk_add_f32 v[132:133], v[80:81], 0 op_sel_hi:[1,0]
	v_ashrrev_i32_e32 v127, 31, v126
	v_pk_fma_f32 v[128:129], v[132:133], v[128:129], v[152:153]
	v_lshl_add_u64 v[146:147], v[176:177], 0, s[14:15]
	global_store_dwordx4 v[188:189], v[128:131], off
	v_lshl_add_u64 v[126:127], v[126:127], 2, s[16:17]
	global_load_dwordx4 v[88:91], v[124:125], off offset:576
	global_load_dwordx4 v[80:83], v[146:147], off offset:576
	s_nop 0
	global_load_dwordx4 v[126:129], v[126:127], off
	s_nop 0
	global_load_dwordx4 v[130:133], v[120:121], off offset:64
	global_load_dwordx4 v[134:137], v[122:123], off offset:64
	global_load_dwordx4 v[138:141], v[124:125], off offset:64
	global_load_dwordx4 v[142:145], v[146:147], off offset:64
	v_pk_add_f32 v[192:193], v[52:53], 0 op_sel_hi:[1,0]
	v_or_b32_e32 v52, 0x80, v184
	v_pk_add_f32 v[148:149], v[94:95], 0 op_sel_hi:[1,0]
	v_pk_add_f32 v[150:151], v[92:93], 0 op_sel_hi:[1,0]
	v_pk_add_f32 v[152:153], v[86:87], 0 op_sel_hi:[1,0]
	v_pk_add_f32 v[154:155], v[84:85], 0 op_sel_hi:[1,0]
	v_pk_add_f32 v[156:157], v[78:79], 0 op_sel_hi:[1,0]
	v_pk_add_f32 v[158:159], v[76:77], 0 op_sel_hi:[1,0]
	v_pk_add_f32 v[160:161], v[70:71], 0 op_sel_hi:[1,0]
	v_pk_add_f32 v[162:163], v[68:69], 0 op_sel_hi:[1,0]
	v_pk_add_f32 v[186:187], v[62:63], 0 op_sel_hi:[1,0]
	v_pk_add_f32 v[188:189], v[60:61], 0 op_sel_hi:[1,0]
	v_pk_add_f32 v[190:191], v[54:55], 0 op_sel_hi:[1,0]
	v_ashrrev_i32_e32 v53, 31, v52
	v_lshl_add_u64 v[194:195], v[52:53], 2, s[16:17]
	global_load_dwordx4 v[52:55], v[176:177], off offset:512
	global_load_dwordx4 v[60:63], v[120:121], off offset:512
	global_load_dwordx4 v[68:71], v[122:123], off offset:512
	global_load_dwordx4 v[76:79], v[124:125], off offset:512
	global_load_dwordx4 v[84:87], v[146:147], off offset:512
	s_waitcnt vmcnt(0)
	v_pk_fma_f32 v[94:95], v[102:103], v[128:129], v[106:107]
	v_pk_fma_f32 v[92:93], v[100:101], v[126:127], v[104:105]
	v_pk_fma_f32 v[98:99], v[98:99], v[128:129], v[110:111]
	v_pk_fma_f32 v[96:97], v[96:97], v[126:127], v[108:109]
	v_pk_fma_f32 v[102:103], v[148:149], v[128:129], v[114:115]
	v_pk_fma_f32 v[100:101], v[150:151], v[126:127], v[112:113]
	v_pk_fma_f32 v[106:107], v[152:153], v[128:129], v[118:119]
	v_pk_fma_f32 v[104:105], v[154:155], v[126:127], v[116:117]
	v_pk_fma_f32 v[110:111], v[156:157], v[128:129], v[132:133]
	v_pk_fma_f32 v[108:109], v[158:159], v[126:127], v[130:131]
	v_pk_fma_f32 v[114:115], v[160:161], v[128:129], v[136:137]
	v_pk_fma_f32 v[112:113], v[162:163], v[126:127], v[134:135]
	v_pk_fma_f32 v[118:119], v[186:187], v[128:129], v[140:141]
	v_pk_fma_f32 v[116:117], v[188:189], v[126:127], v[138:139]
	v_pk_fma_f32 v[128:129], v[190:191], v[128:129], v[144:145]
	v_pk_fma_f32 v[126:127], v[192:193], v[126:127], v[142:143]
	global_store_dwordx4 v[176:177], v[92:95], off offset:64
	global_store_dwordx4 v[178:179], v[96:99], off offset:64
	global_store_dwordx4 v[180:181], v[100:103], off offset:64
	global_store_dwordx4 v[182:183], v[104:107], off offset:64
	global_store_dwordx4 v[120:121], v[108:111], off offset:64
	global_store_dwordx4 v[122:123], v[112:115], off offset:64
	global_store_dwordx4 v[124:125], v[116:119], off offset:64
	global_store_dwordx4 v[146:147], v[126:129], off offset:64
	global_load_dwordx4 v[92:95], v[194:195], off
	global_load_dwordx4 v[96:99], v[178:179], off offset:512
	global_load_dwordx4 v[100:103], v[180:181], off offset:512
	global_load_dwordx4 v[104:107], v[182:183], off offset:512
	v_pk_add_f32 v[132:133], v[16:17], 0 op_sel_hi:[1,0]
	v_or_b32_e32 v16, 0x90, v184
	v_pk_add_f32 v[108:109], v[50:51], 0 op_sel_hi:[1,0]
	v_pk_add_f32 v[110:111], v[48:49], 0 op_sel_hi:[1,0]
	v_pk_add_f32 v[112:113], v[34:35], 0 op_sel_hi:[1,0]
	v_pk_add_f32 v[114:115], v[32:33], 0 op_sel_hi:[1,0]
	v_pk_add_f32 v[116:117], v[26:27], 0 op_sel_hi:[1,0]
	v_pk_add_f32 v[118:119], v[24:25], 0 op_sel_hi:[1,0]
	v_pk_add_f32 v[126:127], v[22:23], 0 op_sel_hi:[1,0]
	v_pk_add_f32 v[128:129], v[20:21], 0 op_sel_hi:[1,0]
	v_pk_add_f32 v[130:131], v[18:19], 0 op_sel_hi:[1,0]
	v_ashrrev_i32_e32 v17, 31, v16
	v_lshl_add_u64 v[134:135], v[16:17], 2, s[16:17]
	global_load_dwordx4 v[16:19], v[176:177], off offset:576
	global_load_dwordx4 v[20:23], v[178:179], off offset:576
	global_load_dwordx4 v[24:27], v[180:181], off offset:576
	global_load_dwordx4 v[32:35], v[182:183], off offset:576
	s_waitcnt vmcnt(0)
	v_pk_fma_f32 v[50:51], v[74:75], v[94:95], v[54:55]
	v_pk_fma_f32 v[48:49], v[72:73], v[92:93], v[52:53]
	v_pk_fma_f32 v[54:55], v[66:67], v[94:95], v[98:99]
	v_pk_fma_f32 v[52:53], v[64:65], v[92:93], v[96:97]
	v_pk_fma_f32 v[58:59], v[58:59], v[94:95], v[102:103]
	v_pk_fma_f32 v[56:57], v[56:57], v[92:93], v[100:101]
	v_pk_fma_f32 v[66:67], v[108:109], v[94:95], v[106:107]
	v_pk_fma_f32 v[64:65], v[110:111], v[92:93], v[104:105]
	v_pk_fma_f32 v[62:63], v[112:113], v[94:95], v[62:63]
	v_pk_fma_f32 v[60:61], v[114:115], v[92:93], v[60:61]
	v_pk_fma_f32 v[70:71], v[116:117], v[94:95], v[70:71]
	v_pk_fma_f32 v[68:69], v[118:119], v[92:93], v[68:69]
	v_pk_fma_f32 v[74:75], v[126:127], v[94:95], v[78:79]
	v_pk_fma_f32 v[72:73], v[128:129], v[92:93], v[76:77]
	v_pk_fma_f32 v[78:79], v[130:131], v[94:95], v[86:87]
	v_pk_fma_f32 v[76:77], v[132:133], v[92:93], v[84:85]
	global_store_dwordx4 v[176:177], v[48:51], off offset:512
	global_store_dwordx4 v[178:179], v[52:55], off offset:512
	global_store_dwordx4 v[180:181], v[56:59], off offset:512
	global_store_dwordx4 v[182:183], v[64:67], off offset:512
	global_store_dwordx4 v[120:121], v[60:63], off offset:512
	global_store_dwordx4 v[122:123], v[68:71], off offset:512
	global_store_dwordx4 v[124:125], v[72:75], off offset:512
	global_store_dwordx4 v[146:147], v[76:79], off offset:512
	global_load_dwordx4 v[48:51], v[134:135], off
	v_pk_add_f32 v[52:53], v[14:15], 0 op_sel_hi:[1,0]
	v_pk_add_f32 v[54:55], v[12:13], 0 op_sel_hi:[1,0]
	v_pk_add_f32 v[56:57], v[10:11], 0 op_sel_hi:[1,0]
	v_pk_add_f32 v[58:59], v[8:9], 0 op_sel_hi:[1,0]
	v_pk_add_f32 v[60:61], v[6:7], 0 op_sel_hi:[1,0]
	v_pk_add_f32 v[62:63], v[4:5], 0 op_sel_hi:[1,0]
	v_pk_add_f32 v[64:65], v[2:3], 0 op_sel_hi:[1,0]
	v_pk_add_f32 v[66:67], v[0:1], 0 op_sel_hi:[1,0]
	s_waitcnt vmcnt(0)
	v_pk_fma_f32 v[2:3], v[46:47], v[50:51], v[18:19]
	v_pk_fma_f32 v[0:1], v[44:45], v[48:49], v[16:17]
	v_pk_fma_f32 v[6:7], v[42:43], v[50:51], v[22:23]
	v_pk_fma_f32 v[4:5], v[40:41], v[48:49], v[20:21]
	v_pk_fma_f32 v[10:11], v[38:39], v[50:51], v[26:27]
	v_pk_fma_f32 v[8:9], v[36:37], v[48:49], v[24:25]
	v_pk_fma_f32 v[14:15], v[30:31], v[50:51], v[34:35]
	v_pk_fma_f32 v[12:13], v[28:29], v[48:49], v[32:33]
	v_pk_fma_f32 v[18:19], v[52:53], v[50:51], v[226:227]
	v_pk_fma_f32 v[16:17], v[54:55], v[48:49], v[224:225]
	v_pk_fma_f32 v[22:23], v[56:57], v[50:51], v[230:231]
	v_pk_fma_f32 v[20:21], v[58:59], v[48:49], v[228:229]
	v_pk_fma_f32 v[26:27], v[60:61], v[50:51], v[90:91]
	v_pk_fma_f32 v[24:25], v[62:63], v[48:49], v[88:89]
	v_pk_fma_f32 v[30:31], v[64:65], v[50:51], v[82:83]
	v_pk_fma_f32 v[28:29], v[66:67], v[48:49], v[80:81]
	global_store_dwordx4 v[176:177], v[0:3], off offset:576
	global_store_dwordx4 v[178:179], v[4:7], off offset:576
	global_store_dwordx4 v[180:181], v[8:11], off offset:576
	global_store_dwordx4 v[182:183], v[12:15], off offset:576
	global_store_dwordx4 v[120:121], v[16:19], off offset:576
	global_store_dwordx4 v[122:123], v[20:23], off offset:576
	global_store_dwordx4 v[124:125], v[24:27], off offset:576
	global_store_dwordx4 v[146:147], v[28:31], off offset:576
	s_cbranch_vccz .LBB0_1087
	s_waitcnt vmcnt(0)
	s_cmpk_gt_u32 s23, 0xff
	s_cbranch_scc1 .LBB0_1102
	s_barrier

.LBB0_1233:
	s_ashr_i32 s15, s14, 31
	v_cmp_lt_i64_e32 vcc, s[0:1], v[148:149]
	s_lshl_b64 s[0:1], s[14:15], 20
	s_add_u32 s16, s38, s0
	s_addc_u32 s17, s39, s1
	s_and_b64 s[0:1], vcc, exec
	s_cselect_b32 s0, s17, s37
	s_cselect_b32 s1, s16, s36
	s_ashr_i32 s13, s12, 31
	s_lshl_b64 s[4:5], s[12:13], 20
	s_add_u32 s18, s54, s4
	s_addc_u32 s19, s55, s5
	s_and_b64 s[4:5], vcc, exec
	s_cselect_b32 s13, s19, s59
	s_cselect_b32 s15, s18, s58
	s_add_u32 s46, s36, 0x80080
	s_addc_u32 s47, s37, 0
	s_add_u32 s36, s58, 0x100
	v_mov_b32_e32 v0, 0
	s_addc_u32 s37, s59, 0
	s_mov_b32 s64, -2
	v_mov_b32_e32 v1, v0
	v_mov_b32_e32 v2, v0
	v_mov_b32_e32 v3, v0
	v_mov_b32_e32 v4, v0
	v_mov_b32_e32 v5, v0
	v_mov_b32_e32 v6, v0
	v_mov_b32_e32 v7, v0
	v_mov_b32_e32 v8, v0
	v_mov_b32_e32 v9, v0
	v_mov_b32_e32 v10, v0
	v_mov_b32_e32 v11, v0
	v_mov_b32_e32 v12, v0
	v_mov_b32_e32 v13, v0
	v_mov_b32_e32 v14, v0
	v_mov_b32_e32 v15, v0
	v_mov_b32_e32 v16, v0
	v_mov_b32_e32 v17, v0
	v_mov_b32_e32 v18, v0
	v_mov_b32_e32 v19, v0
	v_mov_b32_e32 v20, v0
	v_mov_b32_e32 v21, v0
	v_mov_b32_e32 v22, v0
	v_mov_b32_e32 v23, v0
	v_mov_b32_e32 v24, v0
	v_mov_b32_e32 v25, v0
	v_mov_b32_e32 v26, v0
	v_mov_b32_e32 v27, v0
	v_mov_b32_e32 v28, v0
	v_mov_b32_e32 v29, v0
	v_mov_b32_e32 v30, v0
	v_mov_b32_e32 v31, v0
	v_mov_b32_e32 v56, v0
	v_mov_b32_e32 v57, v0
	v_mov_b32_e32 v58, v0
	v_mov_b32_e32 v59, v0
	v_mov_b32_e32 v60, v0
	v_mov_b32_e32 v61, v0
	v_mov_b32_e32 v62, v0
	v_mov_b32_e32 v63, v0
	v_mov_b32_e32 v72, v0
	v_mov_b32_e32 v73, v0
	v_mov_b32_e32 v74, v0
	v_mov_b32_e32 v75, v0
	v_mov_b32_e32 v76, v0
	v_mov_b32_e32 v77, v0
	v_mov_b32_e32 v78, v0
	v_mov_b32_e32 v79, v0
	v_mov_b32_e32 v80, v0
	v_mov_b32_e32 v81, v0
	v_mov_b32_e32 v82, v0
	v_mov_b32_e32 v83, v0
	v_mov_b32_e32 v84, v0
	v_mov_b32_e32 v85, v0
	v_mov_b32_e32 v86, v0
	v_mov_b32_e32 v87, v0
	v_mov_b32_e32 v88, v0
	v_mov_b32_e32 v89, v0
	v_mov_b32_e32 v90, v0
	v_mov_b32_e32 v91, v0
	v_mov_b32_e32 v92, v0
	v_mov_b32_e32 v93, v0
	v_mov_b32_e32 v94, v0
	v_mov_b32_e32 v95, v0
	v_mov_b32_e32 v32, v0
	v_mov_b32_e32 v33, v0
	v_mov_b32_e32 v34, v0
	v_mov_b32_e32 v35, v0
	v_mov_b32_e32 v36, v0
	v_mov_b32_e32 v37, v0
	v_mov_b32_e32 v38, v0
	v_mov_b32_e32 v39, v0
	v_mov_b32_e32 v40, v0
	v_mov_b32_e32 v41, v0
	v_mov_b32_e32 v42, v0
	v_mov_b32_e32 v43, v0
	v_mov_b32_e32 v44, v0
	v_mov_b32_e32 v45, v0
	v_mov_b32_e32 v46, v0
	v_mov_b32_e32 v47, v0
	v_mov_b32_e32 v48, v0
	v_mov_b32_e32 v49, v0
	v_mov_b32_e32 v50, v0
	v_mov_b32_e32 v51, v0
	v_mov_b32_e32 v52, v0
	v_mov_b32_e32 v53, v0
	v_mov_b32_e32 v54, v0
	v_mov_b32_e32 v55, v0
	v_mov_b32_e32 v64, v0
	v_mov_b32_e32 v65, v0
	v_mov_b32_e32 v66, v0
	v_mov_b32_e32 v67, v0
	v_mov_b32_e32 v68, v0
	v_mov_b32_e32 v69, v0
	v_mov_b32_e32 v70, v0
	v_mov_b32_e32 v71, v0
	v_mov_b32_e32 v96, v0
	v_mov_b32_e32 v97, v0
	v_mov_b32_e32 v98, v0
	v_mov_b32_e32 v99, v0
	v_mov_b32_e32 v100, v0
	v_mov_b32_e32 v101, v0
	v_mov_b32_e32 v102, v0
	v_mov_b32_e32 v103, v0
	v_mov_b32_e32 v104, v0
	v_mov_b32_e32 v105, v0
	v_mov_b32_e32 v106, v0
	v_mov_b32_e32 v107, v0
	v_mov_b32_e32 v108, v0
	v_mov_b32_e32 v109, v0
	v_mov_b32_e32 v110, v0
	v_mov_b32_e32 v111, v0
	v_mov_b32_e32 v112, v0
	v_mov_b32_e32 v113, v0
	v_mov_b32_e32 v114, v0
	v_mov_b32_e32 v115, v0
	v_mov_b32_e32 v116, v0
	v_mov_b32_e32 v117, v0
	v_mov_b32_e32 v118, v0
	v_mov_b32_e32 v119, v0
	v_mov_b32_e32 v120, v0
	v_mov_b32_e32 v121, v0
	v_mov_b32_e32 v122, v0
	v_mov_b32_e32 v123, v0
	v_mov_b32_e32 v124, v0
	v_mov_b32_e32 v125, v0
	v_mov_b32_e32 v126, v0
	v_mov_b32_e32 v127, v0
	ds_read_b128 v[128:131], v171
	ds_read_b128 v[132:135], v171 offset:1024
	ds_read_b128 v[152:155], v171 offset:2048
	ds_read_b128 v[156:159], v171 offset:3072
	.p2alignl 6, 3212836864
.LBB0_1234:
	s_add_u32 s4, s46, 0xfff80080
	s_addc_u32 s5, s47, -1
	s_cmp_eq_u32 s64, 28
	s_cselect_b32 s5, s0, s5
	s_cselect_b32 s4, s1, s4
	s_cselect_b32 s59, s13, s37
	s_cselect_b32 s58, s15, s36
	s_add_i32 m0, s21, 0xc000
	ds_read_b128 v[160:163], v172
	ds_read_b128 v[164:167], v172 offset:1024
	ds_read_b128 v[174:177], v172 offset:2048
	ds_read_b128 v[178:181], v172 offset:3072
	ds_read_b128 v[182:185], v172 offset:4096
	ds_read_b128 v[186:189], v172 offset:5120
	ds_read_b128 v[190:193], v172 offset:6144
	ds_read_b128 v[194:197], v172 offset:7168
	global_load_lds_dwordx4 v144, s[46:47]
	s_add_i32 m0, s21, 0xe000
	s_nop 0
	global_load_lds_dwordx4 v146, s[46:47]
	s_waitcnt lgkmcnt(8)
	s_barrier
	s_waitcnt lgkmcnt(0)
	s_waitcnt lgkmcnt(0)
	v_mfma_f32_16x16x32_bf16 v[124:127], v[128:131], v[160:163], v[124:127]
	v_mfma_f32_16x16x32_bf16 v[120:123], v[152:155], v[160:163], v[120:123]
	v_mfma_f32_16x16x32_bf16 v[116:119], v[128:131], v[174:177], v[116:119]
	v_mfma_f32_16x16x32_bf16 v[112:115], v[152:155], v[174:177], v[112:115]
	v_mfma_f32_16x16x32_bf16 v[108:111], v[128:131], v[182:185], v[108:111]
	v_mfma_f32_16x16x32_bf16 v[104:107], v[152:155], v[182:185], v[104:107]
	v_mfma_f32_16x16x32_bf16 v[100:103], v[128:131], v[190:193], v[100:103]
	v_mfma_f32_16x16x32_bf16 v[96:99], v[152:155], v[190:193], v[96:99]
	v_mfma_f32_16x16x32_bf16 v[124:127], v[132:135], v[164:167], v[124:127]
	v_mfma_f32_16x16x32_bf16 v[120:123], v[156:159], v[164:167], v[120:123]
	v_mfma_f32_16x16x32_bf16 v[116:119], v[132:135], v[178:181], v[116:119]
	v_mfma_f32_16x16x32_bf16 v[112:115], v[156:159], v[178:181], v[112:115]
	v_mfma_f32_16x16x32_bf16 v[108:111], v[132:135], v[186:189], v[108:111]
	v_mfma_f32_16x16x32_bf16 v[104:107], v[156:159], v[186:189], v[104:107]
	v_mfma_f32_16x16x32_bf16 v[100:103], v[132:135], v[194:197], v[100:103]
	v_mfma_f32_16x16x32_bf16 v[96:99], v[156:159], v[194:197], v[96:99]
	s_barrier
	s_add_i32 s42, s60, s24
	s_add_u32 s98, s58, s10
	s_addc_u32 s99, s59, s11
	s_mov_b32 m0, s42
	ds_read_b128 v[198:201], v173
	ds_read_b128 v[202:205], v173 offset:1024
	ds_read_b128 v[206:209], v173 offset:2048
	ds_read_b128 v[210:213], v173 offset:3072
	global_load_lds_dwordx4 v140, s[58:59]
	s_add_i32 m0, s42, 0x2000
	s_nop 0
	global_load_lds_dwordx4 v136, s[58:59]
	s_barrier
	s_waitcnt lgkmcnt(0)
	s_waitcnt lgkmcnt(0)
	v_mfma_f32_16x16x32_bf16 v[68:71], v[198:201], v[160:163], v[68:71]
	v_mfma_f32_16x16x32_bf16 v[64:67], v[206:209], v[160:163], v[64:67]
	v_mfma_f32_16x16x32_bf16 v[52:55], v[198:201], v[174:177], v[52:55]
	v_mfma_f32_16x16x32_bf16 v[48:51], v[206:209], v[174:177], v[48:51]
	v_mfma_f32_16x16x32_bf16 v[44:47], v[198:201], v[182:185], v[44:47]
	v_mfma_f32_16x16x32_bf16 v[40:43], v[206:209], v[182:185], v[40:43]
	v_mfma_f32_16x16x32_bf16 v[36:39], v[198:201], v[190:193], v[36:39]
	v_mfma_f32_16x16x32_bf16 v[32:35], v[206:209], v[190:193], v[32:35]
	v_mfma_f32_16x16x32_bf16 v[68:71], v[202:205], v[164:167], v[68:71]
	v_mfma_f32_16x16x32_bf16 v[64:67], v[210:213], v[164:167], v[64:67]
	v_mfma_f32_16x16x32_bf16 v[52:55], v[202:205], v[178:181], v[52:55]
	v_mfma_f32_16x16x32_bf16 v[48:51], v[210:213], v[178:181], v[48:51]
	v_mfma_f32_16x16x32_bf16 v[44:47], v[202:205], v[186:189], v[44:47]
	v_mfma_f32_16x16x32_bf16 v[40:43], v[210:213], v[186:189], v[40:43]
	v_mfma_f32_16x16x32_bf16 v[36:39], v[202:205], v[194:197], v[36:39]
	v_mfma_f32_16x16x32_bf16 v[32:35], v[210:213], v[194:197], v[32:35]
	s_mov_b32 m0, s21
	s_add_u32 s100, s4, s10
	s_addc_u32 s101, s5, s11
	s_barrier
	s_waitcnt vmcnt(8)
	ds_read_b128 v[160:163], v172 offset:16384
	ds_read_b128 v[164:167], v172 offset:17408
	ds_read_b128 v[174:177], v172 offset:18432
	ds_read_b128 v[178:181], v172 offset:19456
	ds_read_b128 v[182:185], v172 offset:20480
	ds_read_b128 v[186:189], v172 offset:21504
	ds_read_b128 v[190:193], v172 offset:22528
	ds_read_b128 v[194:197], v172 offset:23552
	global_load_lds_dwordx4 v142, s[4:5]
	s_mov_b32 m0, s28
	s_nop 0
	global_load_lds_dwordx4 v138, s[4:5]
	s_barrier
	s_waitcnt lgkmcnt(0)
	s_waitcnt lgkmcnt(0)
	v_mfma_f32_16x16x32_bf16 v[92:95], v[128:131], v[160:163], v[92:95]
	v_mfma_f32_16x16x32_bf16 v[88:91], v[152:155], v[160:163], v[88:91]
	v_mfma_f32_16x16x32_bf16 v[84:87], v[128:131], v[174:177], v[84:87]
	v_mfma_f32_16x16x32_bf16 v[80:83], v[152:155], v[174:177], v[80:83]
	v_mfma_f32_16x16x32_bf16 v[76:79], v[128:131], v[182:185], v[76:79]
	v_mfma_f32_16x16x32_bf16 v[72:75], v[152:155], v[182:185], v[72:75]
	v_mfma_f32_16x16x32_bf16 v[60:63], v[128:131], v[190:193], v[60:63]
	v_mfma_f32_16x16x32_bf16 v[56:59], v[152:155], v[190:193], v[56:59]
	v_mfma_f32_16x16x32_bf16 v[92:95], v[132:135], v[164:167], v[92:95]
	v_mfma_f32_16x16x32_bf16 v[88:91], v[156:159], v[164:167], v[88:91]
	v_mfma_f32_16x16x32_bf16 v[84:87], v[132:135], v[178:181], v[84:87]
	v_mfma_f32_16x16x32_bf16 v[80:83], v[156:159], v[178:181], v[80:83]
	v_mfma_f32_16x16x32_bf16 v[76:79], v[132:135], v[186:189], v[76:79]
	v_mfma_f32_16x16x32_bf16 v[72:75], v[156:159], v[186:189], v[72:75]
	v_mfma_f32_16x16x32_bf16 v[60:63], v[132:135], v[194:197], v[60:63]
	v_mfma_f32_16x16x32_bf16 v[56:59], v[156:159], v[194:197], v[56:59]
	s_barrier
	s_add_u32 s42, s58, 0x80000
	s_addc_u32 s43, s59, 0
	s_add_i32 s44, s61, s24
	s_mov_b32 m0, s44
	s_nop 0
	global_load_lds_dwordx4 v140, s[42:43]
	s_add_i32 m0, s44, 0x2000
	s_nop 0
	global_load_lds_dwordx4 v136, s[42:43]
	v_add_u32_e32 v156, 0x18000, v169
	ds_read_b128 v[128:131], v156
	ds_read_b128 v[132:135], v156 offset:1024
	ds_read_b128 v[152:155], v156 offset:2048
	ds_read_b128 v[156:159], v156 offset:3072
	s_waitcnt vmcnt(6)
	s_barrier
	v_mfma_f32_16x16x32_bf16 v[28:31], v[198:201], v[160:163], v[28:31]
	v_mfma_f32_16x16x32_bf16 v[24:27], v[206:209], v[160:163], v[24:27]
	v_mfma_f32_16x16x32_bf16 v[20:23], v[198:201], v[174:177], v[20:23]
	v_mfma_f32_16x16x32_bf16 v[16:19], v[206:209], v[174:177], v[16:19]
	v_mfma_f32_16x16x32_bf16 v[12:15], v[198:201], v[182:185], v[12:15]
	v_mfma_f32_16x16x32_bf16 v[8:11], v[206:209], v[182:185], v[8:11]
	v_mfma_f32_16x16x32_bf16 v[4:7], v[198:201], v[190:193], v[4:7]
	v_mfma_f32_16x16x32_bf16 v[0:3], v[206:209], v[190:193], v[0:3]
	v_mfma_f32_16x16x32_bf16 v[28:31], v[202:205], v[164:167], v[28:31]
	v_mfma_f32_16x16x32_bf16 v[24:27], v[210:213], v[164:167], v[24:27]
	v_mfma_f32_16x16x32_bf16 v[20:23], v[202:205], v[178:181], v[20:23]
	v_mfma_f32_16x16x32_bf16 v[16:19], v[210:213], v[178:181], v[16:19]
	v_mfma_f32_16x16x32_bf16 v[12:15], v[202:205], v[186:189], v[12:15]
	v_mfma_f32_16x16x32_bf16 v[8:11], v[210:213], v[186:189], v[8:11]
	v_mfma_f32_16x16x32_bf16 v[4:7], v[202:205], v[194:197], v[4:7]
	v_mfma_f32_16x16x32_bf16 v[0:3], v[210:213], v[194:197], v[0:3]
	s_add_i32 s42, 0, 0x18000
	s_barrier
	s_add_u32 s4, s4, 0x80000
	s_addc_u32 s5, s5, 0
	s_mov_b32 m0, s29
	ds_read_b128 v[160:163], v172 offset:32768
	ds_read_b128 v[164:167], v172 offset:33792
	ds_read_b128 v[174:177], v172 offset:34816
	ds_read_b128 v[178:181], v172 offset:35840
	ds_read_b128 v[182:185], v172 offset:36864
	ds_read_b128 v[186:189], v172 offset:37888
	ds_read_b128 v[190:193], v172 offset:38912
	ds_read_b128 v[194:197], v172 offset:39936
	global_load_lds_dwordx4 v142, s[4:5]
	s_mov_b32 m0, s33
	s_nop 0
	global_load_lds_dwordx4 v138, s[4:5]
	s_waitcnt lgkmcnt(8)
	s_barrier
	s_waitcnt lgkmcnt(0)
	s_waitcnt lgkmcnt(0)
	v_mfma_f32_16x16x32_bf16 v[124:127], v[128:131], v[160:163], v[124:127]
	v_mfma_f32_16x16x32_bf16 v[120:123], v[152:155], v[160:163], v[120:123]
	v_mfma_f32_16x16x32_bf16 v[116:119], v[128:131], v[174:177], v[116:119]
	v_mfma_f32_16x16x32_bf16 v[112:115], v[152:155], v[174:177], v[112:115]
	v_mfma_f32_16x16x32_bf16 v[108:111], v[128:131], v[182:185], v[108:111]
	v_mfma_f32_16x16x32_bf16 v[104:107], v[152:155], v[182:185], v[104:107]
	v_mfma_f32_16x16x32_bf16 v[100:103], v[128:131], v[190:193], v[100:103]
	v_mfma_f32_16x16x32_bf16 v[96:99], v[152:155], v[190:193], v[96:99]
	v_mfma_f32_16x16x32_bf16 v[124:127], v[132:135], v[164:167], v[124:127]
	v_mfma_f32_16x16x32_bf16 v[120:123], v[156:159], v[164:167], v[120:123]
	v_mfma_f32_16x16x32_bf16 v[116:119], v[132:135], v[178:181], v[116:119]
	v_mfma_f32_16x16x32_bf16 v[112:115], v[156:159], v[178:181], v[112:115]
	v_mfma_f32_16x16x32_bf16 v[108:111], v[132:135], v[186:189], v[108:111]
	v_mfma_f32_16x16x32_bf16 v[104:107], v[156:159], v[186:189], v[104:107]
	v_mfma_f32_16x16x32_bf16 v[100:103], v[132:135], v[194:197], v[100:103]
	v_mfma_f32_16x16x32_bf16 v[96:99], v[156:159], v[194:197], v[96:99]
	s_barrier
	s_add_i32 s43, 0, 0x1c000
	s_add_i32 s4, s42, s24
	v_add_u32_e32 v210, s43, v169
	s_mov_b32 m0, s4
	ds_read_b128 v[198:201], v210
	ds_read_b128 v[202:205], v210 offset:1024
	ds_read_b128 v[206:209], v210 offset:2048
	ds_read_b128 v[210:213], v210 offset:3072
	global_load_lds_dwordx4 v140, s[98:99]
	s_add_i32 m0, s4, 0x2000
	s_nop 0
	global_load_lds_dwordx4 v136, s[98:99]
	s_barrier
	s_waitcnt lgkmcnt(0)
	s_waitcnt lgkmcnt(0)
	v_mfma_f32_16x16x32_bf16 v[68:71], v[198:201], v[160:163], v[68:71]
	v_mfma_f32_16x16x32_bf16 v[64:67], v[206:209], v[160:163], v[64:67]
	v_mfma_f32_16x16x32_bf16 v[52:55], v[198:201], v[174:177], v[52:55]
	v_mfma_f32_16x16x32_bf16 v[48:51], v[206:209], v[174:177], v[48:51]
	v_mfma_f32_16x16x32_bf16 v[44:47], v[198:201], v[182:185], v[44:47]
	v_mfma_f32_16x16x32_bf16 v[40:43], v[206:209], v[182:185], v[40:43]
	v_mfma_f32_16x16x32_bf16 v[36:39], v[198:201], v[190:193], v[36:39]
	v_mfma_f32_16x16x32_bf16 v[32:35], v[206:209], v[190:193], v[32:35]
	v_mfma_f32_16x16x32_bf16 v[68:71], v[202:205], v[164:167], v[68:71]
	v_mfma_f32_16x16x32_bf16 v[64:67], v[210:213], v[164:167], v[64:67]
	v_mfma_f32_16x16x32_bf16 v[52:55], v[202:205], v[178:181], v[52:55]
	v_mfma_f32_16x16x32_bf16 v[48:51], v[210:213], v[178:181], v[48:51]
	v_mfma_f32_16x16x32_bf16 v[44:47], v[202:205], v[186:189], v[44:47]
	v_mfma_f32_16x16x32_bf16 v[40:43], v[210:213], v[186:189], v[40:43]
	v_mfma_f32_16x16x32_bf16 v[36:39], v[202:205], v[194:197], v[36:39]
	v_mfma_f32_16x16x32_bf16 v[32:35], v[210:213], v[194:197], v[32:35]
	s_mov_b32 m0, s41
	s_barrier
	s_waitcnt vmcnt(8)
	ds_read_b128 v[160:163], v172 offset:49152
	ds_read_b128 v[164:167], v172 offset:50176
	ds_read_b128 v[174:177], v172 offset:51200
	ds_read_b128 v[178:181], v172 offset:52224
	ds_read_b128 v[182:185], v172 offset:53248
	ds_read_b128 v[186:189], v172 offset:54272
	ds_read_b128 v[190:193], v172 offset:55296
	ds_read_b128 v[194:197], v172 offset:56320
	global_load_lds_dwordx4 v142, s[100:101]
	s_mov_b32 m0, s53
	s_nop 0
	global_load_lds_dwordx4 v138, s[100:101]
	s_barrier
	s_waitcnt lgkmcnt(0)
	s_waitcnt lgkmcnt(0)
	v_mfma_f32_16x16x32_bf16 v[92:95], v[128:131], v[160:163], v[92:95]
	v_mfma_f32_16x16x32_bf16 v[88:91], v[152:155], v[160:163], v[88:91]
	v_mfma_f32_16x16x32_bf16 v[84:87], v[128:131], v[174:177], v[84:87]
	v_mfma_f32_16x16x32_bf16 v[80:83], v[152:155], v[174:177], v[80:83]
	v_mfma_f32_16x16x32_bf16 v[76:79], v[128:131], v[182:185], v[76:79]
	v_mfma_f32_16x16x32_bf16 v[72:75], v[152:155], v[182:185], v[72:75]
	v_mfma_f32_16x16x32_bf16 v[60:63], v[128:131], v[190:193], v[60:63]
	v_mfma_f32_16x16x32_bf16 v[56:59], v[152:155], v[190:193], v[56:59]
	v_mfma_f32_16x16x32_bf16 v[92:95], v[132:135], v[164:167], v[92:95]
	v_mfma_f32_16x16x32_bf16 v[88:91], v[156:159], v[164:167], v[88:91]
	v_mfma_f32_16x16x32_bf16 v[84:87], v[132:135], v[178:181], v[84:87]
	v_mfma_f32_16x16x32_bf16 v[80:83], v[156:159], v[178:181], v[80:83]
	v_mfma_f32_16x16x32_bf16 v[76:79], v[132:135], v[186:189], v[76:79]
	v_mfma_f32_16x16x32_bf16 v[72:75], v[156:159], v[186:189], v[72:75]
	v_mfma_f32_16x16x32_bf16 v[60:63], v[132:135], v[194:197], v[60:63]
	v_mfma_f32_16x16x32_bf16 v[56:59], v[156:159], v[194:197], v[56:59]
	s_barrier
	s_add_u32 s4, s58, 0x80080
	s_addc_u32 s5, s59, 0
	s_add_i32 s42, s43, s24
	s_mov_b32 m0, s42
	s_nop 0
	global_load_lds_dwordx4 v140, s[4:5]
	s_add_i32 m0, s42, 0x2000
	s_nop 0
	global_load_lds_dwordx4 v136, s[4:5]
	ds_read_b128 v[128:131], v171
	ds_read_b128 v[132:135], v171 offset:1024
	ds_read_b128 v[152:155], v171 offset:2048
	ds_read_b128 v[156:159], v171 offset:3072
	s_waitcnt vmcnt(6)
	s_barrier
	v_mfma_f32_16x16x32_bf16 v[28:31], v[198:201], v[160:163], v[28:31]
	v_mfma_f32_16x16x32_bf16 v[24:27], v[206:209], v[160:163], v[24:27]
	v_mfma_f32_16x16x32_bf16 v[20:23], v[198:201], v[174:177], v[20:23]
	v_mfma_f32_16x16x32_bf16 v[16:19], v[206:209], v[174:177], v[16:19]
	v_mfma_f32_16x16x32_bf16 v[12:15], v[198:201], v[182:185], v[12:15]
	v_mfma_f32_16x16x32_bf16 v[8:11], v[206:209], v[182:185], v[8:11]
	v_mfma_f32_16x16x32_bf16 v[4:7], v[198:201], v[190:193], v[4:7]
	v_mfma_f32_16x16x32_bf16 v[0:3], v[206:209], v[190:193], v[0:3]
	v_mfma_f32_16x16x32_bf16 v[28:31], v[202:205], v[164:167], v[28:31]
	v_mfma_f32_16x16x32_bf16 v[24:27], v[210:213], v[164:167], v[24:27]
	v_mfma_f32_16x16x32_bf16 v[20:23], v[202:205], v[178:181], v[20:23]
	v_mfma_f32_16x16x32_bf16 v[16:19], v[210:213], v[178:181], v[16:19]
	v_mfma_f32_16x16x32_bf16 v[12:15], v[202:205], v[186:189], v[12:15]
	v_mfma_f32_16x16x32_bf16 v[8:11], v[210:213], v[186:189], v[8:11]
	v_mfma_f32_16x16x32_bf16 v[4:7], v[202:205], v[194:197], v[4:7]
	v_mfma_f32_16x16x32_bf16 v[0:3], v[210:213], v[194:197], v[0:3]
	s_add_i32 s64, s64, 2
	s_add_u32 s46, s46, 0x100
	s_addc_u32 s47, s47, 0
	s_add_u32 s36, s36, 0x100
	s_addc_u32 s37, s37, 0
	s_cmp_gt_u32 s64, 29
	s_barrier
	s_cbranch_scc0 .LBB0_1234
	v_lshl_or_b32 v152, s63, 8, v170
	v_ashrrev_i32_e32 v153, 31, v152
	v_lshl_add_u64 v[164:165], v[152:153], 2, s[8:9]
	flat_load_dwordx4 v[132:135], v[164:165]
	flat_load_dwordx4 v[128:131], v[164:165] offset:16
	v_lshl_add_u32 v182, s20, 8, v168
	v_mov_b64_e32 v[166:167], s[48:49]
	v_add_u32_e32 v159, 0x80, v182
	v_mad_i64_i32 v[154:155], s[0:1], v182, s62, v[166:167]
	v_or_b32_e32 v156, 16, v182
	v_or_b32_e32 v157, 32, v182
	v_or_b32_e32 v158, 48, v182
	v_lshlrev_b64 v[174:175], 1, v[152:153]
	v_mad_i64_i32 v[178:179], s[0:1], v159, s62, v[166:167]
	v_add_u32_e32 v160, 0x90, v182
	v_mad_i64_i32 v[152:153], s[0:1], v156, s62, v[166:167]
	v_mad_i64_i32 v[156:157], s[0:1], v157, s62, v[166:167]
	v_mad_i64_i32 v[176:177], s[0:1], v158, s62, v[166:167]
	v_lshl_add_u64 v[162:163], v[154:155], 0, v[174:175]
	v_lshl_add_u64 v[154:155], v[178:179], 0, v[174:175]
	v_mad_i64_i32 v[180:181], s[0:1], v160, s62, v[166:167]
	v_lshl_add_u64 v[160:161], v[152:153], 0, v[174:175]
	v_lshl_add_u64 v[158:159], v[156:157], 0, v[174:175]
	v_lshl_add_u64 v[156:157], v[176:177], 0, v[174:175]
	v_lshl_add_u64 v[152:153], v[180:181], 0, v[174:175]
	s_and_b64 vcc, exec, s[6:7]
	s_mov_b32 s63, s12
	s_mov_b32 s20, s14
	s_mov_b64 s[58:59], s[18:19]
	s_mov_b64 s[36:37], s[16:17]
	s_waitcnt vmcnt(0) lgkmcnt(0)
	v_pk_add_f32 v[124:125], v[124:125], v[132:133]
	v_pk_add_f32 v[178:179], v[72:73], v[128:129]
	s_nop 1
	v_cvt_pk_bf16_f32 v72, v124, v125
	v_pk_add_f32 v[126:127], v[126:127], v[134:135]
	v_pk_add_f32 v[122:123], v[122:123], v[130:131]
	v_pk_add_f32 v[120:121], v[120:121], v[128:129]
	v_pk_add_f32 v[116:117], v[116:117], v[132:133]
	v_pk_add_f32 v[176:177], v[74:75], v[130:131]
	s_nop 1
	v_cvt_pk_bf16_f32 v73, v126, v127
	s_nop 1
	v_cvt_pk_bf16_f32 v74, v120, v121
	s_nop 1
	v_cvt_pk_bf16_f32 v75, v122, v123
	global_store_dwordx4 v[162:163], v[72:75], off
	v_pk_add_f32 v[118:119], v[118:119], v[134:135]
	v_pk_add_f32 v[114:115], v[114:115], v[130:131]
	s_nop 1
	v_cvt_pk_bf16_f32 v72, v116, v117
	v_pk_add_f32 v[112:113], v[112:113], v[128:129]
	v_pk_add_f32 v[108:109], v[108:109], v[132:133]
	s_nop 1
	v_cvt_pk_bf16_f32 v73, v118, v119
	s_nop 1
	v_cvt_pk_bf16_f32 v74, v112, v113
	s_nop 1
	v_cvt_pk_bf16_f32 v75, v114, v115
	global_store_dwordx4 v[160:161], v[72:75], off
	v_pk_add_f32 v[110:111], v[110:111], v[134:135]
	v_pk_add_f32 v[106:107], v[106:107], v[130:131]
	s_nop 1
	v_cvt_pk_bf16_f32 v72, v108, v109
	v_pk_add_f32 v[104:105], v[104:105], v[128:129]
	v_pk_add_f32 v[100:101], v[100:101], v[132:133]
	s_nop 1
	v_cvt_pk_bf16_f32 v73, v110, v111
	s_nop 1
	v_cvt_pk_bf16_f32 v74, v104, v105
	s_nop 1
	v_cvt_pk_bf16_f32 v75, v106, v107
	global_store_dwordx4 v[158:159], v[72:75], off
	v_pk_add_f32 v[102:103], v[102:103], v[134:135]
	v_pk_add_f32 v[98:99], v[98:99], v[130:131]
	s_nop 1
	v_cvt_pk_bf16_f32 v72, v100, v101
	v_pk_add_f32 v[96:97], v[96:97], v[128:129]
	v_pk_add_f32 v[92:93], v[92:93], v[132:133]
	s_nop 1
	v_cvt_pk_bf16_f32 v73, v102, v103
	s_nop 1
	v_cvt_pk_bf16_f32 v74, v96, v97
	s_nop 1
	v_cvt_pk_bf16_f32 v75, v98, v99
	global_store_dwordx4 v[156:157], v[72:75], off
	v_pk_add_f32 v[94:95], v[94:95], v[134:135]
	v_pk_add_f32 v[90:91], v[90:91], v[130:131]
	s_nop 1
	v_cvt_pk_bf16_f32 v72, v92, v93
	v_pk_add_f32 v[88:89], v[88:89], v[128:129]
	v_pk_add_f32 v[84:85], v[84:85], v[132:133]
	v_pk_add_f32 v[76:77], v[76:77], v[132:133]
	s_nop 1
	v_cvt_pk_bf16_f32 v73, v94, v95
	s_nop 1
	v_cvt_pk_bf16_f32 v74, v88, v89
	s_nop 1
	v_cvt_pk_bf16_f32 v75, v90, v91
	global_store_dwordx4 v[154:155], v[72:75], off
	v_pk_add_f32 v[86:87], v[86:87], v[134:135]
	v_pk_add_f32 v[82:83], v[82:83], v[130:131]
	s_nop 1
	v_cvt_pk_bf16_f32 v72, v84, v85
	v_pk_add_f32 v[80:81], v[80:81], v[128:129]
	s_nop 1
	v_cvt_pk_bf16_f32 v73, v86, v87
	v_pk_add_f32 v[78:79], v[78:79], v[134:135]
	s_nop 1
	v_cvt_pk_bf16_f32 v74, v80, v81
	s_nop 1
	v_cvt_pk_bf16_f32 v75, v82, v83
	global_store_dwordx4 v[152:153], v[72:75], off
	v_pk_add_f32 v[60:61], v[60:61], v[132:133]
	v_pk_add_f32 v[62:63], v[62:63], v[134:135]
	s_nop 1
	v_cvt_pk_bf16_f32 v72, v76, v77
	v_add_u32_e32 v76, 0xa0, v182
	v_mad_i64_i32 v[76:77], s[0:1], v76, s62, v[166:167]
	s_nop 1
	v_cvt_pk_bf16_f32 v73, v78, v79
	v_lshl_add_u64 v[76:77], v[76:77], 0, v[174:175]
	s_nop 1
	v_cvt_pk_bf16_f32 v74, v178, v179
	s_nop 1
	v_cvt_pk_bf16_f32 v75, v176, v177
	global_store_dwordx4 v[76:77], v[72:75], off
	s_nop 1
	v_pk_add_f32 v[72:73], v[58:59], v[130:131]
	v_pk_add_f32 v[58:59], v[56:57], v[128:129]
	s_nop 1
	v_cvt_pk_bf16_f32 v56, v60, v61
	v_add_u32_e32 v60, 0xb0, v182
	v_mad_i64_i32 v[60:61], s[0:1], v60, s62, v[166:167]
	s_nop 1
	v_cvt_pk_bf16_f32 v57, v62, v63
	s_nop 1
	v_cvt_pk_bf16_f32 v58, v58, v59
	s_nop 1
	v_cvt_pk_bf16_f32 v59, v72, v73
	v_lshl_add_u64 v[72:73], v[60:61], 0, v[174:175]
	global_store_dwordx4 v[72:73], v[56:59], off
	flat_load_dwordx4 v[56:59], v[164:165] offset:512
	s_nop 0
	flat_load_dwordx4 v[60:63], v[164:165] offset:528
	s_waitcnt vmcnt(0) lgkmcnt(0)
	v_pk_add_f32 v[70:71], v[70:71], v[58:59]
	v_pk_add_f32 v[68:69], v[68:69], v[56:57]
	v_pk_add_f32 v[66:67], v[66:67], v[62:63]
	v_pk_add_f32 v[64:65], v[64:65], v[60:61]
	v_pk_add_f32 v[54:55], v[54:55], v[58:59]
	v_pk_add_f32 v[52:53], v[52:53], v[56:57]
	v_pk_add_f32 v[46:47], v[46:47], v[58:59]
	v_pk_add_f32 v[44:45], v[44:45], v[56:57]
	v_pk_add_f32 v[38:39], v[38:39], v[58:59]
	v_pk_add_f32 v[36:37], v[36:37], v[56:57]
	v_pk_add_f32 v[30:31], v[30:31], v[58:59]
	v_pk_add_f32 v[28:29], v[28:29], v[56:57]
	v_pk_add_f32 v[22:23], v[22:23], v[58:59]
	v_pk_add_f32 v[20:21], v[20:21], v[56:57]
	v_pk_add_f32 v[14:15], v[14:15], v[58:59]
	v_pk_add_f32 v[12:13], v[12:13], v[56:57]
	v_pk_add_f32 v[6:7], v[6:7], v[58:59]
	v_pk_add_f32 v[4:5], v[4:5], v[56:57]
	v_pk_add_f32 v[56:57], v[2:3], v[62:63]
	v_pk_add_f32 v[58:59], v[0:1], v[60:61]
	s_nop 1
	v_cvt_pk_bf16_f32 v0, v68, v69
	s_nop 1
	v_cvt_pk_bf16_f32 v1, v70, v71
	s_nop 1
	v_cvt_pk_bf16_f32 v2, v64, v65
	s_nop 1
	v_cvt_pk_bf16_f32 v3, v66, v67
	v_pk_add_f32 v[50:51], v[50:51], v[62:63]
	v_pk_add_f32 v[48:49], v[48:49], v[60:61]
	global_store_dwordx4 v[162:163], v[0:3], off offset:256
	v_pk_add_f32 v[42:43], v[42:43], v[62:63]
	v_pk_add_f32 v[40:41], v[40:41], v[60:61]
	s_nop 1
	v_cvt_pk_bf16_f32 v0, v52, v53
	s_nop 1
	v_cvt_pk_bf16_f32 v1, v54, v55
	s_nop 1
	v_cvt_pk_bf16_f32 v2, v48, v49
	s_nop 1
	v_cvt_pk_bf16_f32 v3, v50, v51
	global_store_dwordx4 v[160:161], v[0:3], off offset:256
	v_pk_add_f32 v[34:35], v[34:35], v[62:63]
	v_pk_add_f32 v[32:33], v[32:33], v[60:61]
	s_nop 1
	v_cvt_pk_bf16_f32 v0, v44, v45
	s_nop 1
	v_cvt_pk_bf16_f32 v1, v46, v47
	s_nop 1
	v_cvt_pk_bf16_f32 v2, v40, v41
	s_nop 1
	v_cvt_pk_bf16_f32 v3, v42, v43
	global_store_dwordx4 v[158:159], v[0:3], off offset:256
	v_pk_add_f32 v[26:27], v[26:27], v[62:63]
	v_pk_add_f32 v[24:25], v[24:25], v[60:61]
	s_nop 1
	v_cvt_pk_bf16_f32 v0, v36, v37
	s_nop 1
	v_cvt_pk_bf16_f32 v1, v38, v39
	s_nop 1
	v_cvt_pk_bf16_f32 v2, v32, v33
	s_nop 1
	v_cvt_pk_bf16_f32 v3, v34, v35
	global_store_dwordx4 v[156:157], v[0:3], off offset:256
	v_pk_add_f32 v[18:19], v[18:19], v[62:63]
	v_pk_add_f32 v[16:17], v[16:17], v[60:61]
	s_nop 1
	v_cvt_pk_bf16_f32 v0, v28, v29
	s_nop 1
	v_cvt_pk_bf16_f32 v1, v30, v31
	s_nop 1
	v_cvt_pk_bf16_f32 v2, v24, v25
	s_nop 1
	v_cvt_pk_bf16_f32 v3, v26, v27
	global_store_dwordx4 v[154:155], v[0:3], off offset:256
	v_pk_add_f32 v[10:11], v[10:11], v[62:63]
	v_pk_add_f32 v[8:9], v[8:9], v[60:61]
	s_nop 1
	v_cvt_pk_bf16_f32 v0, v20, v21
	s_nop 1
	v_cvt_pk_bf16_f32 v1, v22, v23
	s_nop 1
	v_cvt_pk_bf16_f32 v2, v16, v17
	s_nop 1
	v_cvt_pk_bf16_f32 v3, v18, v19
	global_store_dwordx4 v[152:153], v[0:3], off offset:256
	s_nop 1
	s_nop 1
	v_cvt_pk_bf16_f32 v0, v12, v13
	s_nop 1
	v_cvt_pk_bf16_f32 v1, v14, v15
	s_nop 1
	v_cvt_pk_bf16_f32 v2, v8, v9
	s_nop 1
	v_cvt_pk_bf16_f32 v3, v10, v11
	global_store_dwordx4 v[76:77], v[0:3], off offset:256
	s_nop 1
	s_nop 1
	v_cvt_pk_bf16_f32 v0, v4, v5
	s_nop 1
	v_cvt_pk_bf16_f32 v1, v6, v7
	s_nop 1
	v_cvt_pk_bf16_f32 v2, v58, v59
	s_nop 1
	v_cvt_pk_bf16_f32 v3, v56, v57
	global_store_dwordx4 v[72:73], v[0:3], off offset:256
	s_cbranch_vccz .LBB0_1231
	s_waitcnt vmcnt(0)
	s_cmpk_gt_u32 s23, 0xff
	s_cbranch_scc1 .LBB0_1238
	s_barrier

.LBB0_1532:
	s_ashr_i32 s61, s60, 31
	v_cmp_lt_i64_e32 vcc, s[0:1], v[146:147]
	s_lshl_b64 s[0:1], s[60:61], 20
	s_add_u32 s62, s38, s0
	s_addc_u32 s63, s39, s1
	s_and_b64 s[0:1], vcc, exec
	s_cselect_b32 s0, s63, s9
	s_cselect_b32 s1, s62, s8
	s_ashr_i32 s59, s58, 31
	s_lshl_b64 s[4:5], s[58:59], 20
	v_readlane_b32 s42, v255, 26
	v_readlane_b32 s43, v255, 27
	s_add_u32 s64, s42, s4
	s_addc_u32 s65, s43, s5
	s_and_b64 s[4:5], vcc, exec
	s_cselect_b32 s59, s65, s69
	s_cselect_b32 s61, s64, s68
	s_add_u32 s76, s68, 0x100
	v_mov_b32_e32 v0, 0
	s_addc_u32 s77, s69, 0
	s_mov_b32 s78, -2
	v_mov_b32_e32 v1, v0
	v_mov_b32_e32 v2, v0
	v_mov_b32_e32 v3, v0
	v_mov_b32_e32 v32, v0
	v_mov_b32_e32 v33, v0
	v_mov_b32_e32 v34, v0
	v_mov_b32_e32 v35, v0
	v_mov_b32_e32 v4, v0
	v_mov_b32_e32 v5, v0
	v_mov_b32_e32 v6, v0
	v_mov_b32_e32 v7, v0
	v_mov_b32_e32 v36, v0
	v_mov_b32_e32 v37, v0
	v_mov_b32_e32 v38, v0
	v_mov_b32_e32 v39, v0
	v_mov_b32_e32 v8, v0
	v_mov_b32_e32 v9, v0
	v_mov_b32_e32 v10, v0
	v_mov_b32_e32 v11, v0
	v_mov_b32_e32 v40, v0
	v_mov_b32_e32 v41, v0
	v_mov_b32_e32 v42, v0
	v_mov_b32_e32 v43, v0
	v_mov_b32_e32 v12, v0
	v_mov_b32_e32 v13, v0
	v_mov_b32_e32 v14, v0
	v_mov_b32_e32 v15, v0
	v_mov_b32_e32 v44, v0
	v_mov_b32_e32 v45, v0
	v_mov_b32_e32 v46, v0
	v_mov_b32_e32 v47, v0
	v_mov_b32_e32 v64, v0
	v_mov_b32_e32 v65, v0
	v_mov_b32_e32 v66, v0
	v_mov_b32_e32 v67, v0
	v_mov_b32_e32 v96, v0
	v_mov_b32_e32 v97, v0
	v_mov_b32_e32 v98, v0
	v_mov_b32_e32 v99, v0
	v_mov_b32_e32 v68, v0
	v_mov_b32_e32 v69, v0
	v_mov_b32_e32 v70, v0
	v_mov_b32_e32 v71, v0
	v_mov_b32_e32 v100, v0
	v_mov_b32_e32 v101, v0
	v_mov_b32_e32 v102, v0
	v_mov_b32_e32 v103, v0
	v_mov_b32_e32 v72, v0
	v_mov_b32_e32 v73, v0
	v_mov_b32_e32 v74, v0
	v_mov_b32_e32 v75, v0
	v_mov_b32_e32 v104, v0
	v_mov_b32_e32 v105, v0
	v_mov_b32_e32 v106, v0
	v_mov_b32_e32 v107, v0
	v_mov_b32_e32 v76, v0
	v_mov_b32_e32 v77, v0
	v_mov_b32_e32 v78, v0
	v_mov_b32_e32 v79, v0
	v_mov_b32_e32 v108, v0
	v_mov_b32_e32 v109, v0
	v_mov_b32_e32 v110, v0
	v_mov_b32_e32 v111, v0
	v_mov_b32_e32 v16, v0
	v_mov_b32_e32 v17, v0
	v_mov_b32_e32 v18, v0
	v_mov_b32_e32 v19, v0
	v_mov_b32_e32 v48, v0
	v_mov_b32_e32 v49, v0
	v_mov_b32_e32 v50, v0
	v_mov_b32_e32 v51, v0
	v_mov_b32_e32 v20, v0
	v_mov_b32_e32 v21, v0
	v_mov_b32_e32 v22, v0
	v_mov_b32_e32 v23, v0
	v_mov_b32_e32 v52, v0
	v_mov_b32_e32 v53, v0
	v_mov_b32_e32 v54, v0
	v_mov_b32_e32 v55, v0
	v_mov_b32_e32 v24, v0
	v_mov_b32_e32 v25, v0
	v_mov_b32_e32 v26, v0
	v_mov_b32_e32 v27, v0
	v_mov_b32_e32 v56, v0
	v_mov_b32_e32 v57, v0
	v_mov_b32_e32 v58, v0
	v_mov_b32_e32 v59, v0
	v_mov_b32_e32 v28, v0
	v_mov_b32_e32 v29, v0
	v_mov_b32_e32 v30, v0
	v_mov_b32_e32 v31, v0
	v_mov_b32_e32 v60, v0
	v_mov_b32_e32 v61, v0
	v_mov_b32_e32 v62, v0
	v_mov_b32_e32 v63, v0
	v_mov_b32_e32 v80, v0
	v_mov_b32_e32 v81, v0
	v_mov_b32_e32 v82, v0
	v_mov_b32_e32 v83, v0
	v_mov_b32_e32 v112, v0
	v_mov_b32_e32 v113, v0
	v_mov_b32_e32 v114, v0
	v_mov_b32_e32 v115, v0
	v_mov_b32_e32 v84, v0
	v_mov_b32_e32 v85, v0
	v_mov_b32_e32 v86, v0
	v_mov_b32_e32 v87, v0
	v_mov_b32_e32 v116, v0
	v_mov_b32_e32 v117, v0
	v_mov_b32_e32 v118, v0
	v_mov_b32_e32 v119, v0
	v_mov_b32_e32 v88, v0
	v_mov_b32_e32 v89, v0
	v_mov_b32_e32 v90, v0
	v_mov_b32_e32 v91, v0
	v_mov_b32_e32 v120, v0
	v_mov_b32_e32 v121, v0
	v_mov_b32_e32 v122, v0
	v_mov_b32_e32 v123, v0
	v_mov_b32_e32 v92, v0
	v_mov_b32_e32 v93, v0
	v_mov_b32_e32 v94, v0
	v_mov_b32_e32 v95, v0
	v_mov_b32_e32 v124, v0
	v_mov_b32_e32 v125, v0
	v_mov_b32_e32 v126, v0
	v_mov_b32_e32 v127, v0
	ds_read_b128 v[128:131], v165
	ds_read_b128 v[132:135], v165 offset:1024
	ds_read_b128 v[150:153], v165 offset:2048
	ds_read_b128 v[154:157], v165 offset:3072
	.p2alignl 6, 3212836864
.LBB0_1533:
	s_add_u32 s68, s8, 0x100
	s_addc_u32 s69, s9, 0
	s_cmp_eq_u32 s78, 28
	s_cselect_b32 s5, s0, s69
	s_cselect_b32 s4, s1, s68
	s_cselect_b32 s71, s59, s77
	s_cselect_b32 s70, s61, s76
	s_add_i32 m0, s25, 0xc000
	ds_read_b128 v[158:161], v166
	ds_read_b128 v[168:171], v166 offset:1024
	ds_read_b128 v[172:175], v166 offset:2048
	ds_read_b128 v[176:179], v166 offset:3072
	ds_read_b128 v[180:183], v166 offset:4096
	ds_read_b128 v[184:187], v166 offset:5120
	ds_read_b128 v[188:191], v166 offset:6144
	ds_read_b128 v[192:195], v166 offset:7168
	global_load_lds_dwordx4 v142, s[8:9]
	s_add_i32 m0, s25, 0xe000
	s_nop 0
	global_load_lds_dwordx4 v144, s[8:9]
	s_waitcnt lgkmcnt(8)
	s_barrier
	s_waitcnt lgkmcnt(0)
	s_waitcnt lgkmcnt(0)
	v_mfma_f32_16x16x32_bf16 v[124:127], v[128:131], v[158:161], v[124:127]
	v_mfma_f32_16x16x32_bf16 v[92:95], v[150:153], v[158:161], v[92:95]
	v_mfma_f32_16x16x32_bf16 v[120:123], v[128:131], v[172:175], v[120:123]
	v_mfma_f32_16x16x32_bf16 v[88:91], v[150:153], v[172:175], v[88:91]
	v_mfma_f32_16x16x32_bf16 v[116:119], v[128:131], v[180:183], v[116:119]
	v_mfma_f32_16x16x32_bf16 v[84:87], v[150:153], v[180:183], v[84:87]
	v_mfma_f32_16x16x32_bf16 v[112:115], v[128:131], v[188:191], v[112:115]
	v_mfma_f32_16x16x32_bf16 v[80:83], v[150:153], v[188:191], v[80:83]
	v_mfma_f32_16x16x32_bf16 v[124:127], v[132:135], v[168:171], v[124:127]
	v_mfma_f32_16x16x32_bf16 v[92:95], v[154:157], v[168:171], v[92:95]
	v_mfma_f32_16x16x32_bf16 v[120:123], v[132:135], v[176:179], v[120:123]
	v_mfma_f32_16x16x32_bf16 v[88:91], v[154:157], v[176:179], v[88:91]
	v_mfma_f32_16x16x32_bf16 v[116:119], v[132:135], v[184:187], v[116:119]
	v_mfma_f32_16x16x32_bf16 v[84:87], v[154:157], v[184:187], v[84:87]
	v_mfma_f32_16x16x32_bf16 v[112:115], v[132:135], v[192:195], v[112:115]
	v_mfma_f32_16x16x32_bf16 v[80:83], v[154:157], v[192:195], v[80:83]
	s_barrier
	s_add_i32 s8, s41, s24
	s_add_u32 s98, s70, s16
	s_addc_u32 s99, s71, s17
	s_mov_b32 m0, s8
	ds_read_b128 v[196:199], v167
	ds_read_b128 v[200:203], v167 offset:1024
	ds_read_b128 v[204:207], v167 offset:2048
	ds_read_b128 v[208:211], v167 offset:3072
	global_load_lds_dwordx4 v140, s[70:71]
	s_add_i32 m0, s8, 0x2000
	s_nop 0
	global_load_lds_dwordx4 v138, s[70:71]
	s_barrier
	s_waitcnt lgkmcnt(0)
	s_waitcnt lgkmcnt(0)
	v_mfma_f32_16x16x32_bf16 v[60:63], v[196:199], v[158:161], v[60:63]
	v_mfma_f32_16x16x32_bf16 v[28:31], v[204:207], v[158:161], v[28:31]
	v_mfma_f32_16x16x32_bf16 v[56:59], v[196:199], v[172:175], v[56:59]
	v_mfma_f32_16x16x32_bf16 v[24:27], v[204:207], v[172:175], v[24:27]
	v_mfma_f32_16x16x32_bf16 v[52:55], v[196:199], v[180:183], v[52:55]
	v_mfma_f32_16x16x32_bf16 v[20:23], v[204:207], v[180:183], v[20:23]
	v_mfma_f32_16x16x32_bf16 v[48:51], v[196:199], v[188:191], v[48:51]
	v_mfma_f32_16x16x32_bf16 v[16:19], v[204:207], v[188:191], v[16:19]
	v_mfma_f32_16x16x32_bf16 v[60:63], v[200:203], v[168:171], v[60:63]
	v_mfma_f32_16x16x32_bf16 v[28:31], v[208:211], v[168:171], v[28:31]
	v_mfma_f32_16x16x32_bf16 v[56:59], v[200:203], v[176:179], v[56:59]
	v_mfma_f32_16x16x32_bf16 v[24:27], v[208:211], v[176:179], v[24:27]
	v_mfma_f32_16x16x32_bf16 v[52:55], v[200:203], v[184:187], v[52:55]
	v_mfma_f32_16x16x32_bf16 v[20:23], v[208:211], v[184:187], v[20:23]
	v_mfma_f32_16x16x32_bf16 v[48:51], v[200:203], v[192:195], v[48:51]
	v_mfma_f32_16x16x32_bf16 v[16:19], v[208:211], v[192:195], v[16:19]
	s_mov_b32 m0, s25
	s_add_u32 s100, s4, s16
	s_addc_u32 s101, s5, s17
	s_barrier
	s_waitcnt vmcnt(8)
	ds_read_b128 v[158:161], v166 offset:16384
	ds_read_b128 v[168:171], v166 offset:17408
	ds_read_b128 v[172:175], v166 offset:18432
	ds_read_b128 v[176:179], v166 offset:19456
	ds_read_b128 v[180:183], v166 offset:20480
	ds_read_b128 v[184:187], v166 offset:21504
	ds_read_b128 v[188:191], v166 offset:22528
	ds_read_b128 v[192:195], v166 offset:23552
	global_load_lds_dwordx4 v140, s[4:5]
	s_mov_b32 m0, s28
	s_nop 0
	global_load_lds_dwordx4 v138, s[4:5]
	s_barrier
	s_waitcnt lgkmcnt(0)
	s_waitcnt lgkmcnt(0)
	v_mfma_f32_16x16x32_bf16 v[108:111], v[128:131], v[158:161], v[108:111]
	v_mfma_f32_16x16x32_bf16 v[76:79], v[150:153], v[158:161], v[76:79]
	v_mfma_f32_16x16x32_bf16 v[104:107], v[128:131], v[172:175], v[104:107]
	v_mfma_f32_16x16x32_bf16 v[72:75], v[150:153], v[172:175], v[72:75]
	v_mfma_f32_16x16x32_bf16 v[100:103], v[128:131], v[180:183], v[100:103]
	v_mfma_f32_16x16x32_bf16 v[68:71], v[150:153], v[180:183], v[68:71]
	v_mfma_f32_16x16x32_bf16 v[96:99], v[128:131], v[188:191], v[96:99]
	v_mfma_f32_16x16x32_bf16 v[64:67], v[150:153], v[188:191], v[64:67]
	v_mfma_f32_16x16x32_bf16 v[108:111], v[132:135], v[168:171], v[108:111]
	v_mfma_f32_16x16x32_bf16 v[76:79], v[154:157], v[168:171], v[76:79]
	v_mfma_f32_16x16x32_bf16 v[104:107], v[132:135], v[176:179], v[104:107]
	v_mfma_f32_16x16x32_bf16 v[72:75], v[154:157], v[176:179], v[72:75]
	v_mfma_f32_16x16x32_bf16 v[100:103], v[132:135], v[184:187], v[100:103]
	v_mfma_f32_16x16x32_bf16 v[68:71], v[154:157], v[184:187], v[68:71]
	v_mfma_f32_16x16x32_bf16 v[96:99], v[132:135], v[192:195], v[96:99]
	v_mfma_f32_16x16x32_bf16 v[64:67], v[154:157], v[192:195], v[64:67]
	s_barrier
	s_add_u32 s8, s70, 0x80000
	s_addc_u32 s9, s71, 0
	s_add_i32 s42, s53, s24
	s_mov_b32 m0, s42
	s_nop 0
	global_load_lds_dwordx4 v140, s[8:9]
	s_add_i32 m0, s42, 0x2000
	s_nop 0
	global_load_lds_dwordx4 v138, s[8:9]
	v_add_u32_e32 v154, 0x18000, v163
	ds_read_b128 v[128:131], v154
	ds_read_b128 v[132:135], v154 offset:1024
	ds_read_b128 v[150:153], v154 offset:2048
	ds_read_b128 v[154:157], v154 offset:3072
	s_waitcnt vmcnt(6)
	s_barrier
	v_mfma_f32_16x16x32_bf16 v[44:47], v[196:199], v[158:161], v[44:47]
	v_mfma_f32_16x16x32_bf16 v[12:15], v[204:207], v[158:161], v[12:15]
	v_mfma_f32_16x16x32_bf16 v[40:43], v[196:199], v[172:175], v[40:43]
	v_mfma_f32_16x16x32_bf16 v[8:11], v[204:207], v[172:175], v[8:11]
	v_mfma_f32_16x16x32_bf16 v[36:39], v[196:199], v[180:183], v[36:39]
	v_mfma_f32_16x16x32_bf16 v[4:7], v[204:207], v[180:183], v[4:7]
	v_mfma_f32_16x16x32_bf16 v[32:35], v[196:199], v[188:191], v[32:35]
	v_mfma_f32_16x16x32_bf16 v[0:3], v[204:207], v[188:191], v[0:3]
	v_mfma_f32_16x16x32_bf16 v[44:47], v[200:203], v[168:171], v[44:47]
	v_mfma_f32_16x16x32_bf16 v[12:15], v[208:211], v[168:171], v[12:15]
	v_mfma_f32_16x16x32_bf16 v[40:43], v[200:203], v[176:179], v[40:43]
	v_mfma_f32_16x16x32_bf16 v[8:11], v[208:211], v[176:179], v[8:11]
	v_mfma_f32_16x16x32_bf16 v[36:39], v[200:203], v[184:187], v[36:39]
	v_mfma_f32_16x16x32_bf16 v[4:7], v[208:211], v[184:187], v[4:7]
	v_mfma_f32_16x16x32_bf16 v[32:35], v[200:203], v[192:195], v[32:35]
	v_mfma_f32_16x16x32_bf16 v[0:3], v[208:211], v[192:195], v[0:3]
	s_add_i32 s8, 0, 0x18000
	s_barrier
	s_add_u32 s4, s4, 0x80000
	s_addc_u32 s5, s5, 0
	s_mov_b32 m0, s29
	ds_read_b128 v[158:161], v166 offset:32768
	ds_read_b128 v[168:171], v166 offset:33792
	ds_read_b128 v[172:175], v166 offset:34816
	ds_read_b128 v[176:179], v166 offset:35840
	ds_read_b128 v[180:183], v166 offset:36864
	ds_read_b128 v[184:187], v166 offset:37888
	ds_read_b128 v[188:191], v166 offset:38912
	ds_read_b128 v[192:195], v166 offset:39936
	global_load_lds_dwordx4 v140, s[4:5]
	s_mov_b32 m0, s33
	s_nop 0
	global_load_lds_dwordx4 v138, s[4:5]
	s_waitcnt lgkmcnt(8)
	s_barrier
	s_waitcnt lgkmcnt(0)
	s_waitcnt lgkmcnt(0)
	v_mfma_f32_16x16x32_bf16 v[124:127], v[128:131], v[158:161], v[124:127]
	v_mfma_f32_16x16x32_bf16 v[92:95], v[150:153], v[158:161], v[92:95]
	v_mfma_f32_16x16x32_bf16 v[120:123], v[128:131], v[172:175], v[120:123]
	v_mfma_f32_16x16x32_bf16 v[88:91], v[150:153], v[172:175], v[88:91]
	v_mfma_f32_16x16x32_bf16 v[116:119], v[128:131], v[180:183], v[116:119]
	v_mfma_f32_16x16x32_bf16 v[84:87], v[150:153], v[180:183], v[84:87]
	v_mfma_f32_16x16x32_bf16 v[112:115], v[128:131], v[188:191], v[112:115]
	v_mfma_f32_16x16x32_bf16 v[80:83], v[150:153], v[188:191], v[80:83]
	v_mfma_f32_16x16x32_bf16 v[124:127], v[132:135], v[168:171], v[124:127]
	v_mfma_f32_16x16x32_bf16 v[92:95], v[154:157], v[168:171], v[92:95]
	v_mfma_f32_16x16x32_bf16 v[120:123], v[132:135], v[176:179], v[120:123]
	v_mfma_f32_16x16x32_bf16 v[88:91], v[154:157], v[176:179], v[88:91]
	v_mfma_f32_16x16x32_bf16 v[116:119], v[132:135], v[184:187], v[116:119]
	v_mfma_f32_16x16x32_bf16 v[84:87], v[154:157], v[184:187], v[84:87]
	v_mfma_f32_16x16x32_bf16 v[112:115], v[132:135], v[192:195], v[112:115]
	v_mfma_f32_16x16x32_bf16 v[80:83], v[154:157], v[192:195], v[80:83]
	s_barrier
	s_add_i32 s9, 0, 0x1c000
	s_add_i32 s4, s8, s24
	v_add_u32_e32 v208, s9, v163
	s_mov_b32 m0, s4
	ds_read_b128 v[196:199], v208
	ds_read_b128 v[200:203], v208 offset:1024
	ds_read_b128 v[204:207], v208 offset:2048
	ds_read_b128 v[208:211], v208 offset:3072
	global_load_lds_dwordx4 v140, s[98:99]
	s_add_i32 m0, s4, 0x2000
	s_nop 0
	global_load_lds_dwordx4 v138, s[98:99]
	s_barrier
	s_waitcnt lgkmcnt(0)
	s_waitcnt lgkmcnt(0)
	v_mfma_f32_16x16x32_bf16 v[60:63], v[196:199], v[158:161], v[60:63]
	v_mfma_f32_16x16x32_bf16 v[28:31], v[204:207], v[158:161], v[28:31]
	v_mfma_f32_16x16x32_bf16 v[56:59], v[196:199], v[172:175], v[56:59]
	v_mfma_f32_16x16x32_bf16 v[24:27], v[204:207], v[172:175], v[24:27]
	v_mfma_f32_16x16x32_bf16 v[52:55], v[196:199], v[180:183], v[52:55]
	v_mfma_f32_16x16x32_bf16 v[20:23], v[204:207], v[180:183], v[20:23]
	v_mfma_f32_16x16x32_bf16 v[48:51], v[196:199], v[188:191], v[48:51]
	v_mfma_f32_16x16x32_bf16 v[16:19], v[204:207], v[188:191], v[16:19]
	v_mfma_f32_16x16x32_bf16 v[60:63], v[200:203], v[168:171], v[60:63]
	v_mfma_f32_16x16x32_bf16 v[28:31], v[208:211], v[168:171], v[28:31]
	v_mfma_f32_16x16x32_bf16 v[56:59], v[200:203], v[176:179], v[56:59]
	v_mfma_f32_16x16x32_bf16 v[24:27], v[208:211], v[176:179], v[24:27]
	v_mfma_f32_16x16x32_bf16 v[52:55], v[200:203], v[184:187], v[52:55]
	v_mfma_f32_16x16x32_bf16 v[20:23], v[208:211], v[184:187], v[20:23]
	v_mfma_f32_16x16x32_bf16 v[48:51], v[200:203], v[192:195], v[48:51]
	v_mfma_f32_16x16x32_bf16 v[16:19], v[208:211], v[192:195], v[16:19]
	s_mov_b32 m0, s37
	s_barrier
	s_waitcnt vmcnt(8)
	ds_read_b128 v[158:161], v166 offset:49152
	ds_read_b128 v[168:171], v166 offset:50176
	ds_read_b128 v[172:175], v166 offset:51200
	ds_read_b128 v[176:179], v166 offset:52224
	ds_read_b128 v[180:183], v166 offset:53248
	ds_read_b128 v[184:187], v166 offset:54272
	ds_read_b128 v[188:191], v166 offset:55296
	ds_read_b128 v[192:195], v166 offset:56320
	global_load_lds_dwordx4 v140, s[100:101]
	s_mov_b32 m0, s40
	s_nop 0
	global_load_lds_dwordx4 v138, s[100:101]
	s_barrier
	s_waitcnt lgkmcnt(0)
	s_waitcnt lgkmcnt(0)
	v_mfma_f32_16x16x32_bf16 v[108:111], v[128:131], v[158:161], v[108:111]
	v_mfma_f32_16x16x32_bf16 v[76:79], v[150:153], v[158:161], v[76:79]
	v_mfma_f32_16x16x32_bf16 v[104:107], v[128:131], v[172:175], v[104:107]
	v_mfma_f32_16x16x32_bf16 v[72:75], v[150:153], v[172:175], v[72:75]
	v_mfma_f32_16x16x32_bf16 v[100:103], v[128:131], v[180:183], v[100:103]
	v_mfma_f32_16x16x32_bf16 v[68:71], v[150:153], v[180:183], v[68:71]
	v_mfma_f32_16x16x32_bf16 v[96:99], v[128:131], v[188:191], v[96:99]
	v_mfma_f32_16x16x32_bf16 v[64:67], v[150:153], v[188:191], v[64:67]
	v_mfma_f32_16x16x32_bf16 v[108:111], v[132:135], v[168:171], v[108:111]
	v_mfma_f32_16x16x32_bf16 v[76:79], v[154:157], v[168:171], v[76:79]
	v_mfma_f32_16x16x32_bf16 v[104:107], v[132:135], v[176:179], v[104:107]
	v_mfma_f32_16x16x32_bf16 v[72:75], v[154:157], v[176:179], v[72:75]
	v_mfma_f32_16x16x32_bf16 v[100:103], v[132:135], v[184:187], v[100:103]
	v_mfma_f32_16x16x32_bf16 v[68:71], v[154:157], v[184:187], v[68:71]
	v_mfma_f32_16x16x32_bf16 v[96:99], v[132:135], v[192:195], v[96:99]
	v_mfma_f32_16x16x32_bf16 v[64:67], v[154:157], v[192:195], v[64:67]
	s_barrier
	s_add_u32 s4, s70, 0x80080
	s_addc_u32 s5, s71, 0
	s_add_i32 s8, s9, s24
	s_mov_b32 m0, s8
	s_nop 0
	global_load_lds_dwordx4 v140, s[4:5]
	s_add_i32 m0, s8, 0x2000
	s_nop 0
	global_load_lds_dwordx4 v138, s[4:5]
	ds_read_b128 v[128:131], v165
	ds_read_b128 v[132:135], v165 offset:1024
	ds_read_b128 v[150:153], v165 offset:2048
	ds_read_b128 v[154:157], v165 offset:3072
	s_waitcnt vmcnt(6)
	s_barrier
	v_mfma_f32_16x16x32_bf16 v[44:47], v[196:199], v[158:161], v[44:47]
	v_mfma_f32_16x16x32_bf16 v[12:15], v[204:207], v[158:161], v[12:15]
	v_mfma_f32_16x16x32_bf16 v[40:43], v[196:199], v[172:175], v[40:43]
	v_mfma_f32_16x16x32_bf16 v[8:11], v[204:207], v[172:175], v[8:11]
	v_mfma_f32_16x16x32_bf16 v[36:39], v[196:199], v[180:183], v[36:39]
	v_mfma_f32_16x16x32_bf16 v[4:7], v[204:207], v[180:183], v[4:7]
	v_mfma_f32_16x16x32_bf16 v[32:35], v[196:199], v[188:191], v[32:35]
	v_mfma_f32_16x16x32_bf16 v[0:3], v[204:207], v[188:191], v[0:3]
	v_mfma_f32_16x16x32_bf16 v[44:47], v[200:203], v[168:171], v[44:47]
	v_mfma_f32_16x16x32_bf16 v[12:15], v[208:211], v[168:171], v[12:15]
	v_mfma_f32_16x16x32_bf16 v[40:43], v[200:203], v[176:179], v[40:43]
	v_mfma_f32_16x16x32_bf16 v[8:11], v[208:211], v[176:179], v[8:11]
	v_mfma_f32_16x16x32_bf16 v[36:39], v[200:203], v[184:187], v[36:39]
	v_mfma_f32_16x16x32_bf16 v[4:7], v[208:211], v[184:187], v[4:7]
	v_mfma_f32_16x16x32_bf16 v[32:35], v[200:203], v[192:195], v[32:35]
	v_mfma_f32_16x16x32_bf16 v[0:3], v[208:211], v[192:195], v[0:3]
	s_add_i32 s78, s78, 2
	s_add_u32 s76, s76, 0x100
	s_addc_u32 s77, s77, 0
	s_cmp_gt_u32 s78, 29
	s_mov_b64 s[8:9], s[68:69]
	s_barrier
	s_cbranch_scc0 .LBB0_1533
	v_lshl_or_b32 v160, s75, 8, v164
	v_ashrrev_i32_e32 v161, 31, v160
	v_lshl_add_u64 v[128:129], v[160:161], 2, s[14:15]
	global_load_dwordx4 v[130:133], v[128:129], off
	v_cndmask_b32_e64 v129, 0, 1, s[18:19]
	v_mov_b32_e32 v128, 0
	v_cmp_ne_u32_e64 s[8:9], 1, v129
	s_andn2_b64 vcc, exec, s[18:19]
	v_lshl_add_u64 v[158:159], v[160:161], 2, s[10:11]
	v_mov_b32_e32 v134, 0
	v_mov_b32_e32 v135, 0
	v_mov_b32_e32 v136, 0
	v_mov_b32_e32 v137, 0
	s_cbranch_vccnz .LBB0_1536
	flat_load_dwordx4 v[134:137], v[158:159]

.LBB0_1675:
	s_ashr_i32 s13, s12, 31
	v_cmp_lt_i64_e32 vcc, s[0:1], v[140:141]
	s_lshl_b64 s[0:1], s[12:13], 20
	s_add_u32 s14, s38, s0
	s_addc_u32 s15, s39, s1
	s_and_b64 s[0:1], vcc, exec
	s_cselect_b32 s0, s15, s21
	s_cselect_b32 s1, s14, s20
	s_ashr_i32 s11, s10, 31
	s_lshl_b64 s[4:5], s[10:11], 20
	s_add_u32 s16, s56, s4
	s_addc_u32 s17, s57, s5
	s_and_b64 s[4:5], vcc, exec
	s_cselect_b32 s11, s17, s45
	s_cselect_b32 s13, s16, s44
	s_add_u32 s20, s20, 0x80080
	s_addc_u32 s21, s21, 0
	s_add_u32 s51, s44, 0x100
	v_mov_b32_e32 v0, 0
	s_addc_u32 s52, s45, 0
	s_mov_b32 s53, -2
	v_mov_b32_e32 v1, v0
	v_mov_b32_e32 v2, v0
	v_mov_b32_e32 v3, v0
	v_mov_b32_e32 v4, v0
	v_mov_b32_e32 v5, v0
	v_mov_b32_e32 v6, v0
	v_mov_b32_e32 v7, v0
	v_mov_b32_e32 v16, v0
	v_mov_b32_e32 v17, v0
	v_mov_b32_e32 v18, v0
	v_mov_b32_e32 v19, v0
	v_mov_b32_e32 v20, v0
	v_mov_b32_e32 v21, v0
	v_mov_b32_e32 v22, v0
	v_mov_b32_e32 v23, v0
	v_mov_b32_e32 v32, v0
	v_mov_b32_e32 v33, v0
	v_mov_b32_e32 v34, v0
	v_mov_b32_e32 v35, v0
	v_mov_b32_e32 v36, v0
	v_mov_b32_e32 v37, v0
	v_mov_b32_e32 v38, v0
	v_mov_b32_e32 v39, v0
	v_mov_b32_e32 v48, v0
	v_mov_b32_e32 v49, v0
	v_mov_b32_e32 v50, v0
	v_mov_b32_e32 v51, v0
	v_mov_b32_e32 v52, v0
	v_mov_b32_e32 v53, v0
	v_mov_b32_e32 v54, v0
	v_mov_b32_e32 v55, v0
	v_mov_b32_e32 v8, v0
	v_mov_b32_e32 v9, v0
	v_mov_b32_e32 v10, v0
	v_mov_b32_e32 v11, v0
	v_mov_b32_e32 v12, v0
	v_mov_b32_e32 v13, v0
	v_mov_b32_e32 v14, v0
	v_mov_b32_e32 v15, v0
	v_mov_b32_e32 v24, v0
	v_mov_b32_e32 v25, v0
	v_mov_b32_e32 v26, v0
	v_mov_b32_e32 v27, v0
	v_mov_b32_e32 v28, v0
	v_mov_b32_e32 v29, v0
	v_mov_b32_e32 v30, v0
	v_mov_b32_e32 v31, v0
	v_mov_b32_e32 v40, v0
	v_mov_b32_e32 v41, v0
	v_mov_b32_e32 v42, v0
	v_mov_b32_e32 v43, v0
	v_mov_b32_e32 v44, v0
	v_mov_b32_e32 v45, v0
	v_mov_b32_e32 v46, v0
	v_mov_b32_e32 v47, v0
	v_mov_b32_e32 v56, v0
	v_mov_b32_e32 v57, v0
	v_mov_b32_e32 v58, v0
	v_mov_b32_e32 v59, v0
	v_mov_b32_e32 v60, v0
	v_mov_b32_e32 v61, v0
	v_mov_b32_e32 v62, v0
	v_mov_b32_e32 v63, v0
	v_mov_b32_e32 v64, v0
	v_mov_b32_e32 v65, v0
	v_mov_b32_e32 v66, v0
	v_mov_b32_e32 v67, v0
	v_mov_b32_e32 v68, v0
	v_mov_b32_e32 v69, v0
	v_mov_b32_e32 v70, v0
	v_mov_b32_e32 v71, v0
	v_mov_b32_e32 v80, v0
	v_mov_b32_e32 v81, v0
	v_mov_b32_e32 v82, v0
	v_mov_b32_e32 v83, v0
	v_mov_b32_e32 v84, v0
	v_mov_b32_e32 v85, v0
	v_mov_b32_e32 v86, v0
	v_mov_b32_e32 v87, v0
	v_mov_b32_e32 v96, v0
	v_mov_b32_e32 v97, v0
	v_mov_b32_e32 v98, v0
	v_mov_b32_e32 v99, v0
	v_mov_b32_e32 v100, v0
	v_mov_b32_e32 v101, v0
	v_mov_b32_e32 v102, v0
	v_mov_b32_e32 v103, v0
	v_mov_b32_e32 v112, v0
	v_mov_b32_e32 v113, v0
	v_mov_b32_e32 v114, v0
	v_mov_b32_e32 v115, v0
	v_mov_b32_e32 v116, v0
	v_mov_b32_e32 v117, v0
	v_mov_b32_e32 v118, v0
	v_mov_b32_e32 v119, v0
	v_mov_b32_e32 v72, v0
	v_mov_b32_e32 v73, v0
	v_mov_b32_e32 v74, v0
	v_mov_b32_e32 v75, v0
	v_mov_b32_e32 v76, v0
	v_mov_b32_e32 v77, v0
	v_mov_b32_e32 v78, v0
	v_mov_b32_e32 v79, v0
	v_mov_b32_e32 v88, v0
	v_mov_b32_e32 v89, v0
	v_mov_b32_e32 v90, v0
	v_mov_b32_e32 v91, v0
	v_mov_b32_e32 v92, v0
	v_mov_b32_e32 v93, v0
	v_mov_b32_e32 v94, v0
	v_mov_b32_e32 v95, v0
	v_mov_b32_e32 v104, v0
	v_mov_b32_e32 v105, v0
	v_mov_b32_e32 v106, v0
	v_mov_b32_e32 v107, v0
	v_mov_b32_e32 v108, v0
	v_mov_b32_e32 v109, v0
	v_mov_b32_e32 v110, v0
	v_mov_b32_e32 v111, v0
	v_mov_b32_e32 v120, v0
	v_mov_b32_e32 v121, v0
	v_mov_b32_e32 v122, v0
	v_mov_b32_e32 v123, v0
	v_mov_b32_e32 v124, v0
	v_mov_b32_e32 v125, v0
	v_mov_b32_e32 v126, v0
	v_mov_b32_e32 v127, v0
	ds_read_b128 v[150:153], v147
	ds_read_b128 v[154:157], v147 offset:1024
	ds_read_b128 v[158:161], v147 offset:2048
	ds_read_b128 v[162:165], v147 offset:3072
	.p2alignl 6, 3212836864
.LBB0_1676:
	s_add_u32 s4, s20, 0xfff80080
	s_addc_u32 s5, s21, -1
	s_cmp_eq_u32 s53, 28
	s_cselect_b32 s5, s0, s5
	s_cselect_b32 s4, s1, s4
	s_cselect_b32 s45, s11, s52
	s_cselect_b32 s44, s13, s51
	s_add_i32 m0, s19, 0xc000
	ds_read_b128 v[166:169], v148
	ds_read_b128 v[170:173], v148 offset:1024
	ds_read_b128 v[174:177], v148 offset:2048
	ds_read_b128 v[178:181], v148 offset:3072
	ds_read_b128 v[182:185], v148 offset:4096
	ds_read_b128 v[186:189], v148 offset:5120
	ds_read_b128 v[190:193], v148 offset:6144
	ds_read_b128 v[194:197], v148 offset:7168
	global_load_lds_dwordx4 v136, s[20:21]
	s_add_i32 m0, s19, 0xe000
	s_nop 0
	global_load_lds_dwordx4 v138, s[20:21]
	s_waitcnt lgkmcnt(8)
	s_barrier
	s_waitcnt lgkmcnt(0)
	s_waitcnt lgkmcnt(0)
	v_mfma_f32_16x16x32_bf16 v[124:127], v[150:153], v[166:169], v[124:127]
	v_mfma_f32_16x16x32_bf16 v[120:123], v[158:161], v[166:169], v[120:123]
	v_mfma_f32_16x16x32_bf16 v[108:111], v[150:153], v[174:177], v[108:111]
	v_mfma_f32_16x16x32_bf16 v[104:107], v[158:161], v[174:177], v[104:107]
	v_mfma_f32_16x16x32_bf16 v[92:95], v[150:153], v[182:185], v[92:95]
	v_mfma_f32_16x16x32_bf16 v[88:91], v[158:161], v[182:185], v[88:91]
	v_mfma_f32_16x16x32_bf16 v[76:79], v[150:153], v[190:193], v[76:79]
	v_mfma_f32_16x16x32_bf16 v[72:75], v[158:161], v[190:193], v[72:75]
	v_mfma_f32_16x16x32_bf16 v[124:127], v[154:157], v[170:173], v[124:127]
	v_mfma_f32_16x16x32_bf16 v[120:123], v[162:165], v[170:173], v[120:123]
	v_mfma_f32_16x16x32_bf16 v[108:111], v[154:157], v[178:181], v[108:111]
	v_mfma_f32_16x16x32_bf16 v[104:107], v[162:165], v[178:181], v[104:107]
	v_mfma_f32_16x16x32_bf16 v[92:95], v[154:157], v[186:189], v[92:95]
	v_mfma_f32_16x16x32_bf16 v[88:91], v[162:165], v[186:189], v[88:91]
	v_mfma_f32_16x16x32_bf16 v[76:79], v[154:157], v[194:197], v[76:79]
	v_mfma_f32_16x16x32_bf16 v[72:75], v[162:165], v[194:197], v[72:75]
	s_barrier
	s_add_i32 s42, s41, s24
	s_add_u32 s98, s44, s8
	s_addc_u32 s99, s45, s9
	s_mov_b32 m0, s42
	ds_read_b128 v[198:201], v149
	ds_read_b128 v[202:205], v149 offset:1024
	ds_read_b128 v[206:209], v149 offset:2048
	ds_read_b128 v[210:213], v149 offset:3072
	global_load_lds_dwordx4 v132, s[44:45]
	s_add_i32 m0, s42, 0x2000
	s_nop 0
	global_load_lds_dwordx4 v128, s[44:45]
	s_barrier
	s_waitcnt lgkmcnt(0)
	s_waitcnt lgkmcnt(0)
	v_mfma_f32_16x16x32_bf16 v[116:119], v[198:201], v[166:169], v[116:119]
	v_mfma_f32_16x16x32_bf16 v[112:115], v[206:209], v[166:169], v[112:115]
	v_mfma_f32_16x16x32_bf16 v[100:103], v[198:201], v[174:177], v[100:103]
	v_mfma_f32_16x16x32_bf16 v[96:99], v[206:209], v[174:177], v[96:99]
	v_mfma_f32_16x16x32_bf16 v[84:87], v[198:201], v[182:185], v[84:87]
	v_mfma_f32_16x16x32_bf16 v[80:83], v[206:209], v[182:185], v[80:83]
	v_mfma_f32_16x16x32_bf16 v[68:71], v[198:201], v[190:193], v[68:71]
	v_mfma_f32_16x16x32_bf16 v[64:67], v[206:209], v[190:193], v[64:67]
	v_mfma_f32_16x16x32_bf16 v[116:119], v[202:205], v[170:173], v[116:119]
	v_mfma_f32_16x16x32_bf16 v[112:115], v[210:213], v[170:173], v[112:115]
	v_mfma_f32_16x16x32_bf16 v[100:103], v[202:205], v[178:181], v[100:103]
	v_mfma_f32_16x16x32_bf16 v[96:99], v[210:213], v[178:181], v[96:99]
	v_mfma_f32_16x16x32_bf16 v[84:87], v[202:205], v[186:189], v[84:87]
	v_mfma_f32_16x16x32_bf16 v[80:83], v[210:213], v[186:189], v[80:83]
	v_mfma_f32_16x16x32_bf16 v[68:71], v[202:205], v[194:197], v[68:71]
	v_mfma_f32_16x16x32_bf16 v[64:67], v[210:213], v[194:197], v[64:67]
	s_mov_b32 m0, s19
	s_add_u32 s100, s4, s8
	s_addc_u32 s101, s5, s9
	s_barrier
	s_waitcnt vmcnt(8)
	ds_read_b128 v[166:169], v148 offset:16384
	ds_read_b128 v[170:173], v148 offset:17408
	ds_read_b128 v[174:177], v148 offset:18432
	ds_read_b128 v[178:181], v148 offset:19456
	ds_read_b128 v[182:185], v148 offset:20480
	ds_read_b128 v[186:189], v148 offset:21504
	ds_read_b128 v[190:193], v148 offset:22528
	ds_read_b128 v[194:197], v148 offset:23552
	global_load_lds_dwordx4 v134, s[4:5]
	s_mov_b32 m0, s28
	s_nop 0
	global_load_lds_dwordx4 v130, s[4:5]
	s_barrier
	s_waitcnt lgkmcnt(0)
	s_waitcnt lgkmcnt(0)
	v_mfma_f32_16x16x32_bf16 v[60:63], v[150:153], v[166:169], v[60:63]
	v_mfma_f32_16x16x32_bf16 v[56:59], v[158:161], v[166:169], v[56:59]
	v_mfma_f32_16x16x32_bf16 v[44:47], v[150:153], v[174:177], v[44:47]
	v_mfma_f32_16x16x32_bf16 v[40:43], v[158:161], v[174:177], v[40:43]
	v_mfma_f32_16x16x32_bf16 v[28:31], v[150:153], v[182:185], v[28:31]
	v_mfma_f32_16x16x32_bf16 v[24:27], v[158:161], v[182:185], v[24:27]
	v_mfma_f32_16x16x32_bf16 v[12:15], v[150:153], v[190:193], v[12:15]
	v_mfma_f32_16x16x32_bf16 v[8:11], v[158:161], v[190:193], v[8:11]
	v_mfma_f32_16x16x32_bf16 v[60:63], v[154:157], v[170:173], v[60:63]
	v_mfma_f32_16x16x32_bf16 v[56:59], v[162:165], v[170:173], v[56:59]
	v_mfma_f32_16x16x32_bf16 v[44:47], v[154:157], v[178:181], v[44:47]
	v_mfma_f32_16x16x32_bf16 v[40:43], v[162:165], v[178:181], v[40:43]
	v_mfma_f32_16x16x32_bf16 v[28:31], v[154:157], v[186:189], v[28:31]
	v_mfma_f32_16x16x32_bf16 v[24:27], v[162:165], v[186:189], v[24:27]
	v_mfma_f32_16x16x32_bf16 v[12:15], v[154:157], v[194:197], v[12:15]
	v_mfma_f32_16x16x32_bf16 v[8:11], v[162:165], v[194:197], v[8:11]
	s_barrier
	s_add_u32 s42, s44, 0x80000
	s_addc_u32 s43, s45, 0
	s_add_i32 s54, s46, s24
	s_mov_b32 m0, s54
	s_nop 0
	global_load_lds_dwordx4 v132, s[42:43]
	s_add_i32 m0, s54, 0x2000
	s_nop 0
	global_load_lds_dwordx4 v128, s[42:43]
	v_add_u32_e32 v162, 0x18000, v145
	ds_read_b128 v[150:153], v162
	ds_read_b128 v[154:157], v162 offset:1024
	ds_read_b128 v[158:161], v162 offset:2048
	ds_read_b128 v[162:165], v162 offset:3072
	s_waitcnt vmcnt(6)
	s_barrier
	v_mfma_f32_16x16x32_bf16 v[52:55], v[198:201], v[166:169], v[52:55]
	v_mfma_f32_16x16x32_bf16 v[48:51], v[206:209], v[166:169], v[48:51]
	v_mfma_f32_16x16x32_bf16 v[36:39], v[198:201], v[174:177], v[36:39]
	v_mfma_f32_16x16x32_bf16 v[32:35], v[206:209], v[174:177], v[32:35]
	v_mfma_f32_16x16x32_bf16 v[20:23], v[198:201], v[182:185], v[20:23]
	v_mfma_f32_16x16x32_bf16 v[16:19], v[206:209], v[182:185], v[16:19]
	v_mfma_f32_16x16x32_bf16 v[4:7], v[198:201], v[190:193], v[4:7]
	v_mfma_f32_16x16x32_bf16 v[0:3], v[206:209], v[190:193], v[0:3]
	v_mfma_f32_16x16x32_bf16 v[52:55], v[202:205], v[170:173], v[52:55]
	v_mfma_f32_16x16x32_bf16 v[48:51], v[210:213], v[170:173], v[48:51]
	v_mfma_f32_16x16x32_bf16 v[36:39], v[202:205], v[178:181], v[36:39]
	v_mfma_f32_16x16x32_bf16 v[32:35], v[210:213], v[178:181], v[32:35]
	v_mfma_f32_16x16x32_bf16 v[20:23], v[202:205], v[186:189], v[20:23]
	v_mfma_f32_16x16x32_bf16 v[16:19], v[210:213], v[186:189], v[16:19]
	v_mfma_f32_16x16x32_bf16 v[4:7], v[202:205], v[194:197], v[4:7]
	v_mfma_f32_16x16x32_bf16 v[0:3], v[210:213], v[194:197], v[0:3]
	s_add_i32 s42, 0, 0x18000
	s_barrier
	s_add_u32 s4, s4, 0x80000
	s_addc_u32 s5, s5, 0
	s_mov_b32 m0, s29
	ds_read_b128 v[166:169], v148 offset:32768
	ds_read_b128 v[170:173], v148 offset:33792
	ds_read_b128 v[174:177], v148 offset:34816
	ds_read_b128 v[178:181], v148 offset:35840
	ds_read_b128 v[182:185], v148 offset:36864
	ds_read_b128 v[186:189], v148 offset:37888
	ds_read_b128 v[190:193], v148 offset:38912
	ds_read_b128 v[194:197], v148 offset:39936
	global_load_lds_dwordx4 v134, s[4:5]
	s_mov_b32 m0, s33
	s_nop 0
	global_load_lds_dwordx4 v130, s[4:5]
	s_waitcnt lgkmcnt(8)
	s_barrier
	s_waitcnt lgkmcnt(0)
	s_waitcnt lgkmcnt(0)
	v_mfma_f32_16x16x32_bf16 v[124:127], v[150:153], v[166:169], v[124:127]
	v_mfma_f32_16x16x32_bf16 v[120:123], v[158:161], v[166:169], v[120:123]
	v_mfma_f32_16x16x32_bf16 v[108:111], v[150:153], v[174:177], v[108:111]
	v_mfma_f32_16x16x32_bf16 v[104:107], v[158:161], v[174:177], v[104:107]
	v_mfma_f32_16x16x32_bf16 v[92:95], v[150:153], v[182:185], v[92:95]
	v_mfma_f32_16x16x32_bf16 v[88:91], v[158:161], v[182:185], v[88:91]
	v_mfma_f32_16x16x32_bf16 v[76:79], v[150:153], v[190:193], v[76:79]
	v_mfma_f32_16x16x32_bf16 v[72:75], v[158:161], v[190:193], v[72:75]
	v_mfma_f32_16x16x32_bf16 v[124:127], v[154:157], v[170:173], v[124:127]
	v_mfma_f32_16x16x32_bf16 v[120:123], v[162:165], v[170:173], v[120:123]
	v_mfma_f32_16x16x32_bf16 v[108:111], v[154:157], v[178:181], v[108:111]
	v_mfma_f32_16x16x32_bf16 v[104:107], v[162:165], v[178:181], v[104:107]
	v_mfma_f32_16x16x32_bf16 v[92:95], v[154:157], v[186:189], v[92:95]
	v_mfma_f32_16x16x32_bf16 v[88:91], v[162:165], v[186:189], v[88:91]
	v_mfma_f32_16x16x32_bf16 v[76:79], v[154:157], v[194:197], v[76:79]
	v_mfma_f32_16x16x32_bf16 v[72:75], v[162:165], v[194:197], v[72:75]
	s_barrier
	s_add_i32 s43, 0, 0x1c000
	s_add_i32 s4, s42, s24
	v_add_u32_e32 v210, s43, v145
	s_mov_b32 m0, s4
	ds_read_b128 v[198:201], v210
	ds_read_b128 v[202:205], v210 offset:1024
	ds_read_b128 v[206:209], v210 offset:2048
	ds_read_b128 v[210:213], v210 offset:3072
	global_load_lds_dwordx4 v132, s[98:99]
	s_add_i32 m0, s4, 0x2000
	s_nop 0
	global_load_lds_dwordx4 v128, s[98:99]
	s_barrier
	s_waitcnt lgkmcnt(0)
	s_waitcnt lgkmcnt(0)
	v_mfma_f32_16x16x32_bf16 v[116:119], v[198:201], v[166:169], v[116:119]
	v_mfma_f32_16x16x32_bf16 v[112:115], v[206:209], v[166:169], v[112:115]
	v_mfma_f32_16x16x32_bf16 v[100:103], v[198:201], v[174:177], v[100:103]
	v_mfma_f32_16x16x32_bf16 v[96:99], v[206:209], v[174:177], v[96:99]
	v_mfma_f32_16x16x32_bf16 v[84:87], v[198:201], v[182:185], v[84:87]
	v_mfma_f32_16x16x32_bf16 v[80:83], v[206:209], v[182:185], v[80:83]
	v_mfma_f32_16x16x32_bf16 v[68:71], v[198:201], v[190:193], v[68:71]
	v_mfma_f32_16x16x32_bf16 v[64:67], v[206:209], v[190:193], v[64:67]
	v_mfma_f32_16x16x32_bf16 v[116:119], v[202:205], v[170:173], v[116:119]
	v_mfma_f32_16x16x32_bf16 v[112:115], v[210:213], v[170:173], v[112:115]
	v_mfma_f32_16x16x32_bf16 v[100:103], v[202:205], v[178:181], v[100:103]
	v_mfma_f32_16x16x32_bf16 v[96:99], v[210:213], v[178:181], v[96:99]
	v_mfma_f32_16x16x32_bf16 v[84:87], v[202:205], v[186:189], v[84:87]
	v_mfma_f32_16x16x32_bf16 v[80:83], v[210:213], v[186:189], v[80:83]
	v_mfma_f32_16x16x32_bf16 v[68:71], v[202:205], v[194:197], v[68:71]
	v_mfma_f32_16x16x32_bf16 v[64:67], v[210:213], v[194:197], v[64:67]
	s_mov_b32 m0, s37
	s_barrier
	s_waitcnt vmcnt(8)
	ds_read_b128 v[166:169], v148 offset:49152
	ds_read_b128 v[170:173], v148 offset:50176
	ds_read_b128 v[174:177], v148 offset:51200
	ds_read_b128 v[178:181], v148 offset:52224
	ds_read_b128 v[182:185], v148 offset:53248
	ds_read_b128 v[186:189], v148 offset:54272
	ds_read_b128 v[190:193], v148 offset:55296
	ds_read_b128 v[194:197], v148 offset:56320
	global_load_lds_dwordx4 v134, s[100:101]
	s_mov_b32 m0, s40
	s_nop 0
	global_load_lds_dwordx4 v130, s[100:101]
	s_barrier
	s_waitcnt lgkmcnt(0)
	s_waitcnt lgkmcnt(0)
	v_mfma_f32_16x16x32_bf16 v[60:63], v[150:153], v[166:169], v[60:63]
	v_mfma_f32_16x16x32_bf16 v[56:59], v[158:161], v[166:169], v[56:59]
	v_mfma_f32_16x16x32_bf16 v[44:47], v[150:153], v[174:177], v[44:47]
	v_mfma_f32_16x16x32_bf16 v[40:43], v[158:161], v[174:177], v[40:43]
	v_mfma_f32_16x16x32_bf16 v[28:31], v[150:153], v[182:185], v[28:31]
	v_mfma_f32_16x16x32_bf16 v[24:27], v[158:161], v[182:185], v[24:27]
	v_mfma_f32_16x16x32_bf16 v[12:15], v[150:153], v[190:193], v[12:15]
	v_mfma_f32_16x16x32_bf16 v[8:11], v[158:161], v[190:193], v[8:11]
	v_mfma_f32_16x16x32_bf16 v[60:63], v[154:157], v[170:173], v[60:63]
	v_mfma_f32_16x16x32_bf16 v[56:59], v[162:165], v[170:173], v[56:59]
	v_mfma_f32_16x16x32_bf16 v[44:47], v[154:157], v[178:181], v[44:47]
	v_mfma_f32_16x16x32_bf16 v[40:43], v[162:165], v[178:181], v[40:43]
	v_mfma_f32_16x16x32_bf16 v[28:31], v[154:157], v[186:189], v[28:31]
	v_mfma_f32_16x16x32_bf16 v[24:27], v[162:165], v[186:189], v[24:27]
	v_mfma_f32_16x16x32_bf16 v[12:15], v[154:157], v[194:197], v[12:15]
	v_mfma_f32_16x16x32_bf16 v[8:11], v[162:165], v[194:197], v[8:11]
	s_barrier
	s_add_u32 s4, s44, 0x80080
	s_addc_u32 s5, s45, 0
	s_add_i32 s42, s43, s24
	s_mov_b32 m0, s42
	s_nop 0
	global_load_lds_dwordx4 v132, s[4:5]
	s_add_i32 m0, s42, 0x2000
	s_nop 0
	global_load_lds_dwordx4 v128, s[4:5]
	ds_read_b128 v[150:153], v147
	ds_read_b128 v[154:157], v147 offset:1024
	ds_read_b128 v[158:161], v147 offset:2048
	ds_read_b128 v[162:165], v147 offset:3072
	s_waitcnt vmcnt(6)
	s_barrier
	v_mfma_f32_16x16x32_bf16 v[52:55], v[198:201], v[166:169], v[52:55]
	v_mfma_f32_16x16x32_bf16 v[48:51], v[206:209], v[166:169], v[48:51]
	v_mfma_f32_16x16x32_bf16 v[36:39], v[198:201], v[174:177], v[36:39]
	v_mfma_f32_16x16x32_bf16 v[32:35], v[206:209], v[174:177], v[32:35]
	v_mfma_f32_16x16x32_bf16 v[20:23], v[198:201], v[182:185], v[20:23]
	v_mfma_f32_16x16x32_bf16 v[16:19], v[206:209], v[182:185], v[16:19]
	v_mfma_f32_16x16x32_bf16 v[4:7], v[198:201], v[190:193], v[4:7]
	v_mfma_f32_16x16x32_bf16 v[0:3], v[206:209], v[190:193], v[0:3]
	v_mfma_f32_16x16x32_bf16 v[52:55], v[202:205], v[170:173], v[52:55]
	v_mfma_f32_16x16x32_bf16 v[48:51], v[210:213], v[170:173], v[48:51]
	v_mfma_f32_16x16x32_bf16 v[36:39], v[202:205], v[178:181], v[36:39]
	v_mfma_f32_16x16x32_bf16 v[32:35], v[210:213], v[178:181], v[32:35]
	v_mfma_f32_16x16x32_bf16 v[20:23], v[202:205], v[186:189], v[20:23]
	v_mfma_f32_16x16x32_bf16 v[16:19], v[210:213], v[186:189], v[16:19]
	v_mfma_f32_16x16x32_bf16 v[4:7], v[202:205], v[194:197], v[4:7]
	v_mfma_f32_16x16x32_bf16 v[0:3], v[210:213], v[194:197], v[0:3]
	s_add_i32 s53, s53, 2
	s_add_u32 s20, s20, 0x100
	s_addc_u32 s21, s21, 0
	s_add_u32 s51, s51, 0x100
	s_addc_u32 s52, s52, 0
	s_cmp_gt_u32 s53, 29
	s_barrier
	s_cbranch_scc0 .LBB0_1676
	v_mul_f32_e32 v151, 0xbfb8aa3b, v124
	v_exp_f32_e32 v151, v151
	v_mul_f32_e32 v152, 0xbfb8aa3b, v120
	v_exp_f32_e32 v153, v152
	v_lshl_or_b32 v152, s50, 7, v146
	v_add_f32_e32 v151, 1.0, v151
	v_rcp_f32_e32 v151, v151
	v_add_f32_e32 v153, 1.0, v153
	v_rcp_f32_e32 v154, v153
	v_lshl_add_u32 v150, s18, 8, v144
	v_mul_f32_e32 v124, v124, v151
	v_mul_f32_e32 v116, v124, v116
	v_mul_f32_e32 v124, 0xbfb8aa3b, v125
	v_exp_f32_e32 v124, v124
	v_mul_f32_e32 v151, 0xbfb8aa3b, v121
	v_exp_f32_e32 v151, v151
	v_mul_f32_e32 v120, v120, v154
	v_mul_f32_e32 v112, v120, v112
	v_add_f32_e32 v120, 1.0, v124
	v_rcp_f32_e32 v120, v120
	v_add_f32_e32 v124, 1.0, v151
	v_mul_f32_e32 v151, 0xbfb8aa3b, v126
	v_rcp_f32_e32 v124, v124
	v_exp_f32_e32 v151, v151
	v_mul_f32_e32 v120, v125, v120
	v_mul_f32_e32 v117, v120, v117
	v_mul_f32_e32 v120, v121, v124
	v_add_f32_e32 v121, 1.0, v151
	v_rcp_f32_e32 v121, v121
	v_mul_f32_e32 v124, 0xbfb8aa3b, v122
	v_exp_f32_e32 v124, v124
	v_mul_f32_e32 v113, v120, v113
	v_mul_f32_e32 v120, v126, v121
	v_mul_f32_e32 v121, 0xbfb8aa3b, v127
	v_mul_f32_e32 v118, v120, v118
	v_add_f32_e32 v120, 1.0, v124
	v_exp_f32_e32 v121, v121
	v_mul_f32_e32 v124, 0xbfb8aa3b, v123
	v_rcp_f32_e32 v120, v120
	v_exp_f32_e32 v124, v124
	v_add_f32_e32 v121, 1.0, v121
	v_rcp_f32_e32 v121, v121
	v_mul_f32_e32 v120, v122, v120
	v_add_f32_e32 v122, 1.0, v124
	v_rcp_f32_e32 v122, v122
	v_mul_f32_e32 v114, v120, v114
	v_mul_f32_e32 v120, v127, v121
	v_mul_f32_e32 v119, v120, v119
	v_mul_f32_e32 v120, v123, v122
	v_mul_f32_e32 v122, 0xbfb8aa3b, v108
	v_exp_f32_e32 v122, v122
	v_mul_f32_e32 v123, 0xbfb8aa3b, v104
	v_exp_f32_e32 v123, v123
	v_ashrrev_i32_e32 v153, 31, v152
	v_add_f32_e32 v122, 1.0, v122
	v_rcp_f32_e32 v122, v122
	v_mul_f32_e32 v115, v120, v115
	s_nop 1
	v_cvt_pk_bf16_f32 v116, v116, v117
	s_nop 1
	v_cvt_pk_bf16_f32 v117, v118, v119
	s_nop 1
	v_cvt_pk_bf16_f32 v118, v112, v113
	v_mov_b64_e32 v[112:113], s[48:49]
	s_nop 1
	v_cvt_pk_bf16_f32 v119, v114, v115
	v_mad_i64_i32 v[120:121], s[0:1], v150, s47, v[112:113]
	v_lshlrev_b64 v[114:115], 1, v[152:153]
	v_add_f32_e32 v123, 1.0, v123
	v_mul_f32_e32 v108, v108, v122
	v_lshl_add_u64 v[120:121], v[120:121], 0, v[114:115]
	v_rcp_f32_e32 v123, v123
	v_mul_f32_e32 v100, v108, v100
	v_mul_f32_e32 v108, 0xbfb8aa3b, v109
	global_store_dwordx4 v[120:121], v[116:119], off
	v_exp_f32_e32 v108, v108
	v_mul_f32_e32 v104, v104, v123
	v_mul_f32_e32 v116, 0xbfb8aa3b, v105
	v_exp_f32_e32 v116, v116
	v_mul_f32_e32 v104, v104, v96
	v_add_f32_e32 v96, 1.0, v108
	v_rcp_f32_e32 v96, v96
	v_add_f32_e32 v108, 1.0, v116
	v_mul_f32_e32 v116, 0xbfb8aa3b, v110
	v_rcp_f32_e32 v108, v108
	v_exp_f32_e32 v116, v116
	v_mul_f32_e32 v96, v109, v96
	v_mul_f32_e32 v96, v96, v101
	v_mul_f32_e32 v101, v105, v108
	v_add_f32_e32 v105, 1.0, v116
	v_rcp_f32_e32 v105, v105
	v_mul_f32_e32 v108, 0xbfb8aa3b, v106
	v_exp_f32_e32 v108, v108
	v_mul_f32_e32 v101, v101, v97
	v_mul_f32_e32 v97, v110, v105
	v_mul_f32_e32 v105, 0xbfb8aa3b, v111
	v_mul_f32_e32 v97, v97, v102
	v_add_f32_e32 v102, 1.0, v108
	v_exp_f32_e32 v105, v105
	v_mul_f32_e32 v108, 0xbfb8aa3b, v107
	v_rcp_f32_e32 v102, v102
	v_exp_f32_e32 v108, v108
	v_add_f32_e32 v105, 1.0, v105
	v_rcp_f32_e32 v105, v105
	v_mul_f32_e32 v102, v106, v102
	v_add_f32_e32 v106, 1.0, v108
	v_rcp_f32_e32 v106, v106
	v_mul_f32_e32 v102, v102, v98
	v_mul_f32_e32 v98, v111, v105
	v_mul_f32_e32 v98, v98, v103
	v_mul_f32_e32 v103, v107, v106
	v_mul_f32_e32 v99, v103, v99
	s_nop 1
	v_cvt_pk_bf16_f32 v96, v100, v96
	s_nop 1
	v_cvt_pk_bf16_f32 v97, v97, v98
	s_nop 1
	v_cvt_pk_bf16_f32 v98, v104, v101
	s_nop 1
	v_cvt_pk_bf16_f32 v99, v102, v99
	v_mul_f32_e32 v102, 0xbfb8aa3b, v92
	v_exp_f32_e32 v102, v102
	v_mul_f32_e32 v103, 0xbfb8aa3b, v88
	v_exp_f32_e32 v103, v103
	v_or_b32_e32 v100, 16, v150
	v_add_f32_e32 v102, 1.0, v102
	v_rcp_f32_e32 v102, v102
	v_mad_i64_i32 v[100:101], s[0:1], v100, s47, v[112:113]
	v_add_f32_e32 v103, 1.0, v103
	v_mul_f32_e32 v92, v92, v102
	v_lshl_add_u64 v[100:101], v[100:101], 0, v[114:115]
	v_rcp_f32_e32 v103, v103
	v_mul_f32_e32 v84, v92, v84
	v_mul_f32_e32 v92, 0xbfb8aa3b, v93
	global_store_dwordx4 v[100:101], v[96:99], off
	v_exp_f32_e32 v92, v92
	v_mul_f32_e32 v88, v88, v103
	v_mul_f32_e32 v96, 0xbfb8aa3b, v89
	v_exp_f32_e32 v96, v96
	v_mul_f32_e32 v88, v88, v80
	v_add_f32_e32 v80, 1.0, v92
	v_rcp_f32_e32 v80, v80
	v_add_f32_e32 v92, 1.0, v96
	v_mul_f32_e32 v96, 0xbfb8aa3b, v94
	v_rcp_f32_e32 v92, v92
	v_exp_f32_e32 v96, v96
	v_mul_f32_e32 v80, v93, v80
	v_mul_f32_e32 v80, v80, v85
	v_mul_f32_e32 v85, v89, v92
	v_add_f32_e32 v89, 1.0, v96
	v_rcp_f32_e32 v89, v89
	v_mul_f32_e32 v92, 0xbfb8aa3b, v90
	v_exp_f32_e32 v92, v92
	v_mul_f32_e32 v85, v85, v81
	v_mul_f32_e32 v81, v94, v89
	v_mul_f32_e32 v89, 0xbfb8aa3b, v95
	v_mul_f32_e32 v81, v81, v86
	v_add_f32_e32 v86, 1.0, v92
	v_exp_f32_e32 v89, v89
	v_mul_f32_e32 v92, 0xbfb8aa3b, v91
	v_rcp_f32_e32 v86, v86
	v_exp_f32_e32 v92, v92
	v_add_f32_e32 v89, 1.0, v89
	v_rcp_f32_e32 v89, v89
	v_mul_f32_e32 v86, v90, v86
	v_add_f32_e32 v90, 1.0, v92
	v_rcp_f32_e32 v90, v90
	v_mul_f32_e32 v86, v86, v82
	v_mul_f32_e32 v82, v95, v89
	v_mul_f32_e32 v82, v82, v87
	v_mul_f32_e32 v87, v91, v90
	v_mul_f32_e32 v83, v87, v83
	s_nop 1
	v_cvt_pk_bf16_f32 v80, v84, v80
	s_nop 1
	v_cvt_pk_bf16_f32 v81, v81, v82
	s_nop 1
	v_cvt_pk_bf16_f32 v82, v88, v85
	s_nop 1
	v_cvt_pk_bf16_f32 v83, v86, v83
	v_mul_f32_e32 v86, 0xbfb8aa3b, v76
	v_exp_f32_e32 v86, v86
	v_mul_f32_e32 v87, 0xbfb8aa3b, v72
	v_exp_f32_e32 v87, v87
	v_or_b32_e32 v84, 32, v150
	v_add_f32_e32 v86, 1.0, v86
	v_rcp_f32_e32 v86, v86
	v_mad_i64_i32 v[84:85], s[0:1], v84, s47, v[112:113]
	v_add_f32_e32 v87, 1.0, v87
	v_mul_f32_e32 v76, v76, v86
	v_lshl_add_u64 v[84:85], v[84:85], 0, v[114:115]
	v_rcp_f32_e32 v87, v87
	v_mul_f32_e32 v68, v76, v68
	v_mul_f32_e32 v76, 0xbfb8aa3b, v77
	global_store_dwordx4 v[84:85], v[80:83], off
	v_exp_f32_e32 v76, v76
	v_mul_f32_e32 v72, v72, v87
	v_mul_f32_e32 v80, 0xbfb8aa3b, v73
	v_exp_f32_e32 v80, v80
	v_mul_f32_e32 v72, v72, v64
	v_add_f32_e32 v64, 1.0, v76
	v_rcp_f32_e32 v64, v64
	v_add_f32_e32 v76, 1.0, v80
	v_mul_f32_e32 v80, 0xbfb8aa3b, v78
	v_rcp_f32_e32 v76, v76
	v_exp_f32_e32 v80, v80
	v_mul_f32_e32 v64, v77, v64
	v_mul_f32_e32 v64, v64, v69
	v_mul_f32_e32 v69, v73, v76
	v_add_f32_e32 v73, 1.0, v80
	v_rcp_f32_e32 v73, v73
	v_mul_f32_e32 v76, 0xbfb8aa3b, v74
	v_exp_f32_e32 v76, v76
	v_mul_f32_e32 v69, v69, v65
	v_mul_f32_e32 v65, v78, v73
	v_mul_f32_e32 v73, 0xbfb8aa3b, v79
	v_mul_f32_e32 v65, v65, v70
	v_add_f32_e32 v70, 1.0, v76
	v_exp_f32_e32 v73, v73
	v_mul_f32_e32 v76, 0xbfb8aa3b, v75
	v_rcp_f32_e32 v70, v70
	v_exp_f32_e32 v76, v76
	v_add_f32_e32 v73, 1.0, v73
	v_rcp_f32_e32 v73, v73
	v_mul_f32_e32 v70, v74, v70
	v_add_f32_e32 v74, 1.0, v76
	v_rcp_f32_e32 v74, v74
	v_mul_f32_e32 v70, v70, v66
	v_mul_f32_e32 v66, v79, v73
	v_mul_f32_e32 v66, v66, v71
	v_mul_f32_e32 v71, v75, v74
	v_mul_f32_e32 v67, v71, v67
	s_nop 1
	v_cvt_pk_bf16_f32 v64, v68, v64
	s_nop 1
	v_cvt_pk_bf16_f32 v65, v65, v66
	s_nop 1
	v_cvt_pk_bf16_f32 v66, v72, v69
	s_nop 1
	v_cvt_pk_bf16_f32 v67, v70, v67
	v_mul_f32_e32 v70, 0xbfb8aa3b, v60
	v_exp_f32_e32 v70, v70
	v_or_b32_e32 v68, 48, v150
	v_mad_i64_i32 v[68:69], s[0:1], v68, s47, v[112:113]
	v_lshl_add_u64 v[68:69], v[68:69], 0, v[114:115]
	v_mul_f32_e32 v71, 0xbfb8aa3b, v56
	global_store_dwordx4 v[68:69], v[64:67], off
	v_exp_f32_e32 v71, v71
	s_and_b64 vcc, exec, s[6:7]
	v_add_f32_e32 v64, 1.0, v70
	v_rcp_f32_e32 v64, v64
	v_add_f32_e32 v65, 1.0, v71
	v_rcp_f32_e32 v65, v65
	v_add_u32_e32 v66, 0x80, v150
	v_mul_f32_e32 v60, v60, v64
	v_mul_f32_e32 v52, v60, v52
	v_mul_f32_e32 v60, 0xbfb8aa3b, v61
	v_exp_f32_e32 v60, v60
	v_mul_f32_e32 v64, 0xbfb8aa3b, v57
	v_exp_f32_e32 v64, v64
	v_mul_f32_e32 v56, v56, v65
	v_mul_f32_e32 v56, v56, v48
	v_add_f32_e32 v48, 1.0, v60
	v_rcp_f32_e32 v48, v48
	v_add_f32_e32 v60, 1.0, v64
	v_mul_f32_e32 v64, 0xbfb8aa3b, v62
	v_rcp_f32_e32 v60, v60
	v_exp_f32_e32 v64, v64
	v_mul_f32_e32 v48, v61, v48
	v_mul_f32_e32 v48, v48, v53
	v_mul_f32_e32 v53, v57, v60
	v_add_f32_e32 v57, 1.0, v64
	v_rcp_f32_e32 v57, v57
	v_mul_f32_e32 v60, 0xbfb8aa3b, v58
	v_exp_f32_e32 v60, v60
	v_mul_f32_e32 v53, v53, v49
	v_mul_f32_e32 v49, v62, v57
	v_mul_f32_e32 v57, 0xbfb8aa3b, v63
	v_mul_f32_e32 v49, v49, v54
	v_add_f32_e32 v54, 1.0, v60
	v_exp_f32_e32 v57, v57
	v_mul_f32_e32 v60, 0xbfb8aa3b, v59
	v_rcp_f32_e32 v54, v54
	v_exp_f32_e32 v60, v60
	v_add_f32_e32 v57, 1.0, v57
	v_rcp_f32_e32 v57, v57
	v_mul_f32_e32 v54, v58, v54
	v_add_f32_e32 v58, 1.0, v60
	v_rcp_f32_e32 v58, v58
	v_mul_f32_e32 v54, v54, v50
	v_mul_f32_e32 v50, v63, v57
	v_mul_f32_e32 v50, v50, v55
	v_mul_f32_e32 v55, v59, v58
	v_mul_f32_e32 v51, v55, v51
	s_nop 1
	v_cvt_pk_bf16_f32 v48, v52, v48
	s_nop 1
	v_cvt_pk_bf16_f32 v49, v49, v50
	s_nop 1
	v_cvt_pk_bf16_f32 v50, v56, v53
	s_nop 1
	v_cvt_pk_bf16_f32 v51, v54, v51
	v_mul_f32_e32 v54, 0xbfb8aa3b, v44
	v_exp_f32_e32 v54, v54
	v_mul_f32_e32 v55, 0xbfb8aa3b, v40
	v_exp_f32_e32 v55, v55
	v_mad_i64_i32 v[52:53], s[0:1], v66, s47, v[112:113]
	v_add_f32_e32 v54, 1.0, v54
	v_rcp_f32_e32 v54, v54
	v_add_f32_e32 v55, 1.0, v55
	v_lshl_add_u64 v[52:53], v[52:53], 0, v[114:115]
	v_rcp_f32_e32 v55, v55
	v_mul_f32_e32 v44, v44, v54
	v_mul_f32_e32 v36, v44, v36
	v_mul_f32_e32 v44, 0xbfb8aa3b, v45
	global_store_dwordx4 v[52:53], v[48:51], off
	v_exp_f32_e32 v44, v44
	v_mul_f32_e32 v40, v40, v55
	v_mul_f32_e32 v48, 0xbfb8aa3b, v41
	v_exp_f32_e32 v48, v48
	v_mul_f32_e32 v40, v40, v32
	v_add_f32_e32 v32, 1.0, v44
	v_rcp_f32_e32 v32, v32
	v_add_f32_e32 v44, 1.0, v48
	v_mul_f32_e32 v48, 0xbfb8aa3b, v46
	v_rcp_f32_e32 v44, v44
	v_exp_f32_e32 v48, v48
	v_mul_f32_e32 v32, v45, v32
	v_mul_f32_e32 v32, v32, v37
	v_mul_f32_e32 v37, v41, v44
	v_add_f32_e32 v41, 1.0, v48
	v_rcp_f32_e32 v41, v41
	v_mul_f32_e32 v44, 0xbfb8aa3b, v42
	v_exp_f32_e32 v44, v44
	v_mul_f32_e32 v37, v37, v33
	v_mul_f32_e32 v33, v46, v41
	v_mul_f32_e32 v41, 0xbfb8aa3b, v47
	v_mul_f32_e32 v33, v33, v38
	v_add_f32_e32 v38, 1.0, v44
	v_exp_f32_e32 v41, v41
	v_mul_f32_e32 v44, 0xbfb8aa3b, v43
	v_rcp_f32_e32 v38, v38
	v_exp_f32_e32 v44, v44
	v_add_f32_e32 v41, 1.0, v41
	v_rcp_f32_e32 v41, v41
	v_mul_f32_e32 v38, v42, v38
	v_add_f32_e32 v42, 1.0, v44
	v_rcp_f32_e32 v42, v42
	v_mul_f32_e32 v38, v38, v34
	v_mul_f32_e32 v34, v47, v41
	v_mul_f32_e32 v34, v34, v39
	v_mul_f32_e32 v39, v43, v42
	v_mul_f32_e32 v35, v39, v35
	s_nop 1
	v_cvt_pk_bf16_f32 v32, v36, v32
	s_nop 1
	v_cvt_pk_bf16_f32 v33, v33, v34
	s_nop 1
	v_cvt_pk_bf16_f32 v34, v40, v37
	s_nop 1
	v_cvt_pk_bf16_f32 v35, v38, v35
	v_mul_f32_e32 v38, 0xbfb8aa3b, v28
	v_exp_f32_e32 v38, v38
	v_mul_f32_e32 v39, 0xbfb8aa3b, v24
	v_exp_f32_e32 v39, v39
	v_add_u32_e32 v36, 0x90, v150
	v_add_f32_e32 v38, 1.0, v38
	v_rcp_f32_e32 v38, v38
	v_mad_i64_i32 v[36:37], s[0:1], v36, s47, v[112:113]
	v_add_f32_e32 v39, 1.0, v39
	v_mul_f32_e32 v28, v28, v38
	v_lshl_add_u64 v[36:37], v[36:37], 0, v[114:115]
	v_rcp_f32_e32 v39, v39
	v_mul_f32_e32 v20, v28, v20
	v_mul_f32_e32 v28, 0xbfb8aa3b, v29
	global_store_dwordx4 v[36:37], v[32:35], off
	v_exp_f32_e32 v28, v28
	v_mul_f32_e32 v24, v24, v39
	v_mul_f32_e32 v32, 0xbfb8aa3b, v25
	v_exp_f32_e32 v32, v32
	v_mul_f32_e32 v24, v24, v16
	v_add_f32_e32 v16, 1.0, v28
	v_rcp_f32_e32 v16, v16
	v_add_f32_e32 v28, 1.0, v32
	v_mul_f32_e32 v32, 0xbfb8aa3b, v30
	v_rcp_f32_e32 v28, v28
	v_exp_f32_e32 v32, v32
	v_mul_f32_e32 v16, v29, v16
	v_mul_f32_e32 v16, v16, v21
	v_mul_f32_e32 v21, v25, v28
	v_add_f32_e32 v25, 1.0, v32
	v_rcp_f32_e32 v25, v25
	v_mul_f32_e32 v28, 0xbfb8aa3b, v26
	v_exp_f32_e32 v28, v28
	v_mul_f32_e32 v21, v21, v17
	v_mul_f32_e32 v17, v30, v25
	v_mul_f32_e32 v25, 0xbfb8aa3b, v31
	v_mul_f32_e32 v17, v17, v22
	v_add_f32_e32 v22, 1.0, v28
	v_exp_f32_e32 v25, v25
	v_mul_f32_e32 v28, 0xbfb8aa3b, v27
	v_rcp_f32_e32 v22, v22
	v_exp_f32_e32 v28, v28
	v_add_f32_e32 v25, 1.0, v25
	v_rcp_f32_e32 v25, v25
	v_mul_f32_e32 v22, v26, v22
	v_add_f32_e32 v26, 1.0, v28
	v_rcp_f32_e32 v26, v26
	v_mul_f32_e32 v22, v22, v18
	v_mul_f32_e32 v18, v31, v25
	v_mul_f32_e32 v18, v18, v23
	v_mul_f32_e32 v23, v27, v26
	v_mul_f32_e32 v19, v23, v19
	s_nop 1
	v_cvt_pk_bf16_f32 v16, v20, v16
	s_nop 1
	v_cvt_pk_bf16_f32 v17, v17, v18
	s_nop 1
	v_cvt_pk_bf16_f32 v18, v24, v21
	s_nop 1
	v_cvt_pk_bf16_f32 v19, v22, v19
	v_mul_f32_e32 v22, 0xbfb8aa3b, v12
	v_exp_f32_e32 v22, v22
	v_mul_f32_e32 v23, 0xbfb8aa3b, v8
	v_exp_f32_e32 v23, v23
	v_add_u32_e32 v20, 0xa0, v150
	v_add_f32_e32 v22, 1.0, v22
	v_rcp_f32_e32 v22, v22
	v_mad_i64_i32 v[20:21], s[0:1], v20, s47, v[112:113]
	v_add_f32_e32 v23, 1.0, v23
	v_mul_f32_e32 v12, v12, v22
	v_lshl_add_u64 v[20:21], v[20:21], 0, v[114:115]
	v_rcp_f32_e32 v23, v23
	v_mul_f32_e32 v4, v12, v4
	v_mul_f32_e32 v12, 0xbfb8aa3b, v13
	global_store_dwordx4 v[20:21], v[16:19], off
	v_exp_f32_e32 v12, v12
	v_mul_f32_e32 v8, v8, v23
	v_mul_f32_e32 v16, 0xbfb8aa3b, v9
	v_exp_f32_e32 v16, v16
	v_mul_f32_e32 v8, v8, v0
	v_add_f32_e32 v0, 1.0, v12
	v_rcp_f32_e32 v0, v0
	v_add_f32_e32 v12, 1.0, v16
	v_mul_f32_e32 v16, 0xbfb8aa3b, v14
	v_rcp_f32_e32 v12, v12
	v_exp_f32_e32 v16, v16
	v_mul_f32_e32 v0, v13, v0
	v_mul_f32_e32 v0, v0, v5
	v_mul_f32_e32 v5, v9, v12
	v_add_f32_e32 v9, 1.0, v16
	v_rcp_f32_e32 v9, v9
	v_mul_f32_e32 v12, 0xbfb8aa3b, v10
	v_exp_f32_e32 v12, v12
	v_mul_f32_e32 v5, v5, v1
	v_mul_f32_e32 v1, v14, v9
	v_mul_f32_e32 v9, 0xbfb8aa3b, v15
	v_exp_f32_e32 v9, v9
	v_mul_f32_e32 v1, v1, v6
	v_add_f32_e32 v6, 1.0, v12
	v_mul_f32_e32 v12, 0xbfb8aa3b, v11
	v_rcp_f32_e32 v6, v6
	v_exp_f32_e32 v12, v12
	v_add_f32_e32 v9, 1.0, v9
	v_rcp_f32_e32 v9, v9
	v_mul_f32_e32 v6, v10, v6
	v_add_f32_e32 v10, 1.0, v12
	v_rcp_f32_e32 v10, v10
	v_mul_f32_e32 v6, v6, v2
	v_mul_f32_e32 v2, v15, v9
	v_mul_f32_e32 v2, v2, v7
	s_nop 1
	v_cvt_pk_bf16_f32 v0, v4, v0
	v_add_u32_e32 v4, 0xb0, v150
	v_mul_f32_e32 v7, v11, v10
	s_nop 1
	v_cvt_pk_bf16_f32 v1, v1, v2
	s_nop 1
	v_cvt_pk_bf16_f32 v2, v8, v5
	v_mad_i64_i32 v[4:5], s[0:1], v4, s47, v[112:113]
	v_mul_f32_e32 v3, v7, v3
	v_lshl_add_u64 v[4:5], v[4:5], 0, v[114:115]
	s_mov_b32 s50, s10
	s_mov_b32 s18, s12
	s_mov_b64 s[44:45], s[16:17]
	s_mov_b64 s[20:21], s[14:15]
	s_nop 1
	v_cvt_pk_bf16_f32 v3, v6, v3
	global_store_dwordx4 v[4:5], v[0:3], off
	s_cbranch_vccz .LBB0_1673
	s_waitcnt vmcnt(0)
	s_cmpk_gt_u32 s23, 0xff
	s_cbranch_scc1 .LBB0_1680
	s_barrier

.LBB0_1748:
	s_add_u32 s0, s44, 0x100
	v_mov_b32_e32 v0, 0
	s_addc_u32 s1, s45, 0
	s_mov_b32 s61, -2
	v_mov_b32_e32 v1, v0
	v_mov_b32_e32 v2, v0
	v_mov_b32_e32 v3, v0
	v_mov_b32_e32 v16, v0
	v_mov_b32_e32 v17, v0
	v_mov_b32_e32 v18, v0
	v_mov_b32_e32 v19, v0
	v_mov_b32_e32 v4, v0
	v_mov_b32_e32 v5, v0
	v_mov_b32_e32 v6, v0
	v_mov_b32_e32 v7, v0
	v_mov_b32_e32 v20, v0
	v_mov_b32_e32 v21, v0
	v_mov_b32_e32 v22, v0
	v_mov_b32_e32 v23, v0
	v_mov_b32_e32 v8, v0
	v_mov_b32_e32 v9, v0
	v_mov_b32_e32 v10, v0
	v_mov_b32_e32 v11, v0
	v_mov_b32_e32 v24, v0
	v_mov_b32_e32 v25, v0
	v_mov_b32_e32 v26, v0
	v_mov_b32_e32 v27, v0
	v_mov_b32_e32 v12, v0
	v_mov_b32_e32 v13, v0
	v_mov_b32_e32 v14, v0
	v_mov_b32_e32 v15, v0
	v_mov_b32_e32 v32, v0
	v_mov_b32_e32 v33, v0
	v_mov_b32_e32 v34, v0
	v_mov_b32_e32 v35, v0
	v_mov_b32_e32 v52, v0
	v_mov_b32_e32 v53, v0
	v_mov_b32_e32 v54, v0
	v_mov_b32_e32 v55, v0
	v_mov_b32_e32 v80, v0
	v_mov_b32_e32 v81, v0
	v_mov_b32_e32 v82, v0
	v_mov_b32_e32 v83, v0
	v_mov_b32_e32 v60, v0
	v_mov_b32_e32 v61, v0
	v_mov_b32_e32 v62, v0
	v_mov_b32_e32 v63, v0
	v_mov_b32_e32 v88, v0
	v_mov_b32_e32 v89, v0
	v_mov_b32_e32 v90, v0
	v_mov_b32_e32 v91, v0
	v_mov_b32_e32 v68, v0
	v_mov_b32_e32 v69, v0
	v_mov_b32_e32 v70, v0
	v_mov_b32_e32 v71, v0
	v_mov_b32_e32 v104, v0
	v_mov_b32_e32 v105, v0
	v_mov_b32_e32 v106, v0
	v_mov_b32_e32 v107, v0
	v_mov_b32_e32 v76, v0
	v_mov_b32_e32 v77, v0
	v_mov_b32_e32 v78, v0
	v_mov_b32_e32 v79, v0
	v_mov_b32_e32 v108, v0
	v_mov_b32_e32 v109, v0
	v_mov_b32_e32 v110, v0
	v_mov_b32_e32 v111, v0
	v_mov_b32_e32 v28, v0
	v_mov_b32_e32 v29, v0
	v_mov_b32_e32 v30, v0
	v_mov_b32_e32 v31, v0
	v_mov_b32_e32 v48, v0
	v_mov_b32_e32 v49, v0
	v_mov_b32_e32 v50, v0
	v_mov_b32_e32 v51, v0
	v_mov_b32_e32 v36, v0
	v_mov_b32_e32 v37, v0
	v_mov_b32_e32 v38, v0
	v_mov_b32_e32 v39, v0
	v_mov_b32_e32 v56, v0
	v_mov_b32_e32 v57, v0
	v_mov_b32_e32 v58, v0
	v_mov_b32_e32 v59, v0
	v_mov_b32_e32 v40, v0
	v_mov_b32_e32 v41, v0
	v_mov_b32_e32 v42, v0
	v_mov_b32_e32 v43, v0
	v_mov_b32_e32 v64, v0
	v_mov_b32_e32 v65, v0
	v_mov_b32_e32 v66, v0
	v_mov_b32_e32 v67, v0
	v_mov_b32_e32 v44, v0
	v_mov_b32_e32 v45, v0
	v_mov_b32_e32 v46, v0
	v_mov_b32_e32 v47, v0
	v_mov_b32_e32 v72, v0
	v_mov_b32_e32 v73, v0
	v_mov_b32_e32 v74, v0
	v_mov_b32_e32 v75, v0
	v_mov_b32_e32 v84, v0
	v_mov_b32_e32 v85, v0
	v_mov_b32_e32 v86, v0
	v_mov_b32_e32 v87, v0
	v_mov_b32_e32 v112, v0
	v_mov_b32_e32 v113, v0
	v_mov_b32_e32 v114, v0
	v_mov_b32_e32 v115, v0
	v_mov_b32_e32 v92, v0
	v_mov_b32_e32 v93, v0
	v_mov_b32_e32 v94, v0
	v_mov_b32_e32 v95, v0
	v_mov_b32_e32 v116, v0
	v_mov_b32_e32 v117, v0
	v_mov_b32_e32 v118, v0
	v_mov_b32_e32 v119, v0
	v_mov_b32_e32 v96, v0
	v_mov_b32_e32 v97, v0
	v_mov_b32_e32 v98, v0
	v_mov_b32_e32 v99, v0
	v_mov_b32_e32 v120, v0
	v_mov_b32_e32 v121, v0
	v_mov_b32_e32 v122, v0
	v_mov_b32_e32 v123, v0
	v_mov_b32_e32 v100, v0
	v_mov_b32_e32 v101, v0
	v_mov_b32_e32 v102, v0
	v_mov_b32_e32 v103, v0
	v_mov_b32_e32 v124, v0
	v_mov_b32_e32 v125, v0
	v_mov_b32_e32 v126, v0
	v_mov_b32_e32 v127, v0
	ds_read_b128 v[128:131], v221
	ds_read_b128 v[132:135], v221 offset:1024
	ds_read_b128 v[136:139], v221 offset:2048
	ds_read_b128 v[140:143], v221 offset:3072
	.p2alignl 6, 3212836864
.LBB0_1749:
	s_add_u32 s44, s42, 0x100
	s_addc_u32 s45, s43, 0
	s_cmpk_eq_i32 s61, 0x54
	s_cselect_b32 s5, s9, s45
	s_cselect_b32 s4, s8, s44
	s_cselect_b32 s47, s11, s1
	s_cselect_b32 s46, s10, s0
	s_add_i32 m0, s25, 0xc000
	ds_read_b128 v[144:147], v222
	ds_read_b128 v[148:151], v222 offset:1024
	ds_read_b128 v[152:155], v222 offset:2048
	ds_read_b128 v[156:159], v222 offset:3072
	ds_read_b128 v[160:163], v222 offset:4096
	ds_read_b128 v[176:179], v222 offset:5120
	ds_read_b128 v[180:183], v222 offset:6144
	ds_read_b128 v[184:187], v222 offset:7168
	global_load_lds_dwordx4 v168, s[42:43]
	s_add_i32 m0, s25, 0xe000
	s_nop 0
	global_load_lds_dwordx4 v170, s[42:43]
	s_waitcnt lgkmcnt(8)
	s_barrier
	s_waitcnt lgkmcnt(0)
	s_waitcnt lgkmcnt(0)
	v_mfma_f32_16x16x32_bf16 v[124:127], v[128:131], v[144:147], v[124:127]
	v_mfma_f32_16x16x32_bf16 v[100:103], v[136:139], v[144:147], v[100:103]
	v_mfma_f32_16x16x32_bf16 v[120:123], v[128:131], v[152:155], v[120:123]
	v_mfma_f32_16x16x32_bf16 v[96:99], v[136:139], v[152:155], v[96:99]
	v_mfma_f32_16x16x32_bf16 v[116:119], v[128:131], v[160:163], v[116:119]
	v_mfma_f32_16x16x32_bf16 v[92:95], v[136:139], v[160:163], v[92:95]
	v_mfma_f32_16x16x32_bf16 v[112:115], v[128:131], v[180:183], v[112:115]
	v_mfma_f32_16x16x32_bf16 v[84:87], v[136:139], v[180:183], v[84:87]
	v_mfma_f32_16x16x32_bf16 v[124:127], v[132:135], v[148:151], v[124:127]
	v_mfma_f32_16x16x32_bf16 v[100:103], v[140:143], v[148:151], v[100:103]
	v_mfma_f32_16x16x32_bf16 v[120:123], v[132:135], v[156:159], v[120:123]
	v_mfma_f32_16x16x32_bf16 v[96:99], v[140:143], v[156:159], v[96:99]
	v_mfma_f32_16x16x32_bf16 v[116:119], v[132:135], v[176:179], v[116:119]
	v_mfma_f32_16x16x32_bf16 v[92:95], v[140:143], v[176:179], v[92:95]
	v_mfma_f32_16x16x32_bf16 v[112:115], v[132:135], v[184:187], v[112:115]
	v_mfma_f32_16x16x32_bf16 v[84:87], v[140:143], v[184:187], v[84:87]
	s_barrier
	s_add_i32 s42, s51, s24
	s_add_u32 s98, s46, s18
	s_addc_u32 s99, s47, s19
	s_mov_b32 m0, s42
	ds_read_b128 v[188:191], v223
	ds_read_b128 v[192:195], v223 offset:1024
	ds_read_b128 v[196:199], v223 offset:2048
	ds_read_b128 v[200:203], v223 offset:3072
	global_load_lds_dwordx4 v166, s[46:47]
	s_add_i32 m0, s42, 0x2000
	s_nop 0
	global_load_lds_dwordx4 v164, s[46:47]
	s_barrier
	s_waitcnt lgkmcnt(0)
	s_waitcnt lgkmcnt(0)
	v_mfma_f32_16x16x32_bf16 v[72:75], v[188:191], v[144:147], v[72:75]
	v_mfma_f32_16x16x32_bf16 v[44:47], v[196:199], v[144:147], v[44:47]
	v_mfma_f32_16x16x32_bf16 v[64:67], v[188:191], v[152:155], v[64:67]
	v_mfma_f32_16x16x32_bf16 v[40:43], v[196:199], v[152:155], v[40:43]
	v_mfma_f32_16x16x32_bf16 v[56:59], v[188:191], v[160:163], v[56:59]
	v_mfma_f32_16x16x32_bf16 v[36:39], v[196:199], v[160:163], v[36:39]
	v_mfma_f32_16x16x32_bf16 v[48:51], v[188:191], v[180:183], v[48:51]
	v_mfma_f32_16x16x32_bf16 v[28:31], v[196:199], v[180:183], v[28:31]
	v_mfma_f32_16x16x32_bf16 v[72:75], v[192:195], v[148:151], v[72:75]
	v_mfma_f32_16x16x32_bf16 v[44:47], v[200:203], v[148:151], v[44:47]
	v_mfma_f32_16x16x32_bf16 v[64:67], v[192:195], v[156:159], v[64:67]
	v_mfma_f32_16x16x32_bf16 v[40:43], v[200:203], v[156:159], v[40:43]
	v_mfma_f32_16x16x32_bf16 v[56:59], v[192:195], v[176:179], v[56:59]
	v_mfma_f32_16x16x32_bf16 v[36:39], v[200:203], v[176:179], v[36:39]
	v_mfma_f32_16x16x32_bf16 v[48:51], v[192:195], v[184:187], v[48:51]
	v_mfma_f32_16x16x32_bf16 v[28:31], v[200:203], v[184:187], v[28:31]
	s_mov_b32 m0, s25
	s_add_u32 s100, s4, s18
	s_addc_u32 s101, s5, s19
	s_barrier
	s_waitcnt vmcnt(8)
	ds_read_b128 v[144:147], v222 offset:16384
	ds_read_b128 v[148:151], v222 offset:17408
	ds_read_b128 v[152:155], v222 offset:18432
	ds_read_b128 v[156:159], v222 offset:19456
	ds_read_b128 v[160:163], v222 offset:20480
	ds_read_b128 v[176:179], v222 offset:21504
	ds_read_b128 v[180:183], v222 offset:22528
	ds_read_b128 v[184:187], v222 offset:23552
	global_load_lds_dwordx4 v166, s[4:5]
	s_mov_b32 m0, s28
	s_nop 0
	global_load_lds_dwordx4 v164, s[4:5]
	s_barrier
	s_waitcnt lgkmcnt(0)
	s_waitcnt lgkmcnt(0)
	v_mfma_f32_16x16x32_bf16 v[108:111], v[128:131], v[144:147], v[108:111]
	v_mfma_f32_16x16x32_bf16 v[76:79], v[136:139], v[144:147], v[76:79]
	v_mfma_f32_16x16x32_bf16 v[104:107], v[128:131], v[152:155], v[104:107]
	v_mfma_f32_16x16x32_bf16 v[68:71], v[136:139], v[152:155], v[68:71]
	v_mfma_f32_16x16x32_bf16 v[88:91], v[128:131], v[160:163], v[88:91]
	v_mfma_f32_16x16x32_bf16 v[60:63], v[136:139], v[160:163], v[60:63]
	v_mfma_f32_16x16x32_bf16 v[80:83], v[128:131], v[180:183], v[80:83]
	v_mfma_f32_16x16x32_bf16 v[52:55], v[136:139], v[180:183], v[52:55]
	v_mfma_f32_16x16x32_bf16 v[108:111], v[132:135], v[148:151], v[108:111]
	v_mfma_f32_16x16x32_bf16 v[76:79], v[140:143], v[148:151], v[76:79]
	v_mfma_f32_16x16x32_bf16 v[104:107], v[132:135], v[156:159], v[104:107]
	v_mfma_f32_16x16x32_bf16 v[68:71], v[140:143], v[156:159], v[68:71]
	v_mfma_f32_16x16x32_bf16 v[88:91], v[132:135], v[176:179], v[88:91]
	v_mfma_f32_16x16x32_bf16 v[60:63], v[140:143], v[176:179], v[60:63]
	v_mfma_f32_16x16x32_bf16 v[80:83], v[132:135], v[184:187], v[80:83]
	v_mfma_f32_16x16x32_bf16 v[52:55], v[140:143], v[184:187], v[52:55]
	s_barrier
	s_add_u32 s42, s46, 0x160000
	s_addc_u32 s43, s47, 0
	s_add_i32 s62, s52, s24
	s_mov_b32 m0, s62
	s_nop 0
	global_load_lds_dwordx4 v166, s[42:43]
	s_add_i32 m0, s62, 0x2000
	s_nop 0
	global_load_lds_dwordx4 v164, s[42:43]
	v_add_u32_e32 v140, 0x18000, v219
	ds_read_b128 v[128:131], v140
	ds_read_b128 v[132:135], v140 offset:1024
	ds_read_b128 v[136:139], v140 offset:2048
	ds_read_b128 v[140:143], v140 offset:3072
	s_waitcnt vmcnt(6)
	s_barrier
	v_mfma_f32_16x16x32_bf16 v[32:35], v[188:191], v[144:147], v[32:35]
	v_mfma_f32_16x16x32_bf16 v[12:15], v[196:199], v[144:147], v[12:15]
	v_mfma_f32_16x16x32_bf16 v[24:27], v[188:191], v[152:155], v[24:27]
	v_mfma_f32_16x16x32_bf16 v[8:11], v[196:199], v[152:155], v[8:11]
	v_mfma_f32_16x16x32_bf16 v[20:23], v[188:191], v[160:163], v[20:23]
	v_mfma_f32_16x16x32_bf16 v[4:7], v[196:199], v[160:163], v[4:7]
	v_mfma_f32_16x16x32_bf16 v[16:19], v[188:191], v[180:183], v[16:19]
	v_mfma_f32_16x16x32_bf16 v[0:3], v[196:199], v[180:183], v[0:3]
	v_mfma_f32_16x16x32_bf16 v[32:35], v[192:195], v[148:151], v[32:35]
	v_mfma_f32_16x16x32_bf16 v[12:15], v[200:203], v[148:151], v[12:15]
	v_mfma_f32_16x16x32_bf16 v[24:27], v[192:195], v[156:159], v[24:27]
	v_mfma_f32_16x16x32_bf16 v[8:11], v[200:203], v[156:159], v[8:11]
	v_mfma_f32_16x16x32_bf16 v[20:23], v[192:195], v[176:179], v[20:23]
	v_mfma_f32_16x16x32_bf16 v[4:7], v[200:203], v[176:179], v[4:7]
	v_mfma_f32_16x16x32_bf16 v[16:19], v[192:195], v[184:187], v[16:19]
	v_mfma_f32_16x16x32_bf16 v[0:3], v[200:203], v[184:187], v[0:3]
	s_add_i32 s42, 0, 0x18000
	s_barrier
	s_add_u32 s4, s4, 0x160000
	s_addc_u32 s5, s5, 0
	s_mov_b32 m0, s29
	ds_read_b128 v[144:147], v222 offset:32768
	ds_read_b128 v[148:151], v222 offset:33792
	ds_read_b128 v[152:155], v222 offset:34816
	ds_read_b128 v[156:159], v222 offset:35840
	ds_read_b128 v[160:163], v222 offset:36864
	ds_read_b128 v[176:179], v222 offset:37888
	ds_read_b128 v[180:183], v222 offset:38912
	ds_read_b128 v[184:187], v222 offset:39936
	global_load_lds_dwordx4 v166, s[4:5]
	s_mov_b32 m0, s33
	s_nop 0
	global_load_lds_dwordx4 v164, s[4:5]
	s_waitcnt lgkmcnt(8)
	s_barrier
	s_waitcnt lgkmcnt(0)
	s_waitcnt lgkmcnt(0)
	v_mfma_f32_16x16x32_bf16 v[124:127], v[128:131], v[144:147], v[124:127]
	v_mfma_f32_16x16x32_bf16 v[100:103], v[136:139], v[144:147], v[100:103]
	v_mfma_f32_16x16x32_bf16 v[120:123], v[128:131], v[152:155], v[120:123]
	v_mfma_f32_16x16x32_bf16 v[96:99], v[136:139], v[152:155], v[96:99]
	v_mfma_f32_16x16x32_bf16 v[116:119], v[128:131], v[160:163], v[116:119]
	v_mfma_f32_16x16x32_bf16 v[92:95], v[136:139], v[160:163], v[92:95]
	v_mfma_f32_16x16x32_bf16 v[112:115], v[128:131], v[180:183], v[112:115]
	v_mfma_f32_16x16x32_bf16 v[84:87], v[136:139], v[180:183], v[84:87]
	v_mfma_f32_16x16x32_bf16 v[124:127], v[132:135], v[148:151], v[124:127]
	v_mfma_f32_16x16x32_bf16 v[100:103], v[140:143], v[148:151], v[100:103]
	v_mfma_f32_16x16x32_bf16 v[120:123], v[132:135], v[156:159], v[120:123]
	v_mfma_f32_16x16x32_bf16 v[96:99], v[140:143], v[156:159], v[96:99]
	v_mfma_f32_16x16x32_bf16 v[116:119], v[132:135], v[176:179], v[116:119]
	v_mfma_f32_16x16x32_bf16 v[92:95], v[140:143], v[176:179], v[92:95]
	v_mfma_f32_16x16x32_bf16 v[112:115], v[132:135], v[184:187], v[112:115]
	v_mfma_f32_16x16x32_bf16 v[84:87], v[140:143], v[184:187], v[84:87]
	s_barrier
	s_add_i32 s43, 0, 0x1c000
	s_add_i32 s4, s42, s24
	v_add_u32_e32 v200, s43, v219
	s_mov_b32 m0, s4
	ds_read_b128 v[188:191], v200
	ds_read_b128 v[192:195], v200 offset:1024
	ds_read_b128 v[196:199], v200 offset:2048
	ds_read_b128 v[200:203], v200 offset:3072
	global_load_lds_dwordx4 v166, s[98:99]
	s_add_i32 m0, s4, 0x2000
	s_nop 0
	global_load_lds_dwordx4 v164, s[98:99]
	s_barrier
	s_waitcnt lgkmcnt(0)
	s_waitcnt lgkmcnt(0)
	v_mfma_f32_16x16x32_bf16 v[72:75], v[188:191], v[144:147], v[72:75]
	v_mfma_f32_16x16x32_bf16 v[44:47], v[196:199], v[144:147], v[44:47]
	v_mfma_f32_16x16x32_bf16 v[64:67], v[188:191], v[152:155], v[64:67]
	v_mfma_f32_16x16x32_bf16 v[40:43], v[196:199], v[152:155], v[40:43]
	v_mfma_f32_16x16x32_bf16 v[56:59], v[188:191], v[160:163], v[56:59]
	v_mfma_f32_16x16x32_bf16 v[36:39], v[196:199], v[160:163], v[36:39]
	v_mfma_f32_16x16x32_bf16 v[48:51], v[188:191], v[180:183], v[48:51]
	v_mfma_f32_16x16x32_bf16 v[28:31], v[196:199], v[180:183], v[28:31]
	v_mfma_f32_16x16x32_bf16 v[72:75], v[192:195], v[148:151], v[72:75]
	v_mfma_f32_16x16x32_bf16 v[44:47], v[200:203], v[148:151], v[44:47]
	v_mfma_f32_16x16x32_bf16 v[64:67], v[192:195], v[156:159], v[64:67]
	v_mfma_f32_16x16x32_bf16 v[40:43], v[200:203], v[156:159], v[40:43]
	v_mfma_f32_16x16x32_bf16 v[56:59], v[192:195], v[176:179], v[56:59]
	v_mfma_f32_16x16x32_bf16 v[36:39], v[200:203], v[176:179], v[36:39]
	v_mfma_f32_16x16x32_bf16 v[48:51], v[192:195], v[184:187], v[48:51]
	v_mfma_f32_16x16x32_bf16 v[28:31], v[200:203], v[184:187], v[28:31]
	s_mov_b32 m0, s41
	s_barrier
	s_waitcnt vmcnt(8)
	ds_read_b128 v[144:147], v222 offset:49152
	ds_read_b128 v[148:151], v222 offset:50176
	ds_read_b128 v[152:155], v222 offset:51200
	ds_read_b128 v[156:159], v222 offset:52224
	ds_read_b128 v[160:163], v222 offset:53248
	ds_read_b128 v[176:179], v222 offset:54272
	ds_read_b128 v[180:183], v222 offset:55296
	ds_read_b128 v[184:187], v222 offset:56320
	global_load_lds_dwordx4 v166, s[100:101]
	s_mov_b32 m0, s50
	s_nop 0
	global_load_lds_dwordx4 v164, s[100:101]
	s_barrier
	s_waitcnt lgkmcnt(0)
	s_waitcnt lgkmcnt(0)
	v_mfma_f32_16x16x32_bf16 v[108:111], v[128:131], v[144:147], v[108:111]
	v_mfma_f32_16x16x32_bf16 v[76:79], v[136:139], v[144:147], v[76:79]
	v_mfma_f32_16x16x32_bf16 v[104:107], v[128:131], v[152:155], v[104:107]
	v_mfma_f32_16x16x32_bf16 v[68:71], v[136:139], v[152:155], v[68:71]
	v_mfma_f32_16x16x32_bf16 v[88:91], v[128:131], v[160:163], v[88:91]
	v_mfma_f32_16x16x32_bf16 v[60:63], v[136:139], v[160:163], v[60:63]
	v_mfma_f32_16x16x32_bf16 v[80:83], v[128:131], v[180:183], v[80:83]
	v_mfma_f32_16x16x32_bf16 v[52:55], v[136:139], v[180:183], v[52:55]
	v_mfma_f32_16x16x32_bf16 v[108:111], v[132:135], v[148:151], v[108:111]
	v_mfma_f32_16x16x32_bf16 v[76:79], v[140:143], v[148:151], v[76:79]
	v_mfma_f32_16x16x32_bf16 v[104:107], v[132:135], v[156:159], v[104:107]
	v_mfma_f32_16x16x32_bf16 v[68:71], v[140:143], v[156:159], v[68:71]
	v_mfma_f32_16x16x32_bf16 v[88:91], v[132:135], v[176:179], v[88:91]
	v_mfma_f32_16x16x32_bf16 v[60:63], v[140:143], v[176:179], v[60:63]
	v_mfma_f32_16x16x32_bf16 v[80:83], v[132:135], v[184:187], v[80:83]
	v_mfma_f32_16x16x32_bf16 v[52:55], v[140:143], v[184:187], v[52:55]
	s_barrier
	s_add_u32 s4, s46, 0x160080
	s_addc_u32 s5, s47, 0
	s_add_i32 s42, s43, s24
	s_mov_b32 m0, s42
	s_nop 0
	global_load_lds_dwordx4 v166, s[4:5]
	s_add_i32 m0, s42, 0x2000
	s_nop 0
	global_load_lds_dwordx4 v164, s[4:5]
	ds_read_b128 v[128:131], v221
	ds_read_b128 v[132:135], v221 offset:1024
	ds_read_b128 v[136:139], v221 offset:2048
	ds_read_b128 v[140:143], v221 offset:3072
	s_waitcnt vmcnt(6)
	s_barrier
	v_mfma_f32_16x16x32_bf16 v[32:35], v[188:191], v[144:147], v[32:35]
	v_mfma_f32_16x16x32_bf16 v[12:15], v[196:199], v[144:147], v[12:15]
	v_mfma_f32_16x16x32_bf16 v[24:27], v[188:191], v[152:155], v[24:27]
	v_mfma_f32_16x16x32_bf16 v[8:11], v[196:199], v[152:155], v[8:11]
	v_mfma_f32_16x16x32_bf16 v[20:23], v[188:191], v[160:163], v[20:23]
	v_mfma_f32_16x16x32_bf16 v[4:7], v[196:199], v[160:163], v[4:7]
	v_mfma_f32_16x16x32_bf16 v[16:19], v[188:191], v[180:183], v[16:19]
	v_mfma_f32_16x16x32_bf16 v[0:3], v[196:199], v[180:183], v[0:3]
	v_mfma_f32_16x16x32_bf16 v[32:35], v[192:195], v[148:151], v[32:35]
	v_mfma_f32_16x16x32_bf16 v[12:15], v[200:203], v[148:151], v[12:15]
	v_mfma_f32_16x16x32_bf16 v[24:27], v[192:195], v[156:159], v[24:27]
	v_mfma_f32_16x16x32_bf16 v[8:11], v[200:203], v[156:159], v[8:11]
	v_mfma_f32_16x16x32_bf16 v[20:23], v[192:195], v[176:179], v[20:23]
	v_mfma_f32_16x16x32_bf16 v[4:7], v[200:203], v[176:179], v[4:7]
	v_mfma_f32_16x16x32_bf16 v[16:19], v[192:195], v[184:187], v[16:19]
	v_mfma_f32_16x16x32_bf16 v[0:3], v[200:203], v[184:187], v[0:3]
	s_add_i32 s61, s61, 2
	s_add_u32 s0, s0, 0x100
	s_addc_u32 s1, s1, 0
	s_cmpk_gt_u32 s61, 0x55
	s_mov_b64 s[42:43], s[44:45]
	s_barrier
	s_cbranch_scc0 .LBB0_1749
	v_lshl_add_u32 v144, s59, 8, v218
	v_lshl_or_b32 v184, s60, 8, v220
	v_ashrrev_i32_e32 v145, 31, v144
	v_ashrrev_i32_e32 v185, 31, v184
	v_lshlrev_b64 v[132:133], 13, v[144:145]
	v_lshlrev_b64 v[146:147], 2, v[184:185]
	v_lshl_add_u64 v[132:133], s[12:13], 0, v[132:133]
	v_lshl_add_u64 v[176:177], v[132:133], 0, v[146:147]
	v_or_b32_e32 v136, 16, v144
	v_add_co_u32_e32 v186, vcc, s53, v176
	v_ashrrev_i32_e32 v137, 31, v136
	v_or_b32_e32 v140, 32, v144
	v_or_b32_e32 v144, 48, v144
	v_addc_co_u32_e32 v187, vcc, 0, v177, vcc
	v_lshlrev_b64 v[136:137], 13, v[136:137]
	v_ashrrev_i32_e32 v141, 31, v140
	v_ashrrev_i32_e32 v145, 31, v144
	v_add_co_u32_e32 v190, vcc, s54, v176
	v_lshl_add_u64 v[128:129], s[16:17], 0, v[146:147]
	v_lshl_add_u64 v[136:137], s[12:13], 0, v[136:137]
	v_lshlrev_b64 v[140:141], 13, v[140:141]
	v_lshlrev_b64 v[144:145], 13, v[144:145]
	v_addc_co_u32_e32 v191, vcc, 0, v177, vcc
	global_load_dwordx4 v[128:131], v[128:129], off
	v_lshl_add_u64 v[178:179], v[136:137], 0, v[146:147]
	global_load_dwordx4 v[132:135], v[176:177], off
	global_load_dwordx4 v[136:139], v[178:179], off
	v_lshl_add_u64 v[140:141], s[12:13], 0, v[140:141]
	v_lshl_add_u64 v[144:145], s[12:13], 0, v[144:145]
	v_add_co_u32_e32 v192, vcc, s55, v176
	v_lshl_add_u64 v[180:181], v[140:141], 0, v[146:147]
	v_lshl_add_u64 v[182:183], v[144:145], 0, v[146:147]
	v_addc_co_u32_e32 v193, vcc, 0, v177, vcc
	global_load_dwordx4 v[140:143], v[180:181], off
	global_load_dwordx4 v[144:147], v[182:183], off
	global_load_dwordx4 v[148:151], v[186:187], off
	global_load_dwordx4 v[160:163], v[190:191], off
	global_load_dwordx4 v[156:159], v[192:193], off
	v_add_co_u32_e32 v188, vcc, s56, v176
	v_pk_add_f32 v[212:213], v[126:127], 0 op_sel_hi:[1,0]
	s_nop 0
	v_addc_co_u32_e32 v189, vcc, 0, v177, vcc
	global_load_dwordx4 v[152:155], v[188:189], off
	v_pk_add_f32 v[214:215], v[124:125], 0 op_sel_hi:[1,0]
	v_pk_add_f32 v[126:127], v[122:123], 0 op_sel_hi:[1,0]
	v_pk_add_f32 v[194:195], v[120:121], 0 op_sel_hi:[1,0]
	v_pk_add_f32 v[196:197], v[118:119], 0 op_sel_hi:[1,0]
	v_pk_add_f32 v[198:199], v[116:117], 0 op_sel_hi:[1,0]
	v_pk_add_f32 v[200:201], v[114:115], 0 op_sel_hi:[1,0]
	v_pk_add_f32 v[202:203], v[112:113], 0 op_sel_hi:[1,0]
	v_pk_add_f32 v[204:205], v[110:111], 0 op_sel_hi:[1,0]
	v_pk_add_f32 v[206:207], v[108:109], 0 op_sel_hi:[1,0]
	v_pk_add_f32 v[208:209], v[106:107], 0 op_sel_hi:[1,0]
	v_pk_add_f32 v[210:211], v[104:105], 0 op_sel_hi:[1,0]
	v_lshl_add_u64 v[120:121], v[176:177], 0, s[20:21]
	v_lshl_add_u64 v[122:123], v[176:177], 0, s[36:37]
	global_load_dwordx4 v[104:107], v[176:177], off offset:64
	global_load_dwordx4 v[108:111], v[178:179], off offset:64
	global_load_dwordx4 v[112:115], v[180:181], off offset:64
	global_load_dwordx4 v[116:119], v[182:183], off offset:64
	global_load_dwordx4 v[224:227], v[120:121], off offset:576
	global_load_dwordx4 v[228:231], v[122:123], off offset:576
	v_lshl_add_u64 v[124:125], v[176:177], 0, s[38:39]
	v_pk_add_f32 v[102:103], v[102:103], 0 op_sel_hi:[1,0]
	v_pk_add_f32 v[100:101], v[100:101], 0 op_sel_hi:[1,0]
	v_pk_add_f32 v[98:99], v[98:99], 0 op_sel_hi:[1,0]
	v_pk_add_f32 v[96:97], v[96:97], 0 op_sel_hi:[1,0]
	v_pk_add_f32 v[74:75], v[74:75], 0 op_sel_hi:[1,0]
	v_pk_add_f32 v[72:73], v[72:73], 0 op_sel_hi:[1,0]
	v_pk_add_f32 v[66:67], v[66:67], 0 op_sel_hi:[1,0]
	v_pk_add_f32 v[64:65], v[64:65], 0 op_sel_hi:[1,0]
	v_pk_add_f32 v[58:59], v[58:59], 0 op_sel_hi:[1,0]
	v_pk_add_f32 v[56:57], v[56:57], 0 op_sel_hi:[1,0]
	v_pk_add_f32 v[46:47], v[46:47], 0 op_sel_hi:[1,0]
	v_pk_add_f32 v[44:45], v[44:45], 0 op_sel_hi:[1,0]
	v_pk_add_f32 v[42:43], v[42:43], 0 op_sel_hi:[1,0]
	v_pk_add_f32 v[40:41], v[40:41], 0 op_sel_hi:[1,0]
	v_pk_add_f32 v[38:39], v[38:39], 0 op_sel_hi:[1,0]
	v_pk_add_f32 v[36:37], v[36:37], 0 op_sel_hi:[1,0]
	v_pk_add_f32 v[30:31], v[30:31], 0 op_sel_hi:[1,0]
	v_pk_add_f32 v[28:29], v[28:29], 0 op_sel_hi:[1,0]
	s_and_b64 vcc, exec, s[6:7]
	s_mov_b32 s60, s57
	s_mov_b32 s59, s58
	s_mov_b64 s[44:45], s[10:11]
	s_mov_b64 s[42:43], s[8:9]
	s_waitcnt vmcnt(0)
	v_pk_fma_f32 v[134:135], v[212:213], v[130:131], v[134:135]
	v_pk_fma_f32 v[132:133], v[214:215], v[128:129], v[132:133]
	global_store_dwordx4 v[176:177], v[132:135], off
	s_nop 1
	v_pk_fma_f32 v[134:135], v[126:127], v[130:131], v[138:139]
	v_pk_fma_f32 v[132:133], v[194:195], v[128:129], v[136:137]
	v_pk_add_f32 v[126:127], v[90:91], 0 op_sel_hi:[1,0]
	v_pk_fma_f32 v[138:139], v[196:197], v[130:131], v[142:143]
	v_pk_fma_f32 v[136:137], v[198:199], v[128:129], v[140:141]
	v_pk_fma_f32 v[142:143], v[200:201], v[130:131], v[146:147]
	v_pk_fma_f32 v[140:141], v[202:203], v[128:129], v[144:145]
	v_pk_fma_f32 v[146:147], v[204:205], v[130:131], v[150:151]
	v_pk_fma_f32 v[144:145], v[206:207], v[128:129], v[148:149]
	v_pk_fma_f32 v[150:151], v[208:209], v[130:131], v[162:163]
	v_pk_fma_f32 v[148:149], v[210:211], v[128:129], v[160:161]
	global_store_dwordx4 v[178:179], v[132:135], off
	global_store_dwordx4 v[180:181], v[136:139], off
	global_store_dwordx4 v[182:183], v[140:143], off
	global_store_dwordx4 v[186:187], v[144:147], off
	global_store_dwordx4 v[190:191], v[148:151], off
	v_pk_add_f32 v[132:133], v[88:89], 0 op_sel_hi:[1,0]
	v_pk_fma_f32 v[134:135], v[126:127], v[130:131], v[158:159]
	v_pk_fma_f32 v[132:133], v[132:133], v[128:129], v[156:157]
	v_pk_add_f32 v[126:127], v[82:83], 0 op_sel_hi:[1,0]
	global_store_dwordx4 v[192:193], v[132:135], off
	v_pk_fma_f32 v[130:131], v[126:127], v[130:131], v[154:155]
	v_or_b32_e32 v126, 16, v184
	v_pk_add_f32 v[132:133], v[80:81], 0 op_sel_hi:[1,0]
	v_ashrrev_i32_e32 v127, 31, v126
	v_pk_fma_f32 v[128:129], v[132:133], v[128:129], v[152:153]
	v_lshl_add_u64 v[146:147], v[176:177], 0, s[14:15]
	global_store_dwordx4 v[188:189], v[128:131], off
	v_lshl_add_u64 v[126:127], v[126:127], 2, s[16:17]
	global_load_dwordx4 v[88:91], v[124:125], off offset:576
	global_load_dwordx4 v[80:83], v[146:147], off offset:576
	s_nop 0
	global_load_dwordx4 v[126:129], v[126:127], off
	s_nop 0
	global_load_dwordx4 v[130:133], v[120:121], off offset:64
	global_load_dwordx4 v[134:137], v[122:123], off offset:64
	global_load_dwordx4 v[138:141], v[124:125], off offset:64
	global_load_dwordx4 v[142:145], v[146:147], off offset:64
	v_pk_add_f32 v[192:193], v[52:53], 0 op_sel_hi:[1,0]
	v_or_b32_e32 v52, 0x80, v184
	v_pk_add_f32 v[148:149], v[94:95], 0 op_sel_hi:[1,0]
	v_pk_add_f32 v[150:151], v[92:93], 0 op_sel_hi:[1,0]
	v_pk_add_f32 v[152:153], v[86:87], 0 op_sel_hi:[1,0]
	v_pk_add_f32 v[154:155], v[84:85], 0 op_sel_hi:[1,0]
	v_pk_add_f32 v[156:157], v[78:79], 0 op_sel_hi:[1,0]
	v_pk_add_f32 v[158:159], v[76:77], 0 op_sel_hi:[1,0]
	v_pk_add_f32 v[160:161], v[70:71], 0 op_sel_hi:[1,0]
	v_pk_add_f32 v[162:163], v[68:69], 0 op_sel_hi:[1,0]
	v_pk_add_f32 v[186:187], v[62:63], 0 op_sel_hi:[1,0]
	v_pk_add_f32 v[188:189], v[60:61], 0 op_sel_hi:[1,0]
	v_pk_add_f32 v[190:191], v[54:55], 0 op_sel_hi:[1,0]
	v_ashrrev_i32_e32 v53, 31, v52
	v_lshl_add_u64 v[194:195], v[52:53], 2, s[16:17]
	global_load_dwordx4 v[52:55], v[176:177], off offset:512
	global_load_dwordx4 v[60:63], v[120:121], off offset:512
	global_load_dwordx4 v[68:71], v[122:123], off offset:512
	global_load_dwordx4 v[76:79], v[124:125], off offset:512
	global_load_dwordx4 v[84:87], v[146:147], off offset:512
	s_waitcnt vmcnt(0)
	v_pk_fma_f32 v[94:95], v[102:103], v[128:129], v[106:107]
	v_pk_fma_f32 v[92:93], v[100:101], v[126:127], v[104:105]
	v_pk_fma_f32 v[98:99], v[98:99], v[128:129], v[110:111]
	v_pk_fma_f32 v[96:97], v[96:97], v[126:127], v[108:109]
	v_pk_fma_f32 v[102:103], v[148:149], v[128:129], v[114:115]
	v_pk_fma_f32 v[100:101], v[150:151], v[126:127], v[112:113]
	v_pk_fma_f32 v[106:107], v[152:153], v[128:129], v[118:119]
	v_pk_fma_f32 v[104:105], v[154:155], v[126:127], v[116:117]
	v_pk_fma_f32 v[110:111], v[156:157], v[128:129], v[132:133]
	v_pk_fma_f32 v[108:109], v[158:159], v[126:127], v[130:131]
	v_pk_fma_f32 v[114:115], v[160:161], v[128:129], v[136:137]
	v_pk_fma_f32 v[112:113], v[162:163], v[126:127], v[134:135]
	v_pk_fma_f32 v[118:119], v[186:187], v[128:129], v[140:141]
	v_pk_fma_f32 v[116:117], v[188:189], v[126:127], v[138:139]
	v_pk_fma_f32 v[128:129], v[190:191], v[128:129], v[144:145]
	v_pk_fma_f32 v[126:127], v[192:193], v[126:127], v[142:143]
	global_store_dwordx4 v[176:177], v[92:95], off offset:64
	global_store_dwordx4 v[178:179], v[96:99], off offset:64
	global_store_dwordx4 v[180:181], v[100:103], off offset:64
	global_store_dwordx4 v[182:183], v[104:107], off offset:64
	global_store_dwordx4 v[120:121], v[108:111], off offset:64
	global_store_dwordx4 v[122:123], v[112:115], off offset:64
	global_store_dwordx4 v[124:125], v[116:119], off offset:64
	global_store_dwordx4 v[146:147], v[126:129], off offset:64
	global_load_dwordx4 v[92:95], v[194:195], off
	global_load_dwordx4 v[96:99], v[178:179], off offset:512
	global_load_dwordx4 v[100:103], v[180:181], off offset:512
	global_load_dwordx4 v[104:107], v[182:183], off offset:512
	v_pk_add_f32 v[132:133], v[16:17], 0 op_sel_hi:[1,0]
	v_or_b32_e32 v16, 0x90, v184
	v_pk_add_f32 v[108:109], v[50:51], 0 op_sel_hi:[1,0]
	v_pk_add_f32 v[110:111], v[48:49], 0 op_sel_hi:[1,0]
	v_pk_add_f32 v[112:113], v[34:35], 0 op_sel_hi:[1,0]
	v_pk_add_f32 v[114:115], v[32:33], 0 op_sel_hi:[1,0]
	v_pk_add_f32 v[116:117], v[26:27], 0 op_sel_hi:[1,0]
	v_pk_add_f32 v[118:119], v[24:25], 0 op_sel_hi:[1,0]
	v_pk_add_f32 v[126:127], v[22:23], 0 op_sel_hi:[1,0]
	v_pk_add_f32 v[128:129], v[20:21], 0 op_sel_hi:[1,0]
	v_pk_add_f32 v[130:131], v[18:19], 0 op_sel_hi:[1,0]
	v_ashrrev_i32_e32 v17, 31, v16
	v_lshl_add_u64 v[134:135], v[16:17], 2, s[16:17]
	global_load_dwordx4 v[16:19], v[176:177], off offset:576
	global_load_dwordx4 v[20:23], v[178:179], off offset:576
	global_load_dwordx4 v[24:27], v[180:181], off offset:576
	global_load_dwordx4 v[32:35], v[182:183], off offset:576
	s_waitcnt vmcnt(0)
	v_pk_fma_f32 v[50:51], v[74:75], v[94:95], v[54:55]
	v_pk_fma_f32 v[48:49], v[72:73], v[92:93], v[52:53]
	v_pk_fma_f32 v[54:55], v[66:67], v[94:95], v[98:99]
	v_pk_fma_f32 v[52:53], v[64:65], v[92:93], v[96:97]
	v_pk_fma_f32 v[58:59], v[58:59], v[94:95], v[102:103]
	v_pk_fma_f32 v[56:57], v[56:57], v[92:93], v[100:101]
	v_pk_fma_f32 v[66:67], v[108:109], v[94:95], v[106:107]
	v_pk_fma_f32 v[64:65], v[110:111], v[92:93], v[104:105]
	v_pk_fma_f32 v[62:63], v[112:113], v[94:95], v[62:63]
	v_pk_fma_f32 v[60:61], v[114:115], v[92:93], v[60:61]
	v_pk_fma_f32 v[70:71], v[116:117], v[94:95], v[70:71]
	v_pk_fma_f32 v[68:69], v[118:119], v[92:93], v[68:69]
	v_pk_fma_f32 v[74:75], v[126:127], v[94:95], v[78:79]
	v_pk_fma_f32 v[72:73], v[128:129], v[92:93], v[76:77]
	v_pk_fma_f32 v[78:79], v[130:131], v[94:95], v[86:87]
	v_pk_fma_f32 v[76:77], v[132:133], v[92:93], v[84:85]
	global_store_dwordx4 v[176:177], v[48:51], off offset:512
	global_store_dwordx4 v[178:179], v[52:55], off offset:512
	global_store_dwordx4 v[180:181], v[56:59], off offset:512
	global_store_dwordx4 v[182:183], v[64:67], off offset:512
	global_store_dwordx4 v[120:121], v[60:63], off offset:512
	global_store_dwordx4 v[122:123], v[68:71], off offset:512
	global_store_dwordx4 v[124:125], v[72:75], off offset:512
	global_store_dwordx4 v[146:147], v[76:79], off offset:512
	global_load_dwordx4 v[48:51], v[134:135], off
	v_pk_add_f32 v[52:53], v[14:15], 0 op_sel_hi:[1,0]
	v_pk_add_f32 v[54:55], v[12:13], 0 op_sel_hi:[1,0]
	v_pk_add_f32 v[56:57], v[10:11], 0 op_sel_hi:[1,0]
	v_pk_add_f32 v[58:59], v[8:9], 0 op_sel_hi:[1,0]
	v_pk_add_f32 v[60:61], v[6:7], 0 op_sel_hi:[1,0]
	v_pk_add_f32 v[62:63], v[4:5], 0 op_sel_hi:[1,0]
	v_pk_add_f32 v[64:65], v[2:3], 0 op_sel_hi:[1,0]
	v_pk_add_f32 v[66:67], v[0:1], 0 op_sel_hi:[1,0]
	s_waitcnt vmcnt(0)
	v_pk_fma_f32 v[2:3], v[46:47], v[50:51], v[18:19]
	v_pk_fma_f32 v[0:1], v[44:45], v[48:49], v[16:17]
	v_pk_fma_f32 v[6:7], v[42:43], v[50:51], v[22:23]
	v_pk_fma_f32 v[4:5], v[40:41], v[48:49], v[20:21]
	v_pk_fma_f32 v[10:11], v[38:39], v[50:51], v[26:27]
	v_pk_fma_f32 v[8:9], v[36:37], v[48:49], v[24:25]
	v_pk_fma_f32 v[14:15], v[30:31], v[50:51], v[34:35]
	v_pk_fma_f32 v[12:13], v[28:29], v[48:49], v[32:33]
	v_pk_fma_f32 v[18:19], v[52:53], v[50:51], v[226:227]
	v_pk_fma_f32 v[16:17], v[54:55], v[48:49], v[224:225]
	v_pk_fma_f32 v[22:23], v[56:57], v[50:51], v[230:231]
	v_pk_fma_f32 v[20:21], v[58:59], v[48:49], v[228:229]
	v_pk_fma_f32 v[26:27], v[60:61], v[50:51], v[90:91]
	v_pk_fma_f32 v[24:25], v[62:63], v[48:49], v[88:89]
	v_pk_fma_f32 v[30:31], v[64:65], v[50:51], v[82:83]
	v_pk_fma_f32 v[28:29], v[66:67], v[48:49], v[80:81]
	global_store_dwordx4 v[176:177], v[0:3], off offset:576
	global_store_dwordx4 v[178:179], v[4:7], off offset:576
	global_store_dwordx4 v[180:181], v[8:11], off offset:576
	global_store_dwordx4 v[182:183], v[12:15], off offset:576
	global_store_dwordx4 v[120:121], v[16:19], off offset:576
	global_store_dwordx4 v[122:123], v[20:23], off offset:576
	global_store_dwordx4 v[124:125], v[24:27], off offset:576
	global_store_dwordx4 v[146:147], v[28:31], off offset:576
	s_cbranch_vccz .LBB0_1738
	s_waitcnt vmcnt(0)
	s_cmpk_gt_u32 s23, 0xff
	s_cbranch_scc1 .LBB0_1753
	s_barrier
